# L0 out-proj residual epilogue rewritten and reading the kernel input directly (init pass no longer copies x into the residual buffer); non-temporal loads for once-read residual rows
# speedup vs baseline: 1.0789x; 1.0093x over previous
; DI int otid() { int t = threadIdx.x; asm volatile("" : "+v"(t)); return t; }
; DI void st_bf16x4(bf16_t* p, f32x4 v) { u32x2 w; w.x = cvt_pk_bf16(v[0], v[1]); w.y = cvt_pk_bf16(v[2], v[3]); *(u32x2*)p = w; }
; DI void phase_init_x(const Params& p) {
;     const int tid_ = otid(); const int lane = tid_ & 63, gw = blockIdx.x * 8 + (tid_ >> 6), nw = gridDim.x * 8;
;     float* X = (float*)(p.ws + WS_X); bf16_t* H = (bf16_t*)(p.ws + WS_H); const float* mod = (const float*)(p.ws + WS_MOD);
;     for (int row = gw; row < MR; row += nw) {
;         const int b = row / RB, r = row % RB; const int s = r < CL ? 4 : b;
;         const float* src = r < CL ? p.in[2] + ((size_t)b * CL + r) * DM : p.in[0] + ((size_t)b * TL + (r - CL)) * DM;
;         const float* sh = mod + (size_t)s * 12288; const float* sc = sh + 2048;
; #pragma unroll
;         for (int i = 0; i < 8; ++i) {
;             const int col = (i * 64 + lane) * 4;
;             const f32x4 v = *(const f32x4*)(src + col);
;             *(f32x4*)(X + (size_t)row * DM + col) = v;
;             const f32x4 s4 = *(const f32x4*)(sh + col), c4 = *(const f32x4*)(sc + col);
;             st_bf16x4(H + (size_t)row * DM + col, v * (c4 + 1.f) + s4);
;         }
;     }
; }
.Lix_go:
	global_load_dwordx4 v[88:91], v76, s[22:23] offset:0 nt
	global_load_dwordx4 v[92:95], v76, s[22:23] offset:1024 nt
	global_load_dwordx4 v[96:99], v76, s[22:23] offset:2048 nt
	global_load_dwordx4 v[100:103], v76, s[22:23] offset:3072 nt
	global_load_dwordx4 v[104:107], v77, s[22:23] offset:0 nt
	global_load_dwordx4 v[108:111], v77, s[22:23] offset:1024 nt
	global_load_dwordx4 v[112:115], v77, s[22:23] offset:2048 nt
	global_load_dwordx4 v[116:119], v77, s[22:23] offset:3072 nt
	s_mul_i32 s35, s32, 0xc000
	s_add_u32 s4, s50, 0x8000
	s_addc_u32 s5, s51, 0
	s_add_u32 s4, s4, s35
	s_addc_u32 s5, s5, 0
	global_load_dwordx4 v[140:143], v76, s[4:5] offset:0
	global_load_dwordx4 v[144:147], v76, s[4:5] offset:1024
	global_load_dwordx4 v[148:151], v76, s[4:5] offset:2048
	global_load_dwordx4 v[152:155], v76, s[4:5] offset:3072
	global_load_dwordx4 v[156:159], v77, s[4:5] offset:0
	global_load_dwordx4 v[160:163], v77, s[4:5] offset:1024
	global_load_dwordx4 v[164:167], v77, s[4:5] offset:2048
	global_load_dwordx4 v[168:171], v77, s[4:5] offset:3072
	s_add_u32 s4, s4, 0x2000
	s_addc_u32 s5, s5, 0
	global_load_dwordx4 v[204:207], v76, s[4:5] offset:0
	global_load_dwordx4 v[208:211], v76, s[4:5] offset:1024
	global_load_dwordx4 v[212:215], v76, s[4:5] offset:2048
	global_load_dwordx4 v[216:219], v76, s[4:5] offset:3072
	global_load_dwordx4 v[220:223], v77, s[4:5] offset:0
	global_load_dwordx4 v[224:227], v77, s[4:5] offset:1024
	global_load_dwordx4 v[228:231], v77, s[4:5] offset:2048
	global_load_dwordx4 v[232:235], v77, s[4:5] offset:3072
	s_lshl_b32 s35, s9, 13
	s_add_u32 s2, s50, 0xcba0000
	s_addc_u32 s3, s51, 0
	s_add_u32 s2, s2, s35
	s_addc_u32 s3, s3, 0
	s_lshl_b32 s35, s9, 12
	s_add_u32 s6, s50, 0x23ca0000
	s_addc_u32 s7, s51, 0
	s_add_u32 s6, s6, s35
	s_addc_u32 s7, s7, 0
	s_waitcnt vmcnt(0)
	v_add_f32_e32 v204, 1.0, v204
	v_add_f32_e32 v205, 1.0, v205
	v_add_f32_e32 v206, 1.0, v206
	v_add_f32_e32 v207, 1.0, v207
	v_fma_f32 v204, v88, v204, v140
	v_fma_f32 v205, v89, v205, v141
	v_fma_f32 v206, v90, v206, v142
	v_fma_f32 v207, v91, v207, v143
	v_cvt_pk_bf16_f32 v204, v204, v205
	v_cvt_pk_bf16_f32 v205, v206, v207
	global_store_dwordx2 v78, v[204:205], s[6:7] offset:0
	v_add_f32_e32 v208, 1.0, v208
	v_add_f32_e32 v209, 1.0, v209
	v_add_f32_e32 v210, 1.0, v210
	v_add_f32_e32 v211, 1.0, v211
	v_fma_f32 v208, v92, v208, v144
	v_fma_f32 v209, v93, v209, v145
	v_fma_f32 v210, v94, v210, v146
	v_fma_f32 v211, v95, v211, v147
	v_cvt_pk_bf16_f32 v208, v208, v209
	v_cvt_pk_bf16_f32 v209, v210, v211
	global_store_dwordx2 v78, v[208:209], s[6:7] offset:512
	v_add_f32_e32 v212, 1.0, v212
	v_add_f32_e32 v213, 1.0, v213
	v_add_f32_e32 v214, 1.0, v214
	v_add_f32_e32 v215, 1.0, v215
	v_fma_f32 v212, v96, v212, v148
	v_fma_f32 v213, v97, v213, v149
	v_fma_f32 v214, v98, v214, v150
	v_fma_f32 v215, v99, v215, v151
	v_cvt_pk_bf16_f32 v212, v212, v213
	v_cvt_pk_bf16_f32 v213, v214, v215
	global_store_dwordx2 v78, v[212:213], s[6:7] offset:1024
	v_add_f32_e32 v216, 1.0, v216
	v_add_f32_e32 v217, 1.0, v217
	v_add_f32_e32 v218, 1.0, v218
	v_add_f32_e32 v219, 1.0, v219
	v_fma_f32 v216, v100, v216, v152
	v_fma_f32 v217, v101, v217, v153
	v_fma_f32 v218, v102, v218, v154
	v_fma_f32 v219, v103, v219, v155
	v_cvt_pk_bf16_f32 v216, v216, v217
	v_cvt_pk_bf16_f32 v217, v218, v219
	global_store_dwordx2 v78, v[216:217], s[6:7] offset:1536
	v_add_f32_e32 v220, 1.0, v220
	v_add_f32_e32 v221, 1.0, v221
	v_add_f32_e32 v222, 1.0, v222
	v_add_f32_e32 v223, 1.0, v223
	v_fma_f32 v220, v104, v220, v156
	v_fma_f32 v221, v105, v221, v157
	v_fma_f32 v222, v106, v222, v158
	v_fma_f32 v223, v107, v223, v159
	v_cvt_pk_bf16_f32 v220, v220, v221
	v_cvt_pk_bf16_f32 v221, v222, v223
	global_store_dwordx2 v78, v[220:221], s[6:7] offset:2048
	v_add_f32_e32 v224, 1.0, v224
	v_add_f32_e32 v225, 1.0, v225
	v_add_f32_e32 v226, 1.0, v226
	v_add_f32_e32 v227, 1.0, v227
	v_fma_f32 v224, v108, v224, v160
	v_fma_f32 v225, v109, v225, v161
	v_fma_f32 v226, v110, v226, v162
	v_fma_f32 v227, v111, v227, v163
	v_cvt_pk_bf16_f32 v224, v224, v225
	v_cvt_pk_bf16_f32 v225, v226, v227
	global_store_dwordx2 v78, v[224:225], s[6:7] offset:2560
	v_add_f32_e32 v228, 1.0, v228
	v_add_f32_e32 v229, 1.0, v229
	v_add_f32_e32 v230, 1.0, v230
	v_add_f32_e32 v231, 1.0, v231
	v_fma_f32 v228, v112, v228, v164
	v_fma_f32 v229, v113, v229, v165
	v_fma_f32 v230, v114, v230, v166
	v_fma_f32 v231, v115, v231, v167
	v_cvt_pk_bf16_f32 v228, v228, v229
	v_cvt_pk_bf16_f32 v229, v230, v231
	global_store_dwordx2 v78, v[228:229], s[6:7] offset:3072
	v_add_f32_e32 v232, 1.0, v232
	v_add_f32_e32 v233, 1.0, v233
	v_add_f32_e32 v234, 1.0, v234
	v_add_f32_e32 v235, 1.0, v235
	v_fma_f32 v232, v116, v232, v168
	v_fma_f32 v233, v117, v233, v169
	v_fma_f32 v234, v118, v234, v170
	v_fma_f32 v235, v119, v235, v171
	v_cvt_pk_bf16_f32 v232, v232, v233
	v_cvt_pk_bf16_f32 v233, v234, v235
	global_store_dwordx2 v78, v[232:233], s[6:7] offset:3584
	s_add_u32 s9, s9, s11
	s_branch .Lix_row

;     DI void operator()(const f32x4 (&acc)[2][2][4][2], const Unit& u, int wr, int wc, int fr, int fq) const {
;     ...
;         const float* g = gate + (size_t)s * 12288;
;         const float2* RS = (const float2*)(ws + WS_RSTAT);
; #pragma unroll
;         for (int ai = 0; ai < 2; ++ai)
; #pragma unroll
;             for (int m = 0; m < 4; ++m) {
;                 const int row = u.pm * BM + ai * HALF + wr * 64 + m * 16 + fr;
;                 float mu = 0.f, rs = 1.f;
;                 if (pg) { const float2 st = RS[row]; mu = st.x; rs = st.y; }
; #pragma unroll
;                 for (int bj = 0; bj < 2; ++bj)
; #pragma unroll
;                     for (int n = 0; n < 2; ++n) {
;                         const int col = u.pn * BM + bj * HALF + wc * 32 + n * 16 + 4 * fq;
;                         float* xp = X + (size_t)row * DM + col;
;                         f32x4 x4 = *(const f32x4*)xp; const f32x4 g4 = *(const f32x4*)(g + col);
;                         if (pg) x4 = (x4 - mu) * rs * *(const f32x4*)(pg + col) + *(const f32x4*)(pb + col);
;                         *(f32x4*)xp = x4 * ALPHA + g4 * acc[ai][bj][m][n];
;                     }
.LBB0_1358:
	v_and_b32_e32 v183, 15, v202
	v_bfe_u32 v184, v202, 8, 1
	v_lshl_add_u32 v183, v184, 6, v183
	v_lshlrev_b32_e32 v145, 3, v183
	v_bfe_u32 v184, v202, 6, 2
	v_lshlrev_b32_e32 v143, 7, v184
	v_bfe_u32 v184, v202, 4, 2
	v_lshl_add_u32 v143, v184, 4, v143
	s_lshl_b32 s29, s6, 10
	v_add_u32_e32 v143, s29, v143
	v_lshl_add_u32 v147, v183, 13, v143
	v_add_u32_e32 v149, 0x20000, v147
	v_add_u32_e32 v177, 0x40000, v147
	v_add_u32_e32 v178, 0x60000, v147
	v_add_u32_e32 v179, 0x100000, v147
	v_add_u32_e32 v180, 0x120000, v147
	v_add_u32_e32 v181, 0x140000, v147
	v_add_u32_e32 v182, 0x160000, v147
	s_mov_b32 s89, 0x3fb504f3
	s_mul_i32 s29, s68, 57
	s_lshr_b32 s29, s29, 9
	s_mul_i32 s32, s29, 9
	s_cmp_lg_u32 s32, s68
	s_cselect_b32 s81, s29, 4
	s_mul_i32 s81, s81, 0xc000
	s_add_u32 s74, s50, 0xc000
	s_addc_u32 s75, s51, 0
	s_add_u32 s74, s74, s81
	s_addc_u32 s75, s75, 0
	global_load_dwordx4 v[204:207], v143, s[74:75] offset:0
	global_load_dwordx4 v[208:211], v143, s[74:75] offset:64
	global_load_dwordx4 v[212:215], v143, s[74:75] offset:512
	global_load_dwordx4 v[216:219], v143, s[74:75] offset:576
	s_lshl_b32 s29, s68, 21
	s_add_u32 s72, s50, 0xcba0000
	s_addc_u32 s73, s51, 0
	s_add_u32 s72, s72, s29
	s_addc_u32 s73, s73, 0
	v_readlane_b32 s82, v255, 62
	v_readlane_b32 s83, v255, 63
	s_nop 4
	s_load_dwordx2 s[84:85], s[82:83], 0x0
	s_mul_i32 s29, s68, 57
	s_lshr_b32 s29, s29, 9
	s_sub_u32 s29, s68, s29
	s_sub_u32 s29, s29, 1
	s_lshl_b32 s29, s29, 21
	s_waitcnt lgkmcnt(0)
	s_add_u32 s70, s84, s29
	s_addc_u32 s71, s85, 0
	global_load_dwordx4 v[220:223], v147, s[70:71] offset:0 nt
	global_load_dwordx4 v[224:227], v147, s[70:71] offset:64 nt
	global_load_dwordx4 v[228:231], v147, s[70:71] offset:512 nt
	global_load_dwordx4 v[232:235], v147, s[70:71] offset:576 nt
	global_load_dwordx4 v[236:239], v149, s[70:71] offset:0 nt
	global_load_dwordx4 v[240:243], v149, s[70:71] offset:64 nt
	global_load_dwordx4 v[244:247], v149, s[70:71] offset:512 nt
	global_load_dwordx4 v[248:251], v149, s[70:71] offset:576 nt
	s_waitcnt vmcnt(0)
	v_mul_f32_e32 v220, s89, v220
	v_fmac_f32_e32 v220, v204, v124
	v_mul_f32_e32 v221, s89, v221
	v_fmac_f32_e32 v221, v205, v125
	v_mul_f32_e32 v222, s89, v222
	v_fmac_f32_e32 v222, v206, v126
	v_mul_f32_e32 v223, s89, v223
	v_fmac_f32_e32 v223, v207, v127
	v_mul_f32_e32 v224, s89, v224
	v_fmac_f32_e32 v224, v208, v120
	v_mul_f32_e32 v225, s89, v225
	v_fmac_f32_e32 v225, v209, v121
	v_mul_f32_e32 v226, s89, v226
	v_fmac_f32_e32 v226, v210, v122
	v_mul_f32_e32 v227, s89, v227
	v_fmac_f32_e32 v227, v211, v123
	v_mul_f32_e32 v228, s89, v228
	v_fmac_f32_e32 v228, v212, v104
	v_mul_f32_e32 v229, s89, v229
	v_fmac_f32_e32 v229, v213, v105
	v_mul_f32_e32 v230, s89, v230
	v_fmac_f32_e32 v230, v214, v106
	v_mul_f32_e32 v231, s89, v231
	v_fmac_f32_e32 v231, v215, v107
	v_mul_f32_e32 v232, s89, v232
	v_fmac_f32_e32 v232, v216, v96
	v_mul_f32_e32 v233, s89, v233
	v_fmac_f32_e32 v233, v217, v97
	v_mul_f32_e32 v234, s89, v234
	v_fmac_f32_e32 v234, v218, v98
	v_mul_f32_e32 v235, s89, v235
	v_fmac_f32_e32 v235, v219, v99
	v_mul_f32_e32 v236, s89, v236
	v_fmac_f32_e32 v236, v204, v116
	v_mul_f32_e32 v237, s89, v237
	v_fmac_f32_e32 v237, v205, v117
	v_mul_f32_e32 v238, s89, v238
	v_fmac_f32_e32 v238, v206, v118
	v_mul_f32_e32 v239, s89, v239
	v_fmac_f32_e32 v239, v207, v119
	v_mul_f32_e32 v240, s89, v240
	v_fmac_f32_e32 v240, v208, v112
	v_mul_f32_e32 v241, s89, v241
	v_fmac_f32_e32 v241, v209, v113
	v_mul_f32_e32 v242, s89, v242
	v_fmac_f32_e32 v242, v210, v114
	v_mul_f32_e32 v243, s89, v243
	v_fmac_f32_e32 v243, v211, v115
	v_mul_f32_e32 v244, s89, v244
	v_fmac_f32_e32 v244, v212, v88
	v_mul_f32_e32 v245, s89, v245
	v_fmac_f32_e32 v245, v213, v89
	v_mul_f32_e32 v246, s89, v246
	v_fmac_f32_e32 v246, v214, v90
	v_mul_f32_e32 v247, s89, v247
	v_fmac_f32_e32 v247, v215, v91
	v_mul_f32_e32 v248, s89, v248
	v_fmac_f32_e32 v248, v216, v80
	v_mul_f32_e32 v249, s89, v249
	v_fmac_f32_e32 v249, v217, v81
	v_mul_f32_e32 v250, s89, v250
	v_fmac_f32_e32 v250, v218, v82
	v_mul_f32_e32 v251, s89, v251
	v_fmac_f32_e32 v251, v219, v83
	global_load_dwordx4 v[124:127], v177, s[70:71] offset:0 nt
	global_load_dwordx4 v[120:123], v177, s[70:71] offset:64 nt
	global_load_dwordx4 v[104:107], v177, s[70:71] offset:512 nt
	global_load_dwordx4 v[96:99], v177, s[70:71] offset:576 nt
	global_load_dwordx4 v[116:119], v178, s[70:71] offset:0 nt
	global_load_dwordx4 v[112:115], v178, s[70:71] offset:64 nt
	global_load_dwordx4 v[88:91], v178, s[70:71] offset:512 nt
	global_load_dwordx4 v[80:83], v178, s[70:71] offset:576 nt
	global_store_dwordx4 v147, v[220:223], s[72:73] offset:0
	global_store_dwordx4 v147, v[224:227], s[72:73] offset:64
	global_store_dwordx4 v147, v[228:231], s[72:73] offset:512
	global_store_dwordx4 v147, v[232:235], s[72:73] offset:576
	global_store_dwordx4 v149, v[236:239], s[72:73] offset:0
	global_store_dwordx4 v149, v[240:243], s[72:73] offset:64
	global_store_dwordx4 v149, v[244:247], s[72:73] offset:512
	global_store_dwordx4 v149, v[248:251], s[72:73] offset:576
	global_load_dwordx4 v[220:223], v179, s[70:71] offset:0 nt
	global_load_dwordx4 v[224:227], v179, s[70:71] offset:64 nt
	global_load_dwordx4 v[228:231], v179, s[70:71] offset:512 nt
	global_load_dwordx4 v[232:235], v179, s[70:71] offset:576 nt
	global_load_dwordx4 v[236:239], v180, s[70:71] offset:0 nt
	global_load_dwordx4 v[240:243], v180, s[70:71] offset:64 nt
	global_load_dwordx4 v[244:247], v180, s[70:71] offset:512 nt
	global_load_dwordx4 v[248:251], v180, s[70:71] offset:576 nt
	s_waitcnt vmcnt(0)
;     DI void operator()(const f32x4 (&acc)[2][2][4][2], const Unit& u, int wr, int wc, int fr, int fq) const {
;     ...
;         const float* g = gate + (size_t)s * 12288;
;         const float2* RS = (const float2*)(ws + WS_RSTAT);
; #pragma unroll
;         for (int ai = 0; ai < 2; ++ai)
; #pragma unroll
;             for (int m = 0; m < 4; ++m) {
;                 const int row = u.pm * BM + ai * HALF + wr * 64 + m * 16 + fr;
;                 float mu = 0.f, rs = 1.f;
;                 if (pg) { const float2 st = RS[row]; mu = st.x; rs = st.y; }
; #pragma unroll
;                 for (int bj = 0; bj < 2; ++bj)
; #pragma unroll
;                     for (int n = 0; n < 2; ++n) {
;                         const int col = u.pn * BM + bj * HALF + wc * 32 + n * 16 + 4 * fq;
;                         float* xp = X + (size_t)row * DM + col;
;                         f32x4 x4 = *(const f32x4*)xp; const f32x4 g4 = *(const f32x4*)(g + col);
;                         if (pg) x4 = (x4 - mu) * rs * *(const f32x4*)(pg + col) + *(const f32x4*)(pb + col);
;                         *(f32x4*)xp = x4 * ALPHA + g4 * acc[ai][bj][m][n];
;                     }
	v_mul_f32_e32 v124, s89, v124
	v_fmac_f32_e32 v124, v204, v108
	v_mul_f32_e32 v125, s89, v125
	v_fmac_f32_e32 v125, v205, v109
	v_mul_f32_e32 v126, s89, v126
	v_fmac_f32_e32 v126, v206, v110
	v_mul_f32_e32 v127, s89, v127
	v_fmac_f32_e32 v127, v207, v111
	v_mul_f32_e32 v120, s89, v120
	v_fmac_f32_e32 v120, v208, v100
	v_mul_f32_e32 v121, s89, v121
	v_fmac_f32_e32 v121, v209, v101
	v_mul_f32_e32 v122, s89, v122
	v_fmac_f32_e32 v122, v210, v102
	v_mul_f32_e32 v123, s89, v123
	v_fmac_f32_e32 v123, v211, v103
	v_mul_f32_e32 v104, s89, v104
	v_fmac_f32_e32 v104, v212, v76
	v_mul_f32_e32 v105, s89, v105
	v_fmac_f32_e32 v105, v213, v77
	v_mul_f32_e32 v106, s89, v106
	v_fmac_f32_e32 v106, v214, v78
	v_mul_f32_e32 v107, s89, v107
	v_fmac_f32_e32 v107, v215, v79
	v_mul_f32_e32 v96, s89, v96
	v_fmac_f32_e32 v96, v216, v72
	v_mul_f32_e32 v97, s89, v97
	v_fmac_f32_e32 v97, v217, v73
	v_mul_f32_e32 v98, s89, v98
	v_fmac_f32_e32 v98, v218, v74
	v_mul_f32_e32 v99, s89, v99
	v_fmac_f32_e32 v99, v219, v75
	v_mul_f32_e32 v116, s89, v116
	v_fmac_f32_e32 v116, v204, v92
	v_mul_f32_e32 v117, s89, v117
	v_fmac_f32_e32 v117, v205, v93
	v_mul_f32_e32 v118, s89, v118
	v_fmac_f32_e32 v118, v206, v94
	v_mul_f32_e32 v119, s89, v119
	v_fmac_f32_e32 v119, v207, v95
	v_mul_f32_e32 v112, s89, v112
	v_fmac_f32_e32 v112, v208, v84
	v_mul_f32_e32 v113, s89, v113
	v_fmac_f32_e32 v113, v209, v85
	v_mul_f32_e32 v114, s89, v114
	v_fmac_f32_e32 v114, v210, v86
	v_mul_f32_e32 v115, s89, v115
	v_fmac_f32_e32 v115, v211, v87
	v_mul_f32_e32 v88, s89, v88
	v_fmac_f32_e32 v88, v212, v68
	v_mul_f32_e32 v89, s89, v89
	v_fmac_f32_e32 v89, v213, v69
	v_mul_f32_e32 v90, s89, v90
	v_fmac_f32_e32 v90, v214, v70
	v_mul_f32_e32 v91, s89, v91
	v_fmac_f32_e32 v91, v215, v71
	v_mul_f32_e32 v80, s89, v80
	v_fmac_f32_e32 v80, v216, v64
	v_mul_f32_e32 v81, s89, v81
	v_fmac_f32_e32 v81, v217, v65
	v_mul_f32_e32 v82, s89, v82
	v_fmac_f32_e32 v82, v218, v66
	v_mul_f32_e32 v83, s89, v83
	v_fmac_f32_e32 v83, v219, v67
	v_mul_f32_e32 v220, s89, v220
	v_fmac_f32_e32 v220, v204, v60
	v_mul_f32_e32 v221, s89, v221
	v_fmac_f32_e32 v221, v205, v61
	v_mul_f32_e32 v222, s89, v222
	v_fmac_f32_e32 v222, v206, v62
	v_mul_f32_e32 v223, s89, v223
	v_fmac_f32_e32 v223, v207, v63
	v_mul_f32_e32 v224, s89, v224
	v_fmac_f32_e32 v224, v208, v56
	v_mul_f32_e32 v225, s89, v225
	v_fmac_f32_e32 v225, v209, v57
	v_mul_f32_e32 v226, s89, v226
	v_fmac_f32_e32 v226, v210, v58
	v_mul_f32_e32 v227, s89, v227
	v_fmac_f32_e32 v227, v211, v59
	v_mul_f32_e32 v228, s89, v228
	v_fmac_f32_e32 v228, v212, v40
	v_mul_f32_e32 v229, s89, v229
	v_fmac_f32_e32 v229, v213, v41
	v_mul_f32_e32 v230, s89, v230
	v_fmac_f32_e32 v230, v214, v42
	v_mul_f32_e32 v231, s89, v231
	v_fmac_f32_e32 v231, v215, v43
	v_mul_f32_e32 v232, s89, v232
	v_fmac_f32_e32 v232, v216, v32
	v_mul_f32_e32 v233, s89, v233
	v_fmac_f32_e32 v233, v217, v33
	v_mul_f32_e32 v234, s89, v234
	v_fmac_f32_e32 v234, v218, v34
	v_mul_f32_e32 v235, s89, v235
	v_fmac_f32_e32 v235, v219, v35
	v_mul_f32_e32 v236, s89, v236
	v_fmac_f32_e32 v236, v204, v52
	v_mul_f32_e32 v237, s89, v237
	v_fmac_f32_e32 v237, v205, v53
	v_mul_f32_e32 v238, s89, v238
	v_fmac_f32_e32 v238, v206, v54
	v_mul_f32_e32 v239, s89, v239
	v_fmac_f32_e32 v239, v207, v55
	v_mul_f32_e32 v240, s89, v240
	v_fmac_f32_e32 v240, v208, v48
	v_mul_f32_e32 v241, s89, v241
	v_fmac_f32_e32 v241, v209, v49
	v_mul_f32_e32 v242, s89, v242
	v_fmac_f32_e32 v242, v210, v50
	v_mul_f32_e32 v243, s89, v243
	v_fmac_f32_e32 v243, v211, v51
	v_mul_f32_e32 v244, s89, v244
	v_fmac_f32_e32 v244, v212, v24
	v_mul_f32_e32 v245, s89, v245
	v_fmac_f32_e32 v245, v213, v25
	v_mul_f32_e32 v246, s89, v246
	v_fmac_f32_e32 v246, v214, v26
	v_mul_f32_e32 v247, s89, v247
	v_fmac_f32_e32 v247, v215, v27
	v_mul_f32_e32 v248, s89, v248
	v_fmac_f32_e32 v248, v216, v16
	v_mul_f32_e32 v249, s89, v249
	v_fmac_f32_e32 v249, v217, v17
	v_mul_f32_e32 v250, s89, v250
	v_fmac_f32_e32 v250, v218, v18
	v_mul_f32_e32 v251, s89, v251
	v_fmac_f32_e32 v251, v219, v19
	global_load_dwordx4 v[108:111], v181, s[70:71] offset:0 nt
	global_load_dwordx4 v[100:103], v181, s[70:71] offset:64 nt
	global_load_dwordx4 v[76:79], v181, s[70:71] offset:512 nt
	global_load_dwordx4 v[72:75], v181, s[70:71] offset:576 nt
	global_load_dwordx4 v[92:95], v182, s[70:71] offset:0 nt
	global_load_dwordx4 v[84:87], v182, s[70:71] offset:64 nt
	global_load_dwordx4 v[68:71], v182, s[70:71] offset:512 nt
	global_load_dwordx4 v[64:67], v182, s[70:71] offset:576 nt
	global_store_dwordx4 v177, v[124:127], s[72:73] offset:0
	global_store_dwordx4 v177, v[120:123], s[72:73] offset:64
	global_store_dwordx4 v177, v[104:107], s[72:73] offset:512
	global_store_dwordx4 v177, v[96:99], s[72:73] offset:576
	global_store_dwordx4 v178, v[116:119], s[72:73] offset:0
	global_store_dwordx4 v178, v[112:115], s[72:73] offset:64
	global_store_dwordx4 v178, v[88:91], s[72:73] offset:512
	global_store_dwordx4 v178, v[80:83], s[72:73] offset:576
	global_store_dwordx4 v179, v[220:223], s[72:73] offset:0
	global_store_dwordx4 v179, v[224:227], s[72:73] offset:64
	global_store_dwordx4 v179, v[228:231], s[72:73] offset:512
	global_store_dwordx4 v179, v[232:235], s[72:73] offset:576
	global_store_dwordx4 v180, v[236:239], s[72:73] offset:0
	global_store_dwordx4 v180, v[240:243], s[72:73] offset:64
	global_store_dwordx4 v180, v[244:247], s[72:73] offset:512
	global_store_dwordx4 v180, v[248:251], s[72:73] offset:576
	s_waitcnt vmcnt(16)
;     DI void operator()(const f32x4 (&acc)[2][2][4][2], const Unit& u, int wr, int wc, int fr, int fq) const {
;     ...
;         const float* g = gate + (size_t)s * 12288;
;         const float2* RS = (const float2*)(ws + WS_RSTAT);
; #pragma unroll
;         for (int ai = 0; ai < 2; ++ai)
; #pragma unroll
;             for (int m = 0; m < 4; ++m) {
;                 const int row = u.pm * BM + ai * HALF + wr * 64 + m * 16 + fr;
;                 float mu = 0.f, rs = 1.f;
;                 if (pg) { const float2 st = RS[row]; mu = st.x; rs = st.y; }
; #pragma unroll
;                 for (int bj = 0; bj < 2; ++bj)
; #pragma unroll
;                     for (int n = 0; n < 2; ++n) {
;                         const int col = u.pn * BM + bj * HALF + wc * 32 + n * 16 + 4 * fq;
;                         float* xp = X + (size_t)row * DM + col;
;                         f32x4 x4 = *(const f32x4*)xp; const f32x4 g4 = *(const f32x4*)(g + col);
;                         if (pg) x4 = (x4 - mu) * rs * *(const f32x4*)(pg + col) + *(const f32x4*)(pb + col);
;                         *(f32x4*)xp = x4 * ALPHA + g4 * acc[ai][bj][m][n];
;                     }
	v_mul_f32_e32 v108, s89, v108
	v_fmac_f32_e32 v108, v204, v44
	v_mul_f32_e32 v109, s89, v109
	v_fmac_f32_e32 v109, v205, v45
	v_mul_f32_e32 v110, s89, v110
	v_fmac_f32_e32 v110, v206, v46
	v_mul_f32_e32 v111, s89, v111
	v_fmac_f32_e32 v111, v207, v47
	v_mul_f32_e32 v100, s89, v100
	v_fmac_f32_e32 v100, v208, v36
	v_mul_f32_e32 v101, s89, v101
	v_fmac_f32_e32 v101, v209, v37
	v_mul_f32_e32 v102, s89, v102
	v_fmac_f32_e32 v102, v210, v38
	v_mul_f32_e32 v103, s89, v103
	v_fmac_f32_e32 v103, v211, v39
	v_mul_f32_e32 v76, s89, v76
	v_fmac_f32_e32 v76, v212, v12
	v_mul_f32_e32 v77, s89, v77
	v_fmac_f32_e32 v77, v213, v13
	v_mul_f32_e32 v78, s89, v78
	v_fmac_f32_e32 v78, v214, v14
	v_mul_f32_e32 v79, s89, v79
	v_fmac_f32_e32 v79, v215, v15
	v_mul_f32_e32 v72, s89, v72
	v_fmac_f32_e32 v72, v216, v8
	v_mul_f32_e32 v73, s89, v73
	v_fmac_f32_e32 v73, v217, v9
	v_mul_f32_e32 v74, s89, v74
	v_fmac_f32_e32 v74, v218, v10
	v_mul_f32_e32 v75, s89, v75
	v_fmac_f32_e32 v75, v219, v11
	v_mul_f32_e32 v92, s89, v92
	v_fmac_f32_e32 v92, v204, v28
	v_mul_f32_e32 v93, s89, v93
	v_fmac_f32_e32 v93, v205, v29
	v_mul_f32_e32 v94, s89, v94
	v_fmac_f32_e32 v94, v206, v30
	v_mul_f32_e32 v95, s89, v95
	v_fmac_f32_e32 v95, v207, v31
	v_mul_f32_e32 v84, s89, v84
	v_fmac_f32_e32 v84, v208, v20
	v_mul_f32_e32 v85, s89, v85
	v_fmac_f32_e32 v85, v209, v21
	v_mul_f32_e32 v86, s89, v86
	v_fmac_f32_e32 v86, v210, v22
	v_mul_f32_e32 v87, s89, v87
	v_fmac_f32_e32 v87, v211, v23
	v_mul_f32_e32 v68, s89, v68
	v_fmac_f32_e32 v68, v212, v4
	v_mul_f32_e32 v69, s89, v69
	v_fmac_f32_e32 v69, v213, v5
	v_mul_f32_e32 v70, s89, v70
	v_fmac_f32_e32 v70, v214, v6
	v_mul_f32_e32 v71, s89, v71
	v_fmac_f32_e32 v71, v215, v7
	v_mul_f32_e32 v64, s89, v64
	v_fmac_f32_e32 v64, v216, v0
	v_mul_f32_e32 v65, s89, v65
	v_fmac_f32_e32 v65, v217, v1
	v_mul_f32_e32 v66, s89, v66
	v_fmac_f32_e32 v66, v218, v2
	v_mul_f32_e32 v67, s89, v67
	v_fmac_f32_e32 v67, v219, v3
	global_store_dwordx4 v181, v[108:111], s[72:73] offset:0
	global_store_dwordx4 v181, v[100:103], s[72:73] offset:64
	global_store_dwordx4 v181, v[76:79], s[72:73] offset:512
	global_store_dwordx4 v181, v[72:75], s[72:73] offset:576
	global_store_dwordx4 v182, v[92:95], s[72:73] offset:0
	global_store_dwordx4 v182, v[84:87], s[72:73] offset:64
	global_store_dwordx4 v182, v[68:71], s[72:73] offset:512
	global_store_dwordx4 v182, v[64:67], s[72:73] offset:576
	s_cbranch_execnz .LBB0_1357

; DI void phase_ln(const Params& p, const float* gam, const float* bet, const float* modnext  , bool skip_ctx, bool final_out,
;                  const float* cgate  , const float* pg, const float* pb  ) {
;     ...
;     for (int rowA = gw; rowA < MR; rowA += 2 * nw) {
;         f32x4 v[2][8]; float sum[2] = {0.f, 0.f}; bool act[2]; int rows[2];
; #pragma unroll
;         for (int q = 0; q < 2; ++q) {
;             const int row = rowA + q * nw; rows[q] = row;
;             const int b = row / RB, r = row % RB;
;             act[q] = row < MR && !(skip_ctx && r < CL);
;             if (act[q]) {
;                 const bool cpart = cgate && r < CL;
;                 float pmu = 0.f, prs = 1.f;
;                 if (cpart && pg) { const float2 st = RS[row]; pmu = st.x; prs = st.y; }
; #pragma unroll
;                 for (int i = 0; i < 8; ++i) {
;                     const int col = (i * 64 + lane) * 4;
;                     v[q][i] = *(const f32x4*)(X + (size_t)row * DM + col);
.Ll0a_row:
	s_cmpk_ge_u32 s9, 0x2400
	s_cbranch_scc1 .Ll0a_done
	s_lshr_b32 s35, s9, 8
	s_mul_i32 s27, s35, 57
	s_lshr_b32 s27, s27, 9
	s_mul_i32 s35, s27, 0x900
	s_sub_u32 s29, s9, s35
	s_cmpk_lt_u32 s29, 0x100
	s_cselect_b32 s32, 4, s27
	s_lshl_b32 s35, s9, 13
	s_add_u32 s2, s50, 0xcba0000
	s_addc_u32 s3, s51, 0
	s_add_u32 s2, s2, s35
	s_addc_u32 s3, s3, 0
	s_cmpk_lt_u32 s29, 0x100
	s_cbranch_scc0 .Ll0a_ldx
	v_readlane_b32 s74, v255, 62
	v_readlane_b32 s75, v255, 63
	s_nop 4
	s_load_dwordx2 s[74:75], s[74:75], 0x10
	s_lshl_b32 s35, s27, 8
	s_add_u32 s35, s35, s29
	s_lshl_b32 s35, s35, 13
	s_waitcnt lgkmcnt(0)
	s_add_u32 s22, s74, s35
	s_addc_u32 s23, s75, 0
	global_load_dwordx4 v[88:91], v76, s[22:23] offset:0 nt
	global_load_dwordx4 v[92:95], v76, s[22:23] offset:1024 nt
	global_load_dwordx4 v[96:99], v76, s[22:23] offset:2048 nt
	global_load_dwordx4 v[100:103], v76, s[22:23] offset:3072 nt
	global_load_dwordx4 v[104:107], v77, s[22:23] offset:0 nt
	global_load_dwordx4 v[108:111], v77, s[22:23] offset:1024 nt
	global_load_dwordx4 v[112:115], v77, s[22:23] offset:2048 nt
	global_load_dwordx4 v[116:119], v77, s[22:23] offset:3072 nt
	s_branch .Ll0a_cpart
.Ll0a_ldx:
	global_load_dwordx4 v[88:91], v76, s[2:3] offset:0 nt
	global_load_dwordx4 v[92:95], v76, s[2:3] offset:1024 nt
	global_load_dwordx4 v[96:99], v76, s[2:3] offset:2048 nt
	global_load_dwordx4 v[100:103], v76, s[2:3] offset:3072 nt
	global_load_dwordx4 v[104:107], v77, s[2:3] offset:0 nt
	global_load_dwordx4 v[108:111], v77, s[2:3] offset:1024 nt
	global_load_dwordx4 v[112:115], v77, s[2:3] offset:2048 nt
	global_load_dwordx4 v[116:119], v77, s[2:3] offset:3072 nt

; DI void phase_ln(const Params& p, const float* gam, const float* bet, const float* modnext  , bool skip_ctx, bool final_out,
;                  const float* cgate  , const float* pg, const float* pb  ) {
;     ...
;                     if (cpart) {
;                         if (pg) v[q][i] = (v[q][i] - pmu) * prs * *(const f32x4*)(pg + col) + *(const f32x4*)(pb + col);
;                         const float* pt = (const float*)(p.ws + WS_PART) + ((size_t)b * 256 + r) * DM + col;
;                         const f32x4 ps = *(const f32x4*)pt + *(const f32x4*)(pt + (size_t)1024 * DM) + *(const f32x4*)(pt + (size_t)2048 * DM) + *(const f32x4*)(pt + (size_t)3072 * DM);
;                         v[q][i] = v[q][i] * ALPHA + *(const f32x4*)(cgate + col) * ps;
;                         *(f32x4*)(X + (size_t)row * DM + col) = v[q][i];
;                     }
.Ll0a_cpart:
	s_lshl_b32 s35, s27, 8
	s_add_u32 s35, s35, s29
	s_lshl_b32 s35, s35, 13
	s_add_u32 s4, s50, 0x123a0000
	s_addc_u32 s5, s51, 0
	s_add_u32 s4, s4, s35
	s_addc_u32 s5, s5, 0
	global_load_dwordx4 v[140:143], v76, s[4:5] offset:0 nt
	global_load_dwordx4 v[144:147], v76, s[4:5] offset:1024 nt
	s_add_u32 s4, s4, 0x800000
	s_addc_u32 s5, s5, 0
	global_load_dwordx4 v[148:151], v76, s[4:5] offset:0 nt
	global_load_dwordx4 v[152:155], v76, s[4:5] offset:1024 nt
	s_add_u32 s4, s4, 0x800000
	s_addc_u32 s5, s5, 0
	global_load_dwordx4 v[156:159], v76, s[4:5] offset:0 nt
	global_load_dwordx4 v[160:163], v76, s[4:5] offset:1024 nt
	s_add_u32 s4, s4, 0x800000
	s_addc_u32 s5, s5, 0
	global_load_dwordx4 v[164:167], v76, s[4:5] offset:0 nt
	global_load_dwordx4 v[168:171], v76, s[4:5] offset:1024 nt
	s_sub_u32 s4, s4, 0x1800000
	s_subb_u32 s5, s5, 0
	s_add_u32 s22, s50, 0x3c000
	s_addc_u32 s23, s51, 0
	global_load_dwordx4 v[204:207], v76, s[22:23] offset:0
	global_load_dwordx4 v[208:211], v76, s[22:23] offset:1024
	s_waitcnt vmcnt(0)
	v_add_f32_e32 v140, v140, v148
	v_add_f32_e32 v140, v140, v156
	v_add_f32_e32 v140, v140, v164
	v_mul_f32_e32 v140, v204, v140
	v_fmac_f32_e32 v140, s89, v88
	v_mov_b32_e32 v88, v140
	v_add_f32_e32 v141, v141, v149
	v_add_f32_e32 v141, v141, v157
	v_add_f32_e32 v141, v141, v165
	v_mul_f32_e32 v141, v205, v141
	v_fmac_f32_e32 v141, s89, v89
	v_mov_b32_e32 v89, v141
	v_add_f32_e32 v142, v142, v150
	v_add_f32_e32 v142, v142, v158
	v_add_f32_e32 v142, v142, v166
	v_mul_f32_e32 v142, v206, v142
	v_fmac_f32_e32 v142, s89, v90
	v_mov_b32_e32 v90, v142
	v_add_f32_e32 v143, v143, v151
	v_add_f32_e32 v143, v143, v159
	v_add_f32_e32 v143, v143, v167
	v_mul_f32_e32 v143, v207, v143
	v_fmac_f32_e32 v143, s89, v91
	v_mov_b32_e32 v91, v143
	global_store_dwordx4 v76, v[88:91], s[2:3] offset:0
	v_add_f32_e32 v144, v144, v152
	v_add_f32_e32 v144, v144, v160
	v_add_f32_e32 v144, v144, v168
	v_mul_f32_e32 v144, v208, v144
	v_fmac_f32_e32 v144, s89, v92
	v_mov_b32_e32 v92, v144
	v_add_f32_e32 v145, v145, v153
	v_add_f32_e32 v145, v145, v161
	v_add_f32_e32 v145, v145, v169
	v_mul_f32_e32 v145, v209, v145
	v_fmac_f32_e32 v145, s89, v93
	v_mov_b32_e32 v93, v145
	v_add_f32_e32 v146, v146, v154
	v_add_f32_e32 v146, v146, v162
	v_add_f32_e32 v146, v146, v170
	v_mul_f32_e32 v146, v210, v146
	v_fmac_f32_e32 v146, s89, v94
	v_mov_b32_e32 v94, v146
	v_add_f32_e32 v147, v147, v155
	v_add_f32_e32 v147, v147, v163
	v_add_f32_e32 v147, v147, v171
	v_mul_f32_e32 v147, v211, v147
	v_fmac_f32_e32 v147, s89, v95
	v_mov_b32_e32 v95, v147
	global_store_dwordx4 v76, v[92:95], s[2:3] offset:1024
	global_load_dwordx4 v[140:143], v76, s[4:5] offset:2048 nt
	global_load_dwordx4 v[144:147], v76, s[4:5] offset:3072 nt
	s_add_u32 s4, s4, 0x800000
	s_addc_u32 s5, s5, 0
	global_load_dwordx4 v[148:151], v76, s[4:5] offset:2048 nt
	global_load_dwordx4 v[152:155], v76, s[4:5] offset:3072 nt
	s_add_u32 s4, s4, 0x800000
	s_addc_u32 s5, s5, 0
	global_load_dwordx4 v[156:159], v76, s[4:5] offset:2048 nt
	global_load_dwordx4 v[160:163], v76, s[4:5] offset:3072 nt
	s_add_u32 s4, s4, 0x800000
	s_addc_u32 s5, s5, 0
	global_load_dwordx4 v[164:167], v76, s[4:5] offset:2048 nt
	global_load_dwordx4 v[168:171], v76, s[4:5] offset:3072 nt
	s_sub_u32 s4, s4, 0x1800000
	s_subb_u32 s5, s5, 0
	s_add_u32 s22, s50, 0x3c000
	s_addc_u32 s23, s51, 0
	global_load_dwordx4 v[204:207], v76, s[22:23] offset:2048
	global_load_dwordx4 v[208:211], v76, s[22:23] offset:3072
	s_waitcnt vmcnt(0)
	v_add_f32_e32 v140, v140, v148
	v_add_f32_e32 v140, v140, v156
	v_add_f32_e32 v140, v140, v164
	v_mul_f32_e32 v140, v204, v140
	v_fmac_f32_e32 v140, s89, v96
	v_mov_b32_e32 v96, v140
	v_add_f32_e32 v141, v141, v149
	v_add_f32_e32 v141, v141, v157
	v_add_f32_e32 v141, v141, v165
	v_mul_f32_e32 v141, v205, v141
	v_fmac_f32_e32 v141, s89, v97
	v_mov_b32_e32 v97, v141
	v_add_f32_e32 v142, v142, v150
	v_add_f32_e32 v142, v142, v158
	v_add_f32_e32 v142, v142, v166
	v_mul_f32_e32 v142, v206, v142
	v_fmac_f32_e32 v142, s89, v98
	v_mov_b32_e32 v98, v142
	v_add_f32_e32 v143, v143, v151
	v_add_f32_e32 v143, v143, v159
	v_add_f32_e32 v143, v143, v167
	v_mul_f32_e32 v143, v207, v143
	v_fmac_f32_e32 v143, s89, v99
	v_mov_b32_e32 v99, v143
	global_store_dwordx4 v76, v[96:99], s[2:3] offset:2048
	v_add_f32_e32 v144, v144, v152
	v_add_f32_e32 v144, v144, v160
	v_add_f32_e32 v144, v144, v168
	v_mul_f32_e32 v144, v208, v144
	v_fmac_f32_e32 v144, s89, v100
	v_mov_b32_e32 v100, v144
	v_add_f32_e32 v145, v145, v153
	v_add_f32_e32 v145, v145, v161
	v_add_f32_e32 v145, v145, v169
	v_mul_f32_e32 v145, v209, v145
	v_fmac_f32_e32 v145, s89, v101
	v_mov_b32_e32 v101, v145
	v_add_f32_e32 v146, v146, v154
	v_add_f32_e32 v146, v146, v162
	v_add_f32_e32 v146, v146, v170
	v_mul_f32_e32 v146, v210, v146
	v_fmac_f32_e32 v146, s89, v102
	v_mov_b32_e32 v102, v146
	v_add_f32_e32 v147, v147, v155
	v_add_f32_e32 v147, v147, v163
	v_add_f32_e32 v147, v147, v171
	v_mul_f32_e32 v147, v211, v147
	v_fmac_f32_e32 v147, s89, v103
	v_mov_b32_e32 v103, v147
	global_store_dwordx4 v76, v[100:103], s[2:3] offset:3072
	global_load_dwordx4 v[140:143], v77, s[4:5] offset:0 nt
	global_load_dwordx4 v[144:147], v77, s[4:5] offset:1024 nt
	s_add_u32 s4, s4, 0x800000
	s_addc_u32 s5, s5, 0
	global_load_dwordx4 v[148:151], v77, s[4:5] offset:0 nt
	global_load_dwordx4 v[152:155], v77, s[4:5] offset:1024 nt
	s_add_u32 s4, s4, 0x800000
	s_addc_u32 s5, s5, 0
	global_load_dwordx4 v[156:159], v77, s[4:5] offset:0 nt
	global_load_dwordx4 v[160:163], v77, s[4:5] offset:1024 nt
	s_add_u32 s4, s4, 0x800000
	s_addc_u32 s5, s5, 0
	global_load_dwordx4 v[164:167], v77, s[4:5] offset:0 nt
	global_load_dwordx4 v[168:171], v77, s[4:5] offset:1024 nt
	s_sub_u32 s4, s4, 0x1800000
	s_subb_u32 s5, s5, 0
	s_add_u32 s22, s50, 0x3c000
	s_addc_u32 s23, s51, 0
	global_load_dwordx4 v[204:207], v77, s[22:23] offset:0
	global_load_dwordx4 v[208:211], v77, s[22:23] offset:1024
	s_waitcnt vmcnt(0)
; DI void phase_ln(const Params& p, const float* gam, const float* bet, const float* modnext  , bool skip_ctx, bool final_out,
;                  const float* cgate  , const float* pg, const float* pb  ) {
;     ...
;                     if (cpart) {
;                         if (pg) v[q][i] = (v[q][i] - pmu) * prs * *(const f32x4*)(pg + col) + *(const f32x4*)(pb + col);
;                         const float* pt = (const float*)(p.ws + WS_PART) + ((size_t)b * 256 + r) * DM + col;
;                         const f32x4 ps = *(const f32x4*)pt + *(const f32x4*)(pt + (size_t)1024 * DM) + *(const f32x4*)(pt + (size_t)2048 * DM) + *(const f32x4*)(pt + (size_t)3072 * DM);
;                         v[q][i] = v[q][i] * ALPHA + *(const f32x4*)(cgate + col) * ps;
;                         *(f32x4*)(X + (size_t)row * DM + col) = v[q][i];
	v_add_f32_e32 v140, v140, v148
	v_add_f32_e32 v140, v140, v156
	v_add_f32_e32 v140, v140, v164
	v_mul_f32_e32 v140, v204, v140
	v_fmac_f32_e32 v140, s89, v104
	v_mov_b32_e32 v104, v140
	v_add_f32_e32 v141, v141, v149
	v_add_f32_e32 v141, v141, v157
	v_add_f32_e32 v141, v141, v165
	v_mul_f32_e32 v141, v205, v141
	v_fmac_f32_e32 v141, s89, v105
	v_mov_b32_e32 v105, v141
	v_add_f32_e32 v142, v142, v150
	v_add_f32_e32 v142, v142, v158
	v_add_f32_e32 v142, v142, v166
	v_mul_f32_e32 v142, v206, v142
	v_fmac_f32_e32 v142, s89, v106
	v_mov_b32_e32 v106, v142
	v_add_f32_e32 v143, v143, v151
	v_add_f32_e32 v143, v143, v159
	v_add_f32_e32 v143, v143, v167
	v_mul_f32_e32 v143, v207, v143
	v_fmac_f32_e32 v143, s89, v107
	v_mov_b32_e32 v107, v143
	global_store_dwordx4 v77, v[104:107], s[2:3] offset:0
	v_add_f32_e32 v144, v144, v152
	v_add_f32_e32 v144, v144, v160
	v_add_f32_e32 v144, v144, v168
	v_mul_f32_e32 v144, v208, v144
	v_fmac_f32_e32 v144, s89, v108
	v_mov_b32_e32 v108, v144
	v_add_f32_e32 v145, v145, v153
	v_add_f32_e32 v145, v145, v161
	v_add_f32_e32 v145, v145, v169
	v_mul_f32_e32 v145, v209, v145
	v_fmac_f32_e32 v145, s89, v109
	v_mov_b32_e32 v109, v145
	v_add_f32_e32 v146, v146, v154
	v_add_f32_e32 v146, v146, v162
	v_add_f32_e32 v146, v146, v170
	v_mul_f32_e32 v146, v210, v146
	v_fmac_f32_e32 v146, s89, v110
	v_mov_b32_e32 v110, v146
	v_add_f32_e32 v147, v147, v155
	v_add_f32_e32 v147, v147, v163
	v_add_f32_e32 v147, v147, v171
	v_mul_f32_e32 v147, v211, v147
	v_fmac_f32_e32 v147, s89, v111
	v_mov_b32_e32 v111, v147
	global_store_dwordx4 v77, v[108:111], s[2:3] offset:1024
	global_load_dwordx4 v[140:143], v77, s[4:5] offset:2048 nt
	global_load_dwordx4 v[144:147], v77, s[4:5] offset:3072 nt
	s_add_u32 s4, s4, 0x800000
	s_addc_u32 s5, s5, 0
	global_load_dwordx4 v[148:151], v77, s[4:5] offset:2048 nt
	global_load_dwordx4 v[152:155], v77, s[4:5] offset:3072 nt
	s_add_u32 s4, s4, 0x800000
	s_addc_u32 s5, s5, 0
	global_load_dwordx4 v[156:159], v77, s[4:5] offset:2048 nt
	global_load_dwordx4 v[160:163], v77, s[4:5] offset:3072 nt
	s_add_u32 s4, s4, 0x800000
	s_addc_u32 s5, s5, 0
	global_load_dwordx4 v[164:167], v77, s[4:5] offset:2048 nt
	global_load_dwordx4 v[168:171], v77, s[4:5] offset:3072 nt
	s_sub_u32 s4, s4, 0x1800000
	s_subb_u32 s5, s5, 0
	s_add_u32 s22, s50, 0x3c000
	s_addc_u32 s23, s51, 0
	global_load_dwordx4 v[204:207], v77, s[22:23] offset:2048
	global_load_dwordx4 v[208:211], v77, s[22:23] offset:3072
	s_waitcnt vmcnt(0)
	v_add_f32_e32 v140, v140, v148
	v_add_f32_e32 v140, v140, v156
	v_add_f32_e32 v140, v140, v164
	v_mul_f32_e32 v140, v204, v140
	v_fmac_f32_e32 v140, s89, v112
	v_mov_b32_e32 v112, v140
	v_add_f32_e32 v141, v141, v149
	v_add_f32_e32 v141, v141, v157
	v_add_f32_e32 v141, v141, v165
	v_mul_f32_e32 v141, v205, v141
	v_fmac_f32_e32 v141, s89, v113
	v_mov_b32_e32 v113, v141
	v_add_f32_e32 v142, v142, v150
	v_add_f32_e32 v142, v142, v158
	v_add_f32_e32 v142, v142, v166
	v_mul_f32_e32 v142, v206, v142
	v_fmac_f32_e32 v142, s89, v114
	v_mov_b32_e32 v114, v142
	v_add_f32_e32 v143, v143, v151
	v_add_f32_e32 v143, v143, v159
	v_add_f32_e32 v143, v143, v167
	v_mul_f32_e32 v143, v207, v143
	v_fmac_f32_e32 v143, s89, v115
	v_mov_b32_e32 v115, v143
	global_store_dwordx4 v77, v[112:115], s[2:3] offset:2048
	v_add_f32_e32 v144, v144, v152
	v_add_f32_e32 v144, v144, v160
	v_add_f32_e32 v144, v144, v168
	v_mul_f32_e32 v144, v208, v144
	v_fmac_f32_e32 v144, s89, v116
	v_mov_b32_e32 v116, v144
	v_add_f32_e32 v145, v145, v153
	v_add_f32_e32 v145, v145, v161
	v_add_f32_e32 v145, v145, v169
	v_mul_f32_e32 v145, v209, v145
	v_fmac_f32_e32 v145, s89, v117
	v_mov_b32_e32 v117, v145
	v_add_f32_e32 v146, v146, v154
	v_add_f32_e32 v146, v146, v162
	v_add_f32_e32 v146, v146, v170
	v_mul_f32_e32 v146, v210, v146
	v_fmac_f32_e32 v146, s89, v118
	v_mov_b32_e32 v118, v146
	v_add_f32_e32 v147, v147, v155
	v_add_f32_e32 v147, v147, v163
	v_add_f32_e32 v147, v147, v171
	v_mul_f32_e32 v147, v211, v147
	v_fmac_f32_e32 v147, s89, v119
	v_mov_b32_e32 v119, v147
	global_store_dwordx4 v77, v[116:119], s[2:3] offset:3072
	s_branch .Ll0a_cpart_done

;     DI void operator()(const f32x4 (&acc)[2][2][4][2], const Unit& u, int wr, int wc, int fr, int fq) const {
;     ...
;         const float* g = gate + (size_t)s * 12288;
;         const float2* RS = (const float2*)(ws + WS_RSTAT);
; #pragma unroll
;         for (int ai = 0; ai < 2; ++ai)
; #pragma unroll
;             for (int m = 0; m < 4; ++m) {
;                 const int row = u.pm * BM + ai * HALF + wr * 64 + m * 16 + fr;
;                 float mu = 0.f, rs = 1.f;
;                 if (pg) { const float2 st = RS[row]; mu = st.x; rs = st.y; }
; #pragma unroll
;                 for (int bj = 0; bj < 2; ++bj)
; #pragma unroll
;                     for (int n = 0; n < 2; ++n) {
;                         const int col = u.pn * BM + bj * HALF + wc * 32 + n * 16 + 4 * fq;
;                         float* xp = X + (size_t)row * DM + col;
;                         f32x4 x4 = *(const f32x4*)xp; const f32x4 g4 = *(const f32x4*)(g + col);
;                         if (pg) x4 = (x4 - mu) * rs * *(const f32x4*)(pg + col) + *(const f32x4*)(pb + col);
;                         *(f32x4*)xp = x4 * ALPHA + g4 * acc[ai][bj][m][n];
.LBB0_1694:
	v_and_b32_e32 v197, 15, v202
	v_bfe_u32 v198, v202, 8, 1
	v_lshl_add_u32 v197, v198, 6, v197
	v_lshlrev_b32_e32 v159, 3, v197
	v_bfe_u32 v198, v202, 6, 2
	v_lshlrev_b32_e32 v157, 7, v198
	v_bfe_u32 v198, v202, 4, 2
	v_lshl_add_u32 v157, v198, 4, v157
	s_lshl_b32 s29, s3, 10
	v_add_u32_e32 v157, s29, v157
	v_lshl_add_u32 v161, v197, 13, v157
	v_add_u32_e32 v163, 0x20000, v161
	v_add_u32_e32 v165, 0x40000, v161
	v_add_u32_e32 v192, 0x60000, v161
	v_add_u32_e32 v193, 0x100000, v161
	v_add_u32_e32 v194, 0x120000, v161
	v_add_u32_e32 v195, 0x140000, v161
	v_add_u32_e32 v196, 0x160000, v161
	s_mov_b32 s89, 0x3fb504f3
	s_mul_i32 s29, s80, 57
	s_lshr_b32 s29, s29, 9
	s_mul_i32 s32, s29, 9
	s_cmp_lg_u32 s32, s80
	s_cselect_b32 s12, s29, 4
	s_mul_i32 s12, s12, 0xc000
	s_add_u32 s74, s50, 0x12000
	s_addc_u32 s75, s51, 0
	s_add_u32 s74, s74, s12
	s_addc_u32 s75, s75, 0
	global_load_dwordx4 v[222:225], v157, s[74:75] offset:0
	global_load_dwordx4 v[226:229], v157, s[74:75] offset:64
	global_load_dwordx4 v[230:233], v157, s[74:75] offset:512
	global_load_dwordx4 v[234:237], v157, s[74:75] offset:576
	s_add_u32 s74, s64, 0x0
	s_addc_u32 s75, s65, 0
	global_load_dwordx4 v[206:209], v157, s[74:75] offset:0
	global_load_dwordx4 v[210:213], v157, s[74:75] offset:64
	global_load_dwordx4 v[214:217], v157, s[74:75] offset:512
	global_load_dwordx4 v[218:221], v157, s[74:75] offset:576
	s_add_u32 s74, s66, 0x0
	s_addc_u32 s75, s67, 0
	global_load_dwordx4 v[238:241], v157, s[74:75] offset:0
	global_load_dwordx4 v[242:245], v157, s[74:75] offset:64
	global_load_dwordx4 v[246:249], v157, s[74:75] offset:512
	global_load_dwordx4 v[188:191], v157, s[74:75] offset:576
	s_lshl_b32 s29, s80, 11
	s_add_u32 s74, s50, 0x260a0000
	s_addc_u32 s75, s51, 0
	s_add_u32 s74, s74, s29
	s_addc_u32 s75, s75, 0
	global_load_dwordx2 v[128:129], v159, s[74:75] offset:0
	global_load_dwordx2 v[130:131], v159, s[74:75] offset:128
	global_load_dwordx2 v[132:133], v159, s[74:75] offset:256
	global_load_dwordx2 v[134:135], v159, s[74:75] offset:384
	global_load_dwordx2 v[136:137], v159, s[74:75] offset:1024
	global_load_dwordx2 v[138:139], v159, s[74:75] offset:1152
	global_load_dwordx2 v[140:141], v159, s[74:75] offset:1280
	global_load_dwordx2 v[142:143], v159, s[74:75] offset:1408
	s_lshl_b32 s29, s80, 21
	s_add_u32 s72, s50, 0xcba0000
	s_addc_u32 s73, s51, 0
	s_add_u32 s72, s72, s29
	s_addc_u32 s73, s73, 0
	s_waitcnt vmcnt(0)
	v_mul_f32_e32 v206, s89, v206
	v_mul_f32_e32 v238, s89, v238
	v_mul_f32_e32 v207, s89, v207
	v_mul_f32_e32 v239, s89, v239
	v_mul_f32_e32 v208, s89, v208
	v_mul_f32_e32 v240, s89, v240
	v_mul_f32_e32 v209, s89, v209
	v_mul_f32_e32 v241, s89, v241
	v_mul_f32_e32 v210, s89, v210
	v_mul_f32_e32 v242, s89, v242
	v_mul_f32_e32 v211, s89, v211
	v_mul_f32_e32 v243, s89, v243
	v_mul_f32_e32 v212, s89, v212
	v_mul_f32_e32 v244, s89, v244
	v_mul_f32_e32 v213, s89, v213
	v_mul_f32_e32 v245, s89, v245
	v_mul_f32_e32 v214, s89, v214
	v_mul_f32_e32 v246, s89, v246
	v_mul_f32_e32 v215, s89, v215
	v_mul_f32_e32 v247, s89, v247
	v_mul_f32_e32 v216, s89, v216
	v_mul_f32_e32 v248, s89, v248
	v_mul_f32_e32 v217, s89, v217
	v_mul_f32_e32 v249, s89, v249
	v_mul_f32_e32 v218, s89, v218
	v_mul_f32_e32 v188, s89, v188
	v_mul_f32_e32 v219, s89, v219
	v_mul_f32_e32 v189, s89, v189
	v_mul_f32_e32 v220, s89, v220
	v_mul_f32_e32 v190, s89, v190
	v_mul_f32_e32 v221, s89, v221
	v_mul_f32_e32 v191, s89, v191
	v_fma_f32 v124, v222, v124, v238
	v_fma_f32 v125, v223, v125, v239
	v_fma_f32 v126, v224, v126, v240
	v_fma_f32 v127, v225, v127, v241
	v_fma_f32 v120, v226, v120, v242
	v_fma_f32 v121, v227, v121, v243
	v_fma_f32 v122, v228, v122, v244
	v_fma_f32 v123, v229, v123, v245
	v_fma_f32 v104, v230, v104, v246
	v_fma_f32 v105, v231, v105, v247
	v_fma_f32 v106, v232, v106, v248
	v_fma_f32 v107, v233, v107, v249
	v_fma_f32 v96, v234, v96, v188
	v_fma_f32 v97, v235, v97, v189
	v_fma_f32 v98, v236, v98, v190
	v_fma_f32 v99, v237, v99, v191
	v_fma_f32 v116, v222, v116, v238
	v_fma_f32 v117, v223, v117, v239
	v_fma_f32 v118, v224, v118, v240
	v_fma_f32 v119, v225, v119, v241
	v_fma_f32 v112, v226, v112, v242
	v_fma_f32 v113, v227, v113, v243
	v_fma_f32 v114, v228, v114, v244
	v_fma_f32 v115, v229, v115, v245
	v_fma_f32 v88, v230, v88, v246
	v_fma_f32 v89, v231, v89, v247
	v_fma_f32 v90, v232, v90, v248
	v_fma_f32 v91, v233, v91, v249
	v_fma_f32 v80, v234, v80, v188
	v_fma_f32 v81, v235, v81, v189
	v_fma_f32 v82, v236, v82, v190
	v_fma_f32 v83, v237, v83, v191
	v_fma_f32 v108, v222, v108, v238
	v_fma_f32 v109, v223, v109, v239
	v_fma_f32 v110, v224, v110, v240
	v_fma_f32 v111, v225, v111, v241
	v_fma_f32 v100, v226, v100, v242
	v_fma_f32 v101, v227, v101, v243
	v_fma_f32 v102, v228, v102, v244
	v_fma_f32 v103, v229, v103, v245
	v_fma_f32 v76, v230, v76, v246
	v_fma_f32 v77, v231, v77, v247
	v_fma_f32 v78, v232, v78, v248
	v_fma_f32 v79, v233, v79, v249
	v_fma_f32 v72, v234, v72, v188
	v_fma_f32 v73, v235, v73, v189
	v_fma_f32 v74, v236, v74, v190
	v_fma_f32 v75, v237, v75, v191
	v_fma_f32 v92, v222, v92, v238
	v_fma_f32 v93, v223, v93, v239
	v_fma_f32 v94, v224, v94, v240
	v_fma_f32 v95, v225, v95, v241
	v_fma_f32 v84, v226, v84, v242
	v_fma_f32 v85, v227, v85, v243
	v_fma_f32 v86, v228, v86, v244
	v_fma_f32 v87, v229, v87, v245
	v_fma_f32 v68, v230, v68, v246
	v_fma_f32 v69, v231, v69, v247
	v_fma_f32 v70, v232, v70, v248
	v_fma_f32 v71, v233, v71, v249
	v_fma_f32 v64, v234, v64, v188
	v_fma_f32 v65, v235, v65, v189
	v_fma_f32 v66, v236, v66, v190
	v_fma_f32 v67, v237, v67, v191
	v_fma_f32 v60, v222, v60, v238
	v_fma_f32 v61, v223, v61, v239
	v_fma_f32 v62, v224, v62, v240
;     DI void operator()(const f32x4 (&acc)[2][2][4][2], const Unit& u, int wr, int wc, int fr, int fq) const {
;     ...
;                 const int row = u.pm * BM + ai * HALF + wr * 64 + m * 16 + fr;
;                 float mu = 0.f, rs = 1.f;
;                 if (pg) { const float2 st = RS[row]; mu = st.x; rs = st.y; }
; #pragma unroll
;                 for (int bj = 0; bj < 2; ++bj)
; #pragma unroll
;                     for (int n = 0; n < 2; ++n) {
;                         const int col = u.pn * BM + bj * HALF + wc * 32 + n * 16 + 4 * fq;
;                         float* xp = X + (size_t)row * DM + col;
;                         f32x4 x4 = *(const f32x4*)xp; const f32x4 g4 = *(const f32x4*)(g + col);
;                         if (pg) x4 = (x4 - mu) * rs * *(const f32x4*)(pg + col) + *(const f32x4*)(pb + col);
;                         *(f32x4*)xp = x4 * ALPHA + g4 * acc[ai][bj][m][n];
	v_fma_f32 v63, v225, v63, v241
	v_fma_f32 v56, v226, v56, v242
	v_fma_f32 v57, v227, v57, v243
	v_fma_f32 v58, v228, v58, v244
	v_fma_f32 v59, v229, v59, v245
	v_fma_f32 v40, v230, v40, v246
	v_fma_f32 v41, v231, v41, v247
	v_fma_f32 v42, v232, v42, v248
	v_fma_f32 v43, v233, v43, v249
	v_fma_f32 v32, v234, v32, v188
	v_fma_f32 v33, v235, v33, v189
	v_fma_f32 v34, v236, v34, v190
	v_fma_f32 v35, v237, v35, v191
	v_fma_f32 v52, v222, v52, v238
	v_fma_f32 v53, v223, v53, v239
	v_fma_f32 v54, v224, v54, v240
	v_fma_f32 v55, v225, v55, v241
	v_fma_f32 v48, v226, v48, v242
	v_fma_f32 v49, v227, v49, v243
	v_fma_f32 v50, v228, v50, v244
	v_fma_f32 v51, v229, v51, v245
	v_fma_f32 v24, v230, v24, v246
	v_fma_f32 v25, v231, v25, v247
	v_fma_f32 v26, v232, v26, v248
	v_fma_f32 v27, v233, v27, v249
	v_fma_f32 v16, v234, v16, v188
	v_fma_f32 v17, v235, v17, v189
	v_fma_f32 v18, v236, v18, v190
	v_fma_f32 v19, v237, v19, v191
	v_fma_f32 v44, v222, v44, v238
	v_fma_f32 v45, v223, v45, v239
	v_fma_f32 v46, v224, v46, v240
	v_fma_f32 v47, v225, v47, v241
	v_fma_f32 v36, v226, v36, v242
	v_fma_f32 v37, v227, v37, v243
	v_fma_f32 v38, v228, v38, v244
	v_fma_f32 v39, v229, v39, v245
	v_fma_f32 v12, v230, v12, v246
	v_fma_f32 v13, v231, v13, v247
	v_fma_f32 v14, v232, v14, v248
	v_fma_f32 v15, v233, v15, v249
	v_fma_f32 v8, v234, v8, v188
	v_fma_f32 v9, v235, v9, v189
	v_fma_f32 v10, v236, v10, v190
	v_fma_f32 v11, v237, v11, v191
	v_fma_f32 v28, v222, v28, v238
	v_fma_f32 v29, v223, v29, v239
	v_fma_f32 v30, v224, v30, v240
	v_fma_f32 v31, v225, v31, v241
	v_fma_f32 v20, v226, v20, v242
	v_fma_f32 v21, v227, v21, v243
	v_fma_f32 v22, v228, v22, v244
	v_fma_f32 v23, v229, v23, v245
	v_fma_f32 v4, v230, v4, v246
	v_fma_f32 v5, v231, v5, v247
	v_fma_f32 v6, v232, v6, v248
	v_fma_f32 v7, v233, v7, v249
	v_fma_f32 v0, v234, v0, v188
	v_fma_f32 v1, v235, v1, v189
	v_fma_f32 v2, v236, v2, v190
	v_fma_f32 v3, v237, v3, v191
	global_load_dwordx4 v[222:225], v161, s[72:73] offset:0 nt
	global_load_dwordx4 v[226:229], v161, s[72:73] offset:64 nt
	global_load_dwordx4 v[230:233], v161, s[72:73] offset:512 nt
	global_load_dwordx4 v[234:237], v161, s[72:73] offset:576 nt
	global_load_dwordx4 v[238:241], v163, s[72:73] offset:0 nt
	global_load_dwordx4 v[242:245], v163, s[72:73] offset:64 nt
	global_load_dwordx4 v[246:249], v163, s[72:73] offset:512 nt
	global_load_dwordx4 v[188:191], v163, s[72:73] offset:576 nt
	s_waitcnt vmcnt(0)
	v_sub_f32_e32 v222, v222, v128
	v_mul_f32_e32 v222, v222, v129
	v_fma_f32 v222, v222, v206, v124
	v_sub_f32_e32 v223, v223, v128
	v_mul_f32_e32 v223, v223, v129
	v_fma_f32 v223, v223, v207, v125
	v_sub_f32_e32 v224, v224, v128
	v_mul_f32_e32 v224, v224, v129
	v_fma_f32 v224, v224, v208, v126
	v_sub_f32_e32 v225, v225, v128
	v_mul_f32_e32 v225, v225, v129
	v_fma_f32 v225, v225, v209, v127
	v_sub_f32_e32 v226, v226, v128
	v_mul_f32_e32 v226, v226, v129
	v_fma_f32 v226, v226, v210, v120
	v_sub_f32_e32 v227, v227, v128
	v_mul_f32_e32 v227, v227, v129
	v_fma_f32 v227, v227, v211, v121
	v_sub_f32_e32 v228, v228, v128
	v_mul_f32_e32 v228, v228, v129
	v_fma_f32 v228, v228, v212, v122
	v_sub_f32_e32 v229, v229, v128
	v_mul_f32_e32 v229, v229, v129
	v_fma_f32 v229, v229, v213, v123
	v_sub_f32_e32 v230, v230, v128
	v_mul_f32_e32 v230, v230, v129
	v_fma_f32 v230, v230, v214, v104
	v_sub_f32_e32 v231, v231, v128
	v_mul_f32_e32 v231, v231, v129
	v_fma_f32 v231, v231, v215, v105
	v_sub_f32_e32 v232, v232, v128
	v_mul_f32_e32 v232, v232, v129
	v_fma_f32 v232, v232, v216, v106
	v_sub_f32_e32 v233, v233, v128
	v_mul_f32_e32 v233, v233, v129
	v_fma_f32 v233, v233, v217, v107
	v_sub_f32_e32 v234, v234, v128
	v_mul_f32_e32 v234, v234, v129
	v_fma_f32 v234, v234, v218, v96
	v_sub_f32_e32 v235, v235, v128
	v_mul_f32_e32 v235, v235, v129
	v_fma_f32 v235, v235, v219, v97
	v_sub_f32_e32 v236, v236, v128
	v_mul_f32_e32 v236, v236, v129
	v_fma_f32 v236, v236, v220, v98
	v_sub_f32_e32 v237, v237, v128
	v_mul_f32_e32 v237, v237, v129
	v_fma_f32 v237, v237, v221, v99
	v_sub_f32_e32 v238, v238, v130
	v_mul_f32_e32 v238, v238, v131
	v_fma_f32 v238, v238, v206, v116
	v_sub_f32_e32 v239, v239, v130
	v_mul_f32_e32 v239, v239, v131
	v_fma_f32 v239, v239, v207, v117
	v_sub_f32_e32 v240, v240, v130
	v_mul_f32_e32 v240, v240, v131
	v_fma_f32 v240, v240, v208, v118
	v_sub_f32_e32 v241, v241, v130
	v_mul_f32_e32 v241, v241, v131
	v_fma_f32 v241, v241, v209, v119
	v_sub_f32_e32 v242, v242, v130
	v_mul_f32_e32 v242, v242, v131
	v_fma_f32 v242, v242, v210, v112
	v_sub_f32_e32 v243, v243, v130
	v_mul_f32_e32 v243, v243, v131
	v_fma_f32 v243, v243, v211, v113
	v_sub_f32_e32 v244, v244, v130
	v_mul_f32_e32 v244, v244, v131
	v_fma_f32 v244, v244, v212, v114
	v_sub_f32_e32 v245, v245, v130
	v_mul_f32_e32 v245, v245, v131
	v_fma_f32 v245, v245, v213, v115
	v_sub_f32_e32 v246, v246, v130
	v_mul_f32_e32 v246, v246, v131
	v_fma_f32 v246, v246, v214, v88
	v_sub_f32_e32 v247, v247, v130
	v_mul_f32_e32 v247, v247, v131
	v_fma_f32 v247, v247, v215, v89
	v_sub_f32_e32 v248, v248, v130
	v_mul_f32_e32 v248, v248, v131
	v_fma_f32 v248, v248, v216, v90
	v_sub_f32_e32 v249, v249, v130
	v_mul_f32_e32 v249, v249, v131
	v_fma_f32 v249, v249, v217, v91
	v_sub_f32_e32 v188, v188, v130
	v_mul_f32_e32 v188, v188, v131
	v_fma_f32 v188, v188, v218, v80
	v_sub_f32_e32 v189, v189, v130
	v_mul_f32_e32 v189, v189, v131
	v_fma_f32 v189, v189, v219, v81
	v_sub_f32_e32 v190, v190, v130
	v_mul_f32_e32 v190, v190, v131
	v_fma_f32 v190, v190, v220, v82
	v_sub_f32_e32 v191, v191, v130
	v_mul_f32_e32 v191, v191, v131
	v_fma_f32 v191, v191, v221, v83
	global_load_dwordx4 v[124:127], v165, s[72:73] offset:0 nt
	global_load_dwordx4 v[120:123], v165, s[72:73] offset:64 nt
	global_load_dwordx4 v[104:107], v165, s[72:73] offset:512 nt
	global_load_dwordx4 v[96:99], v165, s[72:73] offset:576 nt
	global_load_dwordx4 v[116:119], v192, s[72:73] offset:0 nt
	global_load_dwordx4 v[112:115], v192, s[72:73] offset:64 nt
	global_load_dwordx4 v[88:91], v192, s[72:73] offset:512 nt
	global_load_dwordx4 v[80:83], v192, s[72:73] offset:576 nt
	global_store_dwordx4 v161, v[222:225], s[72:73] offset:0
	global_store_dwordx4 v161, v[226:229], s[72:73] offset:64
	global_store_dwordx4 v161, v[230:233], s[72:73] offset:512
	global_store_dwordx4 v161, v[234:237], s[72:73] offset:576
	global_store_dwordx4 v163, v[238:241], s[72:73] offset:0
	global_store_dwordx4 v163, v[242:245], s[72:73] offset:64
	global_store_dwordx4 v163, v[246:249], s[72:73] offset:512
	global_store_dwordx4 v163, v[188:191], s[72:73] offset:576
	global_load_dwordx4 v[222:225], v193, s[72:73] offset:0 nt
	global_load_dwordx4 v[226:229], v193, s[72:73] offset:64 nt
	global_load_dwordx4 v[230:233], v193, s[72:73] offset:512 nt
	global_load_dwordx4 v[234:237], v193, s[72:73] offset:576 nt
	global_load_dwordx4 v[238:241], v194, s[72:73] offset:0 nt
	global_load_dwordx4 v[242:245], v194, s[72:73] offset:64 nt
	global_load_dwordx4 v[246:249], v194, s[72:73] offset:512 nt
	global_load_dwordx4 v[188:191], v194, s[72:73] offset:576 nt
	s_waitcnt vmcnt(0)
;     DI void operator()(const f32x4 (&acc)[2][2][4][2], const Unit& u, int wr, int wc, int fr, int fq) const {
;     ...
;                     for (int n = 0; n < 2; ++n) {
;                         const int col = u.pn * BM + bj * HALF + wc * 32 + n * 16 + 4 * fq;
;                         float* xp = X + (size_t)row * DM + col;
;                         f32x4 x4 = *(const f32x4*)xp; const f32x4 g4 = *(const f32x4*)(g + col);
;                         if (pg) x4 = (x4 - mu) * rs * *(const f32x4*)(pg + col) + *(const f32x4*)(pb + col);
;                         *(f32x4*)xp = x4 * ALPHA + g4 * acc[ai][bj][m][n];
	v_sub_f32_e32 v124, v124, v132
	v_mul_f32_e32 v124, v124, v133
	v_fma_f32 v124, v124, v206, v108
	v_sub_f32_e32 v125, v125, v132
	v_mul_f32_e32 v125, v125, v133
	v_fma_f32 v125, v125, v207, v109
	v_sub_f32_e32 v126, v126, v132
	v_mul_f32_e32 v126, v126, v133
	v_fma_f32 v126, v126, v208, v110
	v_sub_f32_e32 v127, v127, v132
	v_mul_f32_e32 v127, v127, v133
	v_fma_f32 v127, v127, v209, v111
	v_sub_f32_e32 v120, v120, v132
	v_mul_f32_e32 v120, v120, v133
	v_fma_f32 v120, v120, v210, v100
	v_sub_f32_e32 v121, v121, v132
	v_mul_f32_e32 v121, v121, v133
	v_fma_f32 v121, v121, v211, v101
	v_sub_f32_e32 v122, v122, v132
	v_mul_f32_e32 v122, v122, v133
	v_fma_f32 v122, v122, v212, v102
	v_sub_f32_e32 v123, v123, v132
	v_mul_f32_e32 v123, v123, v133
	v_fma_f32 v123, v123, v213, v103
	v_sub_f32_e32 v104, v104, v132
	v_mul_f32_e32 v104, v104, v133
	v_fma_f32 v104, v104, v214, v76
	v_sub_f32_e32 v105, v105, v132
	v_mul_f32_e32 v105, v105, v133
	v_fma_f32 v105, v105, v215, v77
	v_sub_f32_e32 v106, v106, v132
	v_mul_f32_e32 v106, v106, v133
	v_fma_f32 v106, v106, v216, v78
	v_sub_f32_e32 v107, v107, v132
	v_mul_f32_e32 v107, v107, v133
	v_fma_f32 v107, v107, v217, v79
	v_sub_f32_e32 v96, v96, v132
	v_mul_f32_e32 v96, v96, v133
	v_fma_f32 v96, v96, v218, v72
	v_sub_f32_e32 v97, v97, v132
	v_mul_f32_e32 v97, v97, v133
	v_fma_f32 v97, v97, v219, v73
	v_sub_f32_e32 v98, v98, v132
	v_mul_f32_e32 v98, v98, v133
	v_fma_f32 v98, v98, v220, v74
	v_sub_f32_e32 v99, v99, v132
	v_mul_f32_e32 v99, v99, v133
	v_fma_f32 v99, v99, v221, v75
	v_sub_f32_e32 v116, v116, v134
	v_mul_f32_e32 v116, v116, v135
	v_fma_f32 v116, v116, v206, v92
	v_sub_f32_e32 v117, v117, v134
	v_mul_f32_e32 v117, v117, v135
	v_fma_f32 v117, v117, v207, v93
	v_sub_f32_e32 v118, v118, v134
	v_mul_f32_e32 v118, v118, v135
	v_fma_f32 v118, v118, v208, v94
	v_sub_f32_e32 v119, v119, v134
	v_mul_f32_e32 v119, v119, v135
	v_fma_f32 v119, v119, v209, v95
	v_sub_f32_e32 v112, v112, v134
	v_mul_f32_e32 v112, v112, v135
	v_fma_f32 v112, v112, v210, v84
	v_sub_f32_e32 v113, v113, v134
	v_mul_f32_e32 v113, v113, v135
	v_fma_f32 v113, v113, v211, v85
	v_sub_f32_e32 v114, v114, v134
	v_mul_f32_e32 v114, v114, v135
	v_fma_f32 v114, v114, v212, v86
	v_sub_f32_e32 v115, v115, v134
	v_mul_f32_e32 v115, v115, v135
	v_fma_f32 v115, v115, v213, v87
	v_sub_f32_e32 v88, v88, v134
	v_mul_f32_e32 v88, v88, v135
	v_fma_f32 v88, v88, v214, v68
	v_sub_f32_e32 v89, v89, v134
	v_mul_f32_e32 v89, v89, v135
	v_fma_f32 v89, v89, v215, v69
	v_sub_f32_e32 v90, v90, v134
	v_mul_f32_e32 v90, v90, v135
	v_fma_f32 v90, v90, v216, v70
	v_sub_f32_e32 v91, v91, v134
	v_mul_f32_e32 v91, v91, v135
	v_fma_f32 v91, v91, v217, v71
	v_sub_f32_e32 v80, v80, v134
	v_mul_f32_e32 v80, v80, v135
	v_fma_f32 v80, v80, v218, v64
	v_sub_f32_e32 v81, v81, v134
	v_mul_f32_e32 v81, v81, v135
	v_fma_f32 v81, v81, v219, v65
	v_sub_f32_e32 v82, v82, v134
	v_mul_f32_e32 v82, v82, v135
	v_fma_f32 v82, v82, v220, v66
	v_sub_f32_e32 v83, v83, v134
	v_mul_f32_e32 v83, v83, v135
	v_fma_f32 v83, v83, v221, v67
	v_sub_f32_e32 v222, v222, v136
	v_mul_f32_e32 v222, v222, v137
	v_fma_f32 v222, v222, v206, v60
	v_sub_f32_e32 v223, v223, v136
	v_mul_f32_e32 v223, v223, v137
	v_fma_f32 v223, v223, v207, v61
	v_sub_f32_e32 v224, v224, v136
	v_mul_f32_e32 v224, v224, v137
	v_fma_f32 v224, v224, v208, v62
	v_sub_f32_e32 v225, v225, v136
	v_mul_f32_e32 v225, v225, v137
	v_fma_f32 v225, v225, v209, v63
	v_sub_f32_e32 v226, v226, v136
	v_mul_f32_e32 v226, v226, v137
	v_fma_f32 v226, v226, v210, v56
	v_sub_f32_e32 v227, v227, v136
	v_mul_f32_e32 v227, v227, v137
	v_fma_f32 v227, v227, v211, v57
	v_sub_f32_e32 v228, v228, v136
	v_mul_f32_e32 v228, v228, v137
	v_fma_f32 v228, v228, v212, v58
	v_sub_f32_e32 v229, v229, v136
	v_mul_f32_e32 v229, v229, v137
	v_fma_f32 v229, v229, v213, v59
	v_sub_f32_e32 v230, v230, v136
	v_mul_f32_e32 v230, v230, v137
	v_fma_f32 v230, v230, v214, v40
	v_sub_f32_e32 v231, v231, v136
	v_mul_f32_e32 v231, v231, v137
	v_fma_f32 v231, v231, v215, v41
	v_sub_f32_e32 v232, v232, v136
	v_mul_f32_e32 v232, v232, v137
	v_fma_f32 v232, v232, v216, v42
	v_sub_f32_e32 v233, v233, v136
	v_mul_f32_e32 v233, v233, v137
	v_fma_f32 v233, v233, v217, v43
	v_sub_f32_e32 v234, v234, v136
	v_mul_f32_e32 v234, v234, v137
	v_fma_f32 v234, v234, v218, v32
	v_sub_f32_e32 v235, v235, v136
	v_mul_f32_e32 v235, v235, v137
	v_fma_f32 v235, v235, v219, v33
	v_sub_f32_e32 v236, v236, v136
	v_mul_f32_e32 v236, v236, v137
	v_fma_f32 v236, v236, v220, v34
	v_sub_f32_e32 v237, v237, v136
	v_mul_f32_e32 v237, v237, v137
	v_fma_f32 v237, v237, v221, v35
	v_sub_f32_e32 v238, v238, v138
	v_mul_f32_e32 v238, v238, v139
	v_fma_f32 v238, v238, v206, v52
	v_sub_f32_e32 v239, v239, v138
	v_mul_f32_e32 v239, v239, v139
	v_fma_f32 v239, v239, v207, v53
	v_sub_f32_e32 v240, v240, v138
	v_mul_f32_e32 v240, v240, v139
	v_fma_f32 v240, v240, v208, v54
	v_sub_f32_e32 v241, v241, v138
	v_mul_f32_e32 v241, v241, v139
	v_fma_f32 v241, v241, v209, v55
	v_sub_f32_e32 v242, v242, v138
	v_mul_f32_e32 v242, v242, v139
	v_fma_f32 v242, v242, v210, v48
	v_sub_f32_e32 v243, v243, v138
	v_mul_f32_e32 v243, v243, v139
	v_fma_f32 v243, v243, v211, v49
	v_sub_f32_e32 v244, v244, v138
	v_mul_f32_e32 v244, v244, v139
	v_fma_f32 v244, v244, v212, v50
	v_sub_f32_e32 v245, v245, v138
	v_mul_f32_e32 v245, v245, v139
	v_fma_f32 v245, v245, v213, v51
	v_sub_f32_e32 v246, v246, v138
	v_mul_f32_e32 v246, v246, v139
	v_fma_f32 v246, v246, v214, v24
	v_sub_f32_e32 v247, v247, v138
;     DI void operator()(const f32x4 (&acc)[2][2][4][2], const Unit& u, int wr, int wc, int fr, int fq) const {
;     ...
;                     for (int n = 0; n < 2; ++n) {
;                         const int col = u.pn * BM + bj * HALF + wc * 32 + n * 16 + 4 * fq;
;                         float* xp = X + (size_t)row * DM + col;
;                         f32x4 x4 = *(const f32x4*)xp; const f32x4 g4 = *(const f32x4*)(g + col);
;                         if (pg) x4 = (x4 - mu) * rs * *(const f32x4*)(pg + col) + *(const f32x4*)(pb + col);
;                         *(f32x4*)xp = x4 * ALPHA + g4 * acc[ai][bj][m][n];
	v_mul_f32_e32 v247, v247, v139
	v_fma_f32 v247, v247, v215, v25
	v_sub_f32_e32 v248, v248, v138
	v_mul_f32_e32 v248, v248, v139
	v_fma_f32 v248, v248, v216, v26
	v_sub_f32_e32 v249, v249, v138
	v_mul_f32_e32 v249, v249, v139
	v_fma_f32 v249, v249, v217, v27
	v_sub_f32_e32 v188, v188, v138
	v_mul_f32_e32 v188, v188, v139
	v_fma_f32 v188, v188, v218, v16
	v_sub_f32_e32 v189, v189, v138
	v_mul_f32_e32 v189, v189, v139
	v_fma_f32 v189, v189, v219, v17
	v_sub_f32_e32 v190, v190, v138
	v_mul_f32_e32 v190, v190, v139
	v_fma_f32 v190, v190, v220, v18
	v_sub_f32_e32 v191, v191, v138
	v_mul_f32_e32 v191, v191, v139
	v_fma_f32 v191, v191, v221, v19
	global_load_dwordx4 v[108:111], v195, s[72:73] offset:0 nt
	global_load_dwordx4 v[100:103], v195, s[72:73] offset:64 nt
	global_load_dwordx4 v[76:79], v195, s[72:73] offset:512 nt
	global_load_dwordx4 v[72:75], v195, s[72:73] offset:576 nt
	global_load_dwordx4 v[92:95], v196, s[72:73] offset:0 nt
	global_load_dwordx4 v[84:87], v196, s[72:73] offset:64 nt
	global_load_dwordx4 v[68:71], v196, s[72:73] offset:512 nt
	global_load_dwordx4 v[64:67], v196, s[72:73] offset:576 nt
	global_store_dwordx4 v165, v[124:127], s[72:73] offset:0
	global_store_dwordx4 v165, v[120:123], s[72:73] offset:64
	global_store_dwordx4 v165, v[104:107], s[72:73] offset:512
	global_store_dwordx4 v165, v[96:99], s[72:73] offset:576
	global_store_dwordx4 v192, v[116:119], s[72:73] offset:0
	global_store_dwordx4 v192, v[112:115], s[72:73] offset:64
	global_store_dwordx4 v192, v[88:91], s[72:73] offset:512
	global_store_dwordx4 v192, v[80:83], s[72:73] offset:576
	global_store_dwordx4 v193, v[222:225], s[72:73] offset:0
	global_store_dwordx4 v193, v[226:229], s[72:73] offset:64
	global_store_dwordx4 v193, v[230:233], s[72:73] offset:512
	global_store_dwordx4 v193, v[234:237], s[72:73] offset:576
	global_store_dwordx4 v194, v[238:241], s[72:73] offset:0
	global_store_dwordx4 v194, v[242:245], s[72:73] offset:64
	global_store_dwordx4 v194, v[246:249], s[72:73] offset:512
	global_store_dwordx4 v194, v[188:191], s[72:73] offset:576
	s_waitcnt vmcnt(16)
	v_sub_f32_e32 v108, v108, v140
	v_mul_f32_e32 v108, v108, v141
	v_fma_f32 v108, v108, v206, v44
	v_sub_f32_e32 v109, v109, v140
	v_mul_f32_e32 v109, v109, v141
	v_fma_f32 v109, v109, v207, v45
	v_sub_f32_e32 v110, v110, v140
	v_mul_f32_e32 v110, v110, v141
	v_fma_f32 v110, v110, v208, v46
	v_sub_f32_e32 v111, v111, v140
	v_mul_f32_e32 v111, v111, v141
	v_fma_f32 v111, v111, v209, v47
	v_sub_f32_e32 v100, v100, v140
	v_mul_f32_e32 v100, v100, v141
	v_fma_f32 v100, v100, v210, v36
	v_sub_f32_e32 v101, v101, v140
	v_mul_f32_e32 v101, v101, v141
	v_fma_f32 v101, v101, v211, v37
	v_sub_f32_e32 v102, v102, v140
	v_mul_f32_e32 v102, v102, v141
	v_fma_f32 v102, v102, v212, v38
	v_sub_f32_e32 v103, v103, v140
	v_mul_f32_e32 v103, v103, v141
	v_fma_f32 v103, v103, v213, v39
	v_sub_f32_e32 v76, v76, v140
	v_mul_f32_e32 v76, v76, v141
	v_fma_f32 v76, v76, v214, v12
	v_sub_f32_e32 v77, v77, v140
	v_mul_f32_e32 v77, v77, v141
	v_fma_f32 v77, v77, v215, v13
	v_sub_f32_e32 v78, v78, v140
	v_mul_f32_e32 v78, v78, v141
	v_fma_f32 v78, v78, v216, v14
	v_sub_f32_e32 v79, v79, v140
	v_mul_f32_e32 v79, v79, v141
	v_fma_f32 v79, v79, v217, v15
	v_sub_f32_e32 v72, v72, v140
	v_mul_f32_e32 v72, v72, v141
	v_fma_f32 v72, v72, v218, v8
	v_sub_f32_e32 v73, v73, v140
	v_mul_f32_e32 v73, v73, v141
	v_fma_f32 v73, v73, v219, v9
	v_sub_f32_e32 v74, v74, v140
	v_mul_f32_e32 v74, v74, v141
	v_fma_f32 v74, v74, v220, v10
	v_sub_f32_e32 v75, v75, v140
	v_mul_f32_e32 v75, v75, v141
	v_fma_f32 v75, v75, v221, v11
	v_sub_f32_e32 v92, v92, v142
	v_mul_f32_e32 v92, v92, v143
	v_fma_f32 v92, v92, v206, v28
	v_sub_f32_e32 v93, v93, v142
	v_mul_f32_e32 v93, v93, v143
	v_fma_f32 v93, v93, v207, v29
	v_sub_f32_e32 v94, v94, v142
	v_mul_f32_e32 v94, v94, v143
	v_fma_f32 v94, v94, v208, v30
	v_sub_f32_e32 v95, v95, v142
	v_mul_f32_e32 v95, v95, v143
	v_fma_f32 v95, v95, v209, v31
	v_sub_f32_e32 v84, v84, v142
	v_mul_f32_e32 v84, v84, v143
	v_fma_f32 v84, v84, v210, v20
	v_sub_f32_e32 v85, v85, v142
	v_mul_f32_e32 v85, v85, v143
	v_fma_f32 v85, v85, v211, v21
	v_sub_f32_e32 v86, v86, v142
	v_mul_f32_e32 v86, v86, v143
	v_fma_f32 v86, v86, v212, v22
	v_sub_f32_e32 v87, v87, v142
	v_mul_f32_e32 v87, v87, v143
	v_fma_f32 v87, v87, v213, v23
	v_sub_f32_e32 v68, v68, v142
	v_mul_f32_e32 v68, v68, v143
	v_fma_f32 v68, v68, v214, v4
	v_sub_f32_e32 v69, v69, v142
	v_mul_f32_e32 v69, v69, v143
	v_fma_f32 v69, v69, v215, v5
	v_sub_f32_e32 v70, v70, v142
	v_mul_f32_e32 v70, v70, v143
	v_fma_f32 v70, v70, v216, v6
	v_sub_f32_e32 v71, v71, v142
	v_mul_f32_e32 v71, v71, v143
	v_fma_f32 v71, v71, v217, v7
	v_sub_f32_e32 v64, v64, v142
	v_mul_f32_e32 v64, v64, v143
	v_fma_f32 v64, v64, v218, v0
	v_sub_f32_e32 v65, v65, v142
	v_mul_f32_e32 v65, v65, v143
	v_fma_f32 v65, v65, v219, v1
	v_sub_f32_e32 v66, v66, v142
	v_mul_f32_e32 v66, v66, v143
	v_fma_f32 v66, v66, v220, v2
	v_sub_f32_e32 v67, v67, v142
	v_mul_f32_e32 v67, v67, v143
	v_fma_f32 v67, v67, v221, v3
	global_store_dwordx4 v195, v[108:111], s[72:73] offset:0
	global_store_dwordx4 v195, v[100:103], s[72:73] offset:64
	global_store_dwordx4 v195, v[76:79], s[72:73] offset:512
	global_store_dwordx4 v195, v[72:75], s[72:73] offset:576
	global_store_dwordx4 v196, v[92:95], s[72:73] offset:0
	global_store_dwordx4 v196, v[84:87], s[72:73] offset:64
	global_store_dwordx4 v196, v[68:71], s[72:73] offset:512
	global_store_dwordx4 v196, v[64:67], s[72:73] offset:576
	s_branch .LBB0_1693

; DI void phase_ln(const Params& p, const float* gam, const float* bet, const float* modnext  , bool skip_ctx, bool final_out,
;                  const float* cgate  , const float* pg, const float* pb  ) {
;     ...
;     for (int rowA = gw; rowA < MR; rowA += 2 * nw) {
;         f32x4 v[2][8]; float sum[2] = {0.f, 0.f}; bool act[2]; int rows[2];
; #pragma unroll
;         for (int q = 0; q < 2; ++q) {
;             const int row = rowA + q * nw; rows[q] = row;
;             const int b = row / RB, r = row % RB;
;             act[q] = row < MR && !(skip_ctx && r < CL);
;             if (act[q]) {
;                 const bool cpart = cgate && r < CL;
;                 float pmu = 0.f, prs = 1.f;
;                 if (cpart && pg) { const float2 st = RS[row]; pmu = st.x; prs = st.y; }
; #pragma unroll
;                 for (int i = 0; i < 8; ++i) {
;                     const int col = (i * 64 + lane) * 4;
;                     v[q][i] = *(const f32x4*)(X + (size_t)row * DM + col);
.Ll0b_row:
	s_cmpk_ge_u32 s9, 0x2400
	s_cbranch_scc1 .Ll0b_done
	s_lshr_b32 s35, s9, 8
	s_mul_i32 s27, s35, 57
	s_lshr_b32 s27, s27, 9
	s_mul_i32 s35, s27, 0x900
	s_sub_u32 s29, s9, s35
	s_cmpk_lt_u32 s29, 0x100
	s_cselect_b32 s32, 4, s27
	s_lshl_b32 s35, s9, 13
	s_add_u32 s2, s50, 0xcba0000
	s_addc_u32 s3, s51, 0
	s_add_u32 s2, s2, s35
	s_addc_u32 s3, s3, 0
	global_load_dwordx4 v[88:91], v76, s[2:3] offset:0 nt
	global_load_dwordx4 v[92:95], v76, s[2:3] offset:1024 nt
	global_load_dwordx4 v[96:99], v76, s[2:3] offset:2048 nt
	global_load_dwordx4 v[100:103], v76, s[2:3] offset:3072 nt
	global_load_dwordx4 v[104:107], v77, s[2:3] offset:0 nt
	global_load_dwordx4 v[108:111], v77, s[2:3] offset:1024 nt
	global_load_dwordx4 v[112:115], v77, s[2:3] offset:2048 nt
	global_load_dwordx4 v[116:119], v77, s[2:3] offset:3072 nt
	s_cmpk_lt_u32 s29, 0x100
	s_cbranch_scc1 .Ll0b_cpart

; DI void phase_ln(const Params& p, const float* gam, const float* bet, const float* modnext  , bool skip_ctx, bool final_out,
;                  const float* cgate  , const float* pg, const float* pb  ) {
;     ...
;                 const bool cpart = cgate && r < CL;
;                 float pmu = 0.f, prs = 1.f;
;                 if (cpart && pg) { const float2 st = RS[row]; pmu = st.x; prs = st.y; }
; #pragma unroll
;                 for (int i = 0; i < 8; ++i) {
;                     const int col = (i * 64 + lane) * 4;
;                     v[q][i] = *(const f32x4*)(X + (size_t)row * DM + col);
;                     if (cpart) {
;                         if (pg) v[q][i] = (v[q][i] - pmu) * prs * *(const f32x4*)(pg + col) + *(const f32x4*)(pb + col);
;                         const float* pt = (const float*)(p.ws + WS_PART) + ((size_t)b * 256 + r) * DM + col;
;                         const f32x4 ps = *(const f32x4*)pt + *(const f32x4*)(pt + (size_t)1024 * DM) + *(const f32x4*)(pt + (size_t)2048 * DM) + *(const f32x4*)(pt + (size_t)3072 * DM);
;                         v[q][i] = v[q][i] * ALPHA + *(const f32x4*)(cgate + col) * ps;
;                         *(f32x4*)(X + (size_t)row * DM + col) = v[q][i];
.Ll0b_cpart:
	s_lshl_b32 s35, s27, 8
	s_add_u32 s35, s35, s29
	s_lshl_b32 s35, s35, 13
	s_add_u32 s4, s50, 0x123a0000
	s_addc_u32 s5, s51, 0
	s_add_u32 s4, s4, s35
	s_addc_u32 s5, s5, 0
	s_lshl_b32 s35, s9, 3
	s_add_u32 s22, s50, 0x260a0000
	s_addc_u32 s23, s51, 0
	s_add_u32 s22, s22, s35
	s_addc_u32 s23, s23, 0
	global_load_dwordx2 v[238:239], v79, s[22:23]
	global_load_dwordx4 v[140:143], v76, s[4:5] offset:0 nt
	global_load_dwordx4 v[144:147], v76, s[4:5] offset:1024 nt
	s_add_u32 s4, s4, 0x800000
	s_addc_u32 s5, s5, 0
	global_load_dwordx4 v[148:151], v76, s[4:5] offset:0 nt
	global_load_dwordx4 v[152:155], v76, s[4:5] offset:1024 nt
	s_add_u32 s4, s4, 0x800000
	s_addc_u32 s5, s5, 0
	global_load_dwordx4 v[156:159], v76, s[4:5] offset:0 nt
	global_load_dwordx4 v[160:163], v76, s[4:5] offset:1024 nt
	s_add_u32 s4, s4, 0x800000
	s_addc_u32 s5, s5, 0
	global_load_dwordx4 v[164:167], v76, s[4:5] offset:0 nt
	global_load_dwordx4 v[168:171], v76, s[4:5] offset:1024 nt
	s_sub_u32 s4, s4, 0x1800000
	s_subb_u32 s5, s5, 0
	s_add_u32 s22, s50, 0x42000
	s_addc_u32 s23, s51, 0
	global_load_dwordx4 v[204:207], v76, s[22:23] offset:0
	global_load_dwordx4 v[208:211], v76, s[22:23] offset:1024
	global_load_dwordx4 v[212:215], v76, s[64:65] offset:0
	global_load_dwordx4 v[216:219], v76, s[64:65] offset:1024
	global_load_dwordx4 v[220:223], v76, s[66:67] offset:0
	global_load_dwordx4 v[224:227], v76, s[66:67] offset:1024
	s_waitcnt vmcnt(0)
	v_sub_f32_e32 v88, v88, v238
	v_mul_f32_e32 v88, v88, v239
	v_fma_f32 v88, v88, v212, v220
	v_add_f32_e32 v140, v140, v148
	v_add_f32_e32 v140, v140, v156
	v_add_f32_e32 v140, v140, v164
	v_mul_f32_e32 v140, v204, v140
	v_fmac_f32_e32 v140, s89, v88
	v_mov_b32_e32 v88, v140
	v_sub_f32_e32 v89, v89, v238
	v_mul_f32_e32 v89, v89, v239
	v_fma_f32 v89, v89, v213, v221
	v_add_f32_e32 v141, v141, v149
	v_add_f32_e32 v141, v141, v157
	v_add_f32_e32 v141, v141, v165
	v_mul_f32_e32 v141, v205, v141
	v_fmac_f32_e32 v141, s89, v89
	v_mov_b32_e32 v89, v141
	v_sub_f32_e32 v90, v90, v238
	v_mul_f32_e32 v90, v90, v239
	v_fma_f32 v90, v90, v214, v222
	v_add_f32_e32 v142, v142, v150
	v_add_f32_e32 v142, v142, v158
	v_add_f32_e32 v142, v142, v166
	v_mul_f32_e32 v142, v206, v142
	v_fmac_f32_e32 v142, s89, v90
	v_mov_b32_e32 v90, v142
	v_sub_f32_e32 v91, v91, v238
	v_mul_f32_e32 v91, v91, v239
	v_fma_f32 v91, v91, v215, v223
	v_add_f32_e32 v143, v143, v151
	v_add_f32_e32 v143, v143, v159
	v_add_f32_e32 v143, v143, v167
	v_mul_f32_e32 v143, v207, v143
	v_fmac_f32_e32 v143, s89, v91
	v_mov_b32_e32 v91, v143
	global_store_dwordx4 v76, v[88:91], s[2:3] offset:0
	v_sub_f32_e32 v92, v92, v238
	v_mul_f32_e32 v92, v92, v239
	v_fma_f32 v92, v92, v216, v224
	v_add_f32_e32 v144, v144, v152
	v_add_f32_e32 v144, v144, v160
	v_add_f32_e32 v144, v144, v168
	v_mul_f32_e32 v144, v208, v144
	v_fmac_f32_e32 v144, s89, v92
	v_mov_b32_e32 v92, v144
	v_sub_f32_e32 v93, v93, v238
	v_mul_f32_e32 v93, v93, v239
	v_fma_f32 v93, v93, v217, v225
	v_add_f32_e32 v145, v145, v153
	v_add_f32_e32 v145, v145, v161
	v_add_f32_e32 v145, v145, v169
	v_mul_f32_e32 v145, v209, v145
	v_fmac_f32_e32 v145, s89, v93
	v_mov_b32_e32 v93, v145
	v_sub_f32_e32 v94, v94, v238
	v_mul_f32_e32 v94, v94, v239
	v_fma_f32 v94, v94, v218, v226
	v_add_f32_e32 v146, v146, v154
	v_add_f32_e32 v146, v146, v162
	v_add_f32_e32 v146, v146, v170
	v_mul_f32_e32 v146, v210, v146
	v_fmac_f32_e32 v146, s89, v94
	v_mov_b32_e32 v94, v146
	v_sub_f32_e32 v95, v95, v238
	v_mul_f32_e32 v95, v95, v239
	v_fma_f32 v95, v95, v219, v227
	v_add_f32_e32 v147, v147, v155
	v_add_f32_e32 v147, v147, v163
	v_add_f32_e32 v147, v147, v171
	v_mul_f32_e32 v147, v211, v147
	v_fmac_f32_e32 v147, s89, v95
	v_mov_b32_e32 v95, v147
	global_store_dwordx4 v76, v[92:95], s[2:3] offset:1024
	global_load_dwordx4 v[140:143], v76, s[4:5] offset:2048 nt
	global_load_dwordx4 v[144:147], v76, s[4:5] offset:3072 nt
	s_add_u32 s4, s4, 0x800000
	s_addc_u32 s5, s5, 0
	global_load_dwordx4 v[148:151], v76, s[4:5] offset:2048 nt
	global_load_dwordx4 v[152:155], v76, s[4:5] offset:3072 nt
	s_add_u32 s4, s4, 0x800000
	s_addc_u32 s5, s5, 0
	global_load_dwordx4 v[156:159], v76, s[4:5] offset:2048 nt
	global_load_dwordx4 v[160:163], v76, s[4:5] offset:3072 nt
	s_add_u32 s4, s4, 0x800000
	s_addc_u32 s5, s5, 0
	global_load_dwordx4 v[164:167], v76, s[4:5] offset:2048 nt
	global_load_dwordx4 v[168:171], v76, s[4:5] offset:3072 nt
	s_sub_u32 s4, s4, 0x1800000
	s_subb_u32 s5, s5, 0
	s_add_u32 s22, s50, 0x42000
	s_addc_u32 s23, s51, 0
	global_load_dwordx4 v[204:207], v76, s[22:23] offset:2048
	global_load_dwordx4 v[208:211], v76, s[22:23] offset:3072
	global_load_dwordx4 v[212:215], v76, s[64:65] offset:2048
	global_load_dwordx4 v[216:219], v76, s[64:65] offset:3072
	global_load_dwordx4 v[220:223], v76, s[66:67] offset:2048
	global_load_dwordx4 v[224:227], v76, s[66:67] offset:3072
	s_waitcnt vmcnt(0)
; DI void phase_ln(const Params& p, const float* gam, const float* bet, const float* modnext  , bool skip_ctx, bool final_out,
;                  const float* cgate  , const float* pg, const float* pb  ) {
;     ...
;                     if (cpart) {
;                         if (pg) v[q][i] = (v[q][i] - pmu) * prs * *(const f32x4*)(pg + col) + *(const f32x4*)(pb + col);
;                         const float* pt = (const float*)(p.ws + WS_PART) + ((size_t)b * 256 + r) * DM + col;
;                         const f32x4 ps = *(const f32x4*)pt + *(const f32x4*)(pt + (size_t)1024 * DM) + *(const f32x4*)(pt + (size_t)2048 * DM) + *(const f32x4*)(pt + (size_t)3072 * DM);
;                         v[q][i] = v[q][i] * ALPHA + *(const f32x4*)(cgate + col) * ps;
;                         *(f32x4*)(X + (size_t)row * DM + col) = v[q][i];
	v_sub_f32_e32 v96, v96, v238
	v_mul_f32_e32 v96, v96, v239
	v_fma_f32 v96, v96, v212, v220
	v_add_f32_e32 v140, v140, v148
	v_add_f32_e32 v140, v140, v156
	v_add_f32_e32 v140, v140, v164
	v_mul_f32_e32 v140, v204, v140
	v_fmac_f32_e32 v140, s89, v96
	v_mov_b32_e32 v96, v140
	v_sub_f32_e32 v97, v97, v238
	v_mul_f32_e32 v97, v97, v239
	v_fma_f32 v97, v97, v213, v221
	v_add_f32_e32 v141, v141, v149
	v_add_f32_e32 v141, v141, v157
	v_add_f32_e32 v141, v141, v165
	v_mul_f32_e32 v141, v205, v141
	v_fmac_f32_e32 v141, s89, v97
	v_mov_b32_e32 v97, v141
	v_sub_f32_e32 v98, v98, v238
	v_mul_f32_e32 v98, v98, v239
	v_fma_f32 v98, v98, v214, v222
	v_add_f32_e32 v142, v142, v150
	v_add_f32_e32 v142, v142, v158
	v_add_f32_e32 v142, v142, v166
	v_mul_f32_e32 v142, v206, v142
	v_fmac_f32_e32 v142, s89, v98
	v_mov_b32_e32 v98, v142
	v_sub_f32_e32 v99, v99, v238
	v_mul_f32_e32 v99, v99, v239
	v_fma_f32 v99, v99, v215, v223
	v_add_f32_e32 v143, v143, v151
	v_add_f32_e32 v143, v143, v159
	v_add_f32_e32 v143, v143, v167
	v_mul_f32_e32 v143, v207, v143
	v_fmac_f32_e32 v143, s89, v99
	v_mov_b32_e32 v99, v143
	global_store_dwordx4 v76, v[96:99], s[2:3] offset:2048
	v_sub_f32_e32 v100, v100, v238
	v_mul_f32_e32 v100, v100, v239
	v_fma_f32 v100, v100, v216, v224
	v_add_f32_e32 v144, v144, v152
	v_add_f32_e32 v144, v144, v160
	v_add_f32_e32 v144, v144, v168
	v_mul_f32_e32 v144, v208, v144
	v_fmac_f32_e32 v144, s89, v100
	v_mov_b32_e32 v100, v144
	v_sub_f32_e32 v101, v101, v238
	v_mul_f32_e32 v101, v101, v239
	v_fma_f32 v101, v101, v217, v225
	v_add_f32_e32 v145, v145, v153
	v_add_f32_e32 v145, v145, v161
	v_add_f32_e32 v145, v145, v169
	v_mul_f32_e32 v145, v209, v145
	v_fmac_f32_e32 v145, s89, v101
	v_mov_b32_e32 v101, v145
	v_sub_f32_e32 v102, v102, v238
	v_mul_f32_e32 v102, v102, v239
	v_fma_f32 v102, v102, v218, v226
	v_add_f32_e32 v146, v146, v154
	v_add_f32_e32 v146, v146, v162
	v_add_f32_e32 v146, v146, v170
	v_mul_f32_e32 v146, v210, v146
	v_fmac_f32_e32 v146, s89, v102
	v_mov_b32_e32 v102, v146
	v_sub_f32_e32 v103, v103, v238
	v_mul_f32_e32 v103, v103, v239
	v_fma_f32 v103, v103, v219, v227
	v_add_f32_e32 v147, v147, v155
	v_add_f32_e32 v147, v147, v163
	v_add_f32_e32 v147, v147, v171
	v_mul_f32_e32 v147, v211, v147
	v_fmac_f32_e32 v147, s89, v103
	v_mov_b32_e32 v103, v147
	global_store_dwordx4 v76, v[100:103], s[2:3] offset:3072
	global_load_dwordx4 v[140:143], v77, s[4:5] offset:0 nt
	global_load_dwordx4 v[144:147], v77, s[4:5] offset:1024 nt
	s_add_u32 s4, s4, 0x800000
	s_addc_u32 s5, s5, 0
	global_load_dwordx4 v[148:151], v77, s[4:5] offset:0 nt
	global_load_dwordx4 v[152:155], v77, s[4:5] offset:1024 nt
	s_add_u32 s4, s4, 0x800000
	s_addc_u32 s5, s5, 0
	global_load_dwordx4 v[156:159], v77, s[4:5] offset:0 nt
	global_load_dwordx4 v[160:163], v77, s[4:5] offset:1024 nt
	s_add_u32 s4, s4, 0x800000
	s_addc_u32 s5, s5, 0
	global_load_dwordx4 v[164:167], v77, s[4:5] offset:0 nt
	global_load_dwordx4 v[168:171], v77, s[4:5] offset:1024 nt
	s_sub_u32 s4, s4, 0x1800000
	s_subb_u32 s5, s5, 0
	s_add_u32 s22, s50, 0x42000
	s_addc_u32 s23, s51, 0
	global_load_dwordx4 v[204:207], v77, s[22:23] offset:0
	global_load_dwordx4 v[208:211], v77, s[22:23] offset:1024
	global_load_dwordx4 v[212:215], v77, s[64:65] offset:0
	global_load_dwordx4 v[216:219], v77, s[64:65] offset:1024
	global_load_dwordx4 v[220:223], v77, s[66:67] offset:0
	global_load_dwordx4 v[224:227], v77, s[66:67] offset:1024
	s_waitcnt vmcnt(0)
; DI void phase_ln(const Params& p, const float* gam, const float* bet, const float* modnext  , bool skip_ctx, bool final_out,
;                  const float* cgate  , const float* pg, const float* pb  ) {
;     ...
;                     if (cpart) {
;                         if (pg) v[q][i] = (v[q][i] - pmu) * prs * *(const f32x4*)(pg + col) + *(const f32x4*)(pb + col);
;                         const float* pt = (const float*)(p.ws + WS_PART) + ((size_t)b * 256 + r) * DM + col;
;                         const f32x4 ps = *(const f32x4*)pt + *(const f32x4*)(pt + (size_t)1024 * DM) + *(const f32x4*)(pt + (size_t)2048 * DM) + *(const f32x4*)(pt + (size_t)3072 * DM);
;                         v[q][i] = v[q][i] * ALPHA + *(const f32x4*)(cgate + col) * ps;
;                         *(f32x4*)(X + (size_t)row * DM + col) = v[q][i];
	v_sub_f32_e32 v104, v104, v238
	v_mul_f32_e32 v104, v104, v239
	v_fma_f32 v104, v104, v212, v220
	v_add_f32_e32 v140, v140, v148
	v_add_f32_e32 v140, v140, v156
	v_add_f32_e32 v140, v140, v164
	v_mul_f32_e32 v140, v204, v140
	v_fmac_f32_e32 v140, s89, v104
	v_mov_b32_e32 v104, v140
	v_sub_f32_e32 v105, v105, v238
	v_mul_f32_e32 v105, v105, v239
	v_fma_f32 v105, v105, v213, v221
	v_add_f32_e32 v141, v141, v149
	v_add_f32_e32 v141, v141, v157
	v_add_f32_e32 v141, v141, v165
	v_mul_f32_e32 v141, v205, v141
	v_fmac_f32_e32 v141, s89, v105
	v_mov_b32_e32 v105, v141
	v_sub_f32_e32 v106, v106, v238
	v_mul_f32_e32 v106, v106, v239
	v_fma_f32 v106, v106, v214, v222
	v_add_f32_e32 v142, v142, v150
	v_add_f32_e32 v142, v142, v158
	v_add_f32_e32 v142, v142, v166
	v_mul_f32_e32 v142, v206, v142
	v_fmac_f32_e32 v142, s89, v106
	v_mov_b32_e32 v106, v142
	v_sub_f32_e32 v107, v107, v238
	v_mul_f32_e32 v107, v107, v239
	v_fma_f32 v107, v107, v215, v223
	v_add_f32_e32 v143, v143, v151
	v_add_f32_e32 v143, v143, v159
	v_add_f32_e32 v143, v143, v167
	v_mul_f32_e32 v143, v207, v143
	v_fmac_f32_e32 v143, s89, v107
	v_mov_b32_e32 v107, v143
	global_store_dwordx4 v77, v[104:107], s[2:3] offset:0
	v_sub_f32_e32 v108, v108, v238
	v_mul_f32_e32 v108, v108, v239
	v_fma_f32 v108, v108, v216, v224
	v_add_f32_e32 v144, v144, v152
	v_add_f32_e32 v144, v144, v160
	v_add_f32_e32 v144, v144, v168
	v_mul_f32_e32 v144, v208, v144
	v_fmac_f32_e32 v144, s89, v108
	v_mov_b32_e32 v108, v144
	v_sub_f32_e32 v109, v109, v238
	v_mul_f32_e32 v109, v109, v239
	v_fma_f32 v109, v109, v217, v225
	v_add_f32_e32 v145, v145, v153
	v_add_f32_e32 v145, v145, v161
	v_add_f32_e32 v145, v145, v169
	v_mul_f32_e32 v145, v209, v145
	v_fmac_f32_e32 v145, s89, v109
	v_mov_b32_e32 v109, v145
	v_sub_f32_e32 v110, v110, v238
	v_mul_f32_e32 v110, v110, v239
	v_fma_f32 v110, v110, v218, v226
	v_add_f32_e32 v146, v146, v154
	v_add_f32_e32 v146, v146, v162
	v_add_f32_e32 v146, v146, v170
	v_mul_f32_e32 v146, v210, v146
	v_fmac_f32_e32 v146, s89, v110
	v_mov_b32_e32 v110, v146
	v_sub_f32_e32 v111, v111, v238
	v_mul_f32_e32 v111, v111, v239
	v_fma_f32 v111, v111, v219, v227
	v_add_f32_e32 v147, v147, v155
	v_add_f32_e32 v147, v147, v163
	v_add_f32_e32 v147, v147, v171
	v_mul_f32_e32 v147, v211, v147
	v_fmac_f32_e32 v147, s89, v111
	v_mov_b32_e32 v111, v147
	global_store_dwordx4 v77, v[108:111], s[2:3] offset:1024
	global_load_dwordx4 v[140:143], v77, s[4:5] offset:2048 nt
	global_load_dwordx4 v[144:147], v77, s[4:5] offset:3072 nt
	s_add_u32 s4, s4, 0x800000
	s_addc_u32 s5, s5, 0
	global_load_dwordx4 v[148:151], v77, s[4:5] offset:2048 nt
	global_load_dwordx4 v[152:155], v77, s[4:5] offset:3072 nt
	s_add_u32 s4, s4, 0x800000
	s_addc_u32 s5, s5, 0
	global_load_dwordx4 v[156:159], v77, s[4:5] offset:2048 nt
	global_load_dwordx4 v[160:163], v77, s[4:5] offset:3072 nt
	s_add_u32 s4, s4, 0x800000
	s_addc_u32 s5, s5, 0
	global_load_dwordx4 v[164:167], v77, s[4:5] offset:2048 nt
	global_load_dwordx4 v[168:171], v77, s[4:5] offset:3072 nt
	s_sub_u32 s4, s4, 0x1800000
	s_subb_u32 s5, s5, 0
	s_add_u32 s22, s50, 0x42000
	s_addc_u32 s23, s51, 0
	global_load_dwordx4 v[204:207], v77, s[22:23] offset:2048
	global_load_dwordx4 v[208:211], v77, s[22:23] offset:3072
	global_load_dwordx4 v[212:215], v77, s[64:65] offset:2048
	global_load_dwordx4 v[216:219], v77, s[64:65] offset:3072
	global_load_dwordx4 v[220:223], v77, s[66:67] offset:2048
	global_load_dwordx4 v[224:227], v77, s[66:67] offset:3072
	s_waitcnt vmcnt(0)
	v_sub_f32_e32 v112, v112, v238
	v_mul_f32_e32 v112, v112, v239
	v_fma_f32 v112, v112, v212, v220
	v_add_f32_e32 v140, v140, v148
	v_add_f32_e32 v140, v140, v156
	v_add_f32_e32 v140, v140, v164
	v_mul_f32_e32 v140, v204, v140
	v_fmac_f32_e32 v140, s89, v112
	v_mov_b32_e32 v112, v140
	v_sub_f32_e32 v113, v113, v238
	v_mul_f32_e32 v113, v113, v239
	v_fma_f32 v113, v113, v213, v221
	v_add_f32_e32 v141, v141, v149
	v_add_f32_e32 v141, v141, v157
	v_add_f32_e32 v141, v141, v165
	v_mul_f32_e32 v141, v205, v141
	v_fmac_f32_e32 v141, s89, v113
	v_mov_b32_e32 v113, v141
	v_sub_f32_e32 v114, v114, v238
	v_mul_f32_e32 v114, v114, v239
	v_fma_f32 v114, v114, v214, v222
	v_add_f32_e32 v142, v142, v150
	v_add_f32_e32 v142, v142, v158
	v_add_f32_e32 v142, v142, v166
	v_mul_f32_e32 v142, v206, v142
	v_fmac_f32_e32 v142, s89, v114
	v_mov_b32_e32 v114, v142
	v_sub_f32_e32 v115, v115, v238
	v_mul_f32_e32 v115, v115, v239
	v_fma_f32 v115, v115, v215, v223
	v_add_f32_e32 v143, v143, v151
	v_add_f32_e32 v143, v143, v159
	v_add_f32_e32 v143, v143, v167
	v_mul_f32_e32 v143, v207, v143
	v_fmac_f32_e32 v143, s89, v115
	v_mov_b32_e32 v115, v143
	global_store_dwordx4 v77, v[112:115], s[2:3] offset:2048
	v_sub_f32_e32 v116, v116, v238
	v_mul_f32_e32 v116, v116, v239
	v_fma_f32 v116, v116, v216, v224
	v_add_f32_e32 v144, v144, v152
	v_add_f32_e32 v144, v144, v160
	v_add_f32_e32 v144, v144, v168
	v_mul_f32_e32 v144, v208, v144
	v_fmac_f32_e32 v144, s89, v116
	v_mov_b32_e32 v116, v144
	v_sub_f32_e32 v117, v117, v238
	v_mul_f32_e32 v117, v117, v239
	v_fma_f32 v117, v117, v217, v225
	v_add_f32_e32 v145, v145, v153
	v_add_f32_e32 v145, v145, v161
	v_add_f32_e32 v145, v145, v169
	v_mul_f32_e32 v145, v209, v145
	v_fmac_f32_e32 v145, s89, v117
	v_mov_b32_e32 v117, v145
	v_sub_f32_e32 v118, v118, v238
	v_mul_f32_e32 v118, v118, v239
	v_fma_f32 v118, v118, v218, v226
	v_add_f32_e32 v146, v146, v154
	v_add_f32_e32 v146, v146, v162
	v_add_f32_e32 v146, v146, v170
	v_mul_f32_e32 v146, v210, v146
	v_fmac_f32_e32 v146, s89, v118
	v_mov_b32_e32 v118, v146
	v_sub_f32_e32 v119, v119, v238
	v_mul_f32_e32 v119, v119, v239
	v_fma_f32 v119, v119, v219, v227
	v_add_f32_e32 v147, v147, v155
	v_add_f32_e32 v147, v147, v163
	v_add_f32_e32 v147, v147, v171
	v_mul_f32_e32 v147, v211, v147
	v_fmac_f32_e32 v147, s89, v119
	v_mov_b32_e32 v119, v147
	global_store_dwordx4 v77, v[116:119], s[2:3] offset:3072
	s_branch .Ll0b_cpart_done

; #define G_STAGE(bufoff, gbase, voff) do { _Pragma("unroll") for (int _i = 0; _i < 2; ++_i) \
;         __builtin_amdgcn_global_load_lds((const unsigned*)((const char*)(gbase) + (voff)[_i]), (LAS unsigned*)(lds + (bufoff) + ldsw + _i * 8192), 16, 0, 0); } while (0)
; #define G_LDA(dst, b, h) do { _Pragma("unroll") for (int m = 0; m < 4; ++m) _Pragma("unroll") for (int k = 0; k < 2; ++k) dst[m][k] = *(const LAS bf16x8*)(lds + G_SA(b, h) + aoff + m * 2048 + k * 1024); } while (0)
; #define G_LDB(dst, b, h) do { _Pragma("unroll") for (int n = 0; n < 2; ++n) _Pragma("unroll") for (int k = 0; k < 2; ++k) dst[n][k] = *(const LAS bf16x8*)(lds + G_SB(b, h) + boff + n * 2048 + k * 1024); } while (0)
; #define G_MMA(ai, bj, At, Bt_) do { __builtin_amdgcn_s_setprio(1); _Pragma("unroll") for (int m = 0; m < 4; ++m) _Pragma("unroll") for (int n = 0; n < 2; ++n) _Pragma("unroll") for (int k = 0; k < 2; ++k) \
;         acc[ai][bj][m][n] = __builtin_amdgcn_mfma_f32_16x16x32_bf16(Bt_[n][k], At[m][k], acc[ai][bj][m][n], 0, 0, 0); __builtin_amdgcn_s_setprio(0); } while (0)
; #define G_WAIT_V(n) asm volatile("s_waitcnt vmcnt(" #n ")" ::: "memory")
; #define G_WAIT_L(n) asm volatile("s_waitcnt lgkmcnt(" #n ")" ::: "memory")
; #define G_BAR __builtin_amdgcn_s_barrier()
; #define G_SCHED __builtin_amdgcn_sched_barrier(0)
; template <class Epi, bool PERMROWS = false>
; DI void gemm_phase(LAS unsigned char* lds, const bf16_t* A, int lda, const bf16_t* Bt, int K, const Sched& S, const Epi& E) {
;     ...
;             G_LDB(B0, 0, 0); G_SCHED; G_LDA(At, 0, 0); G_STAGE(G_SA(1, 1), a1 + hstepA, voffA);
;             G_WAIT_L(8); G_BAR; G_WAIT_L(0); G_MMA(0, 0, At, B0); G_BAR; G_SCHED;
;             G_LDB(B1, 0, 1); G_STAGE(G_SB(0, 0), b2, voffB);
;             G_BAR; G_WAIT_L(0); G_MMA(0, 1, At, B1); G_BAR;
;             G_LDA(At, 0, 1); G_STAGE(G_SA(0, 0), a2, voffA);
;             G_BAR; G_WAIT_L(0); G_MMA(1, 0, At, B0); G_BAR; G_SCHED;
;             G_STAGE(G_SB(0, 1), b2 + hstepB, voffB);
;             G_WAIT_V(6); G_BAR; G_MMA(1, 1, At, B1); G_BAR;
.LBB0_2751:
	ds_read_b128 v[128:131], v180
	ds_read_b128 v[132:135], v180 offset:1024
	ds_read_b128 v[136:139], v180 offset:2048
	ds_read_b128 v[140:143], v180 offset:3072
	s_add_u32 s29, s4, 0xfff80080
	s_addc_u32 s60, s5, -1
	s_cmp_eq_u32 s28, 28
	s_cselect_b32 s63, s21, s60
	s_cselect_b32 s62, s42, s29
	s_cselect_b32 s61, s19, s73
	s_cselect_b32 s60, s43, s72
	v_lshl_add_u64 v[168:169], s[4:5], 0, v[150:151]
	s_add_i32 m0, s23, 0xc000
	ds_read_b128 v[156:159], v181
	ds_read_b128 v[160:163], v181 offset:1024
	ds_read_b128 v[164:167], v181 offset:2048
	ds_read_b128 v[184:187], v181 offset:3072
	ds_read_b128 v[188:191], v181 offset:4096
	ds_read_b128 v[192:195], v181 offset:5120
	ds_read_b128 v[196:199], v181 offset:6144
	ds_read_b128 v[204:207], v181 offset:7168
	global_load_lds_dwordx4 v[168:169], off
	v_lshl_add_u64 v[168:169], s[4:5], 0, v[148:149]
	s_add_i32 m0, s23, 0xe000
	s_nop 0
	global_load_lds_dwordx4 v[168:169], off
	s_waitcnt lgkmcnt(8)
	s_barrier
	s_waitcnt lgkmcnt(0)
	s_setprio 1
	s_waitcnt lgkmcnt(0)
	v_mfma_f32_16x16x32_bf16 v[124:127], v[128:131], v[156:159], v[124:127]
	v_mfma_f32_16x16x32_bf16 v[120:123], v[136:139], v[156:159], v[120:123]
	v_mfma_f32_16x16x32_bf16 v[108:111], v[128:131], v[164:167], v[108:111]
	v_mfma_f32_16x16x32_bf16 v[104:107], v[136:139], v[164:167], v[104:107]
	v_mfma_f32_16x16x32_bf16 v[92:95], v[128:131], v[188:191], v[92:95]
	v_mfma_f32_16x16x32_bf16 v[88:91], v[136:139], v[188:191], v[88:91]
	v_mfma_f32_16x16x32_bf16 v[76:79], v[128:131], v[196:199], v[76:79]
	v_mfma_f32_16x16x32_bf16 v[72:75], v[136:139], v[196:199], v[72:75]
	v_mfma_f32_16x16x32_bf16 v[124:127], v[132:135], v[160:163], v[124:127]
	v_mfma_f32_16x16x32_bf16 v[120:123], v[140:143], v[160:163], v[120:123]
	v_mfma_f32_16x16x32_bf16 v[108:111], v[132:135], v[184:187], v[108:111]
	v_mfma_f32_16x16x32_bf16 v[104:107], v[140:143], v[184:187], v[104:107]
	v_mfma_f32_16x16x32_bf16 v[92:95], v[132:135], v[192:195], v[92:95]
	v_mfma_f32_16x16x32_bf16 v[88:91], v[140:143], v[192:195], v[88:91]
	v_mfma_f32_16x16x32_bf16 v[76:79], v[132:135], v[204:207], v[76:79]
	v_mfma_f32_16x16x32_bf16 v[72:75], v[140:143], v[204:207], v[72:75]
	s_setprio 0
	s_barrier
	s_add_i32 s29, s70, s22
	v_lshl_add_u64 v[168:169], s[60:61], 0, v[144:145]
	s_mov_b32 m0, s29
	ds_read_b128 v[208:211], v182
	ds_read_b128 v[212:215], v182 offset:1024
	ds_read_b128 v[216:219], v182 offset:2048
	ds_read_b128 v[220:223], v182 offset:3072
	global_load_lds_dwordx4 v[168:169], off
	v_lshl_add_u64 v[200:201], s[60:61], 0, v[146:147]
	s_add_i32 m0, s29, 0x2000
	s_nop 0
	global_load_lds_dwordx4 v[200:201], off
	s_barrier
	s_waitcnt lgkmcnt(0)
	s_setprio 1
	s_waitcnt lgkmcnt(0)
	v_mfma_f32_16x16x32_bf16 v[116:119], v[208:211], v[156:159], v[116:119]
	v_mfma_f32_16x16x32_bf16 v[112:115], v[216:219], v[156:159], v[112:115]
	v_mfma_f32_16x16x32_bf16 v[100:103], v[208:211], v[164:167], v[100:103]
	v_mfma_f32_16x16x32_bf16 v[96:99], v[216:219], v[164:167], v[96:99]
	v_mfma_f32_16x16x32_bf16 v[84:87], v[208:211], v[188:191], v[84:87]
	v_mfma_f32_16x16x32_bf16 v[80:83], v[216:219], v[188:191], v[80:83]
	v_mfma_f32_16x16x32_bf16 v[68:71], v[208:211], v[196:199], v[68:71]
	v_mfma_f32_16x16x32_bf16 v[64:67], v[216:219], v[196:199], v[64:67]
	v_mfma_f32_16x16x32_bf16 v[116:119], v[212:215], v[160:163], v[116:119]
	v_mfma_f32_16x16x32_bf16 v[112:115], v[220:223], v[160:163], v[112:115]
	v_mfma_f32_16x16x32_bf16 v[100:103], v[212:215], v[184:187], v[100:103]
	v_mfma_f32_16x16x32_bf16 v[96:99], v[220:223], v[184:187], v[96:99]
	v_mfma_f32_16x16x32_bf16 v[84:87], v[212:215], v[192:195], v[84:87]
	v_mfma_f32_16x16x32_bf16 v[80:83], v[220:223], v[192:195], v[80:83]
	v_mfma_f32_16x16x32_bf16 v[68:71], v[212:215], v[204:207], v[68:71]
	v_mfma_f32_16x16x32_bf16 v[64:67], v[220:223], v[204:207], v[64:67]
	s_setprio 0
	s_mov_b32 m0, s23
	v_lshl_add_u64 v[224:225], s[62:63], 0, v[144:145]
	s_barrier
	ds_read_b128 v[156:159], v181 offset:16384
	ds_read_b128 v[160:163], v181 offset:17408
	ds_read_b128 v[164:167], v181 offset:18432
	ds_read_b128 v[184:187], v181 offset:19456
	ds_read_b128 v[188:191], v181 offset:20480
	ds_read_b128 v[192:195], v181 offset:21504
	ds_read_b128 v[196:199], v181 offset:22528
	ds_read_b128 v[204:207], v181 offset:23552
	global_load_lds_dwordx4 v[224:225], off
	v_lshl_add_u64 v[226:227], s[62:63], 0, v[146:147]
	s_mov_b32 m0, s27
	s_nop 0
	global_load_lds_dwordx4 v[226:227], off
	s_barrier
	s_waitcnt lgkmcnt(0)
	s_setprio 1
	s_waitcnt lgkmcnt(0)
	v_mfma_f32_16x16x32_bf16 v[60:63], v[128:131], v[156:159], v[60:63]
	v_mfma_f32_16x16x32_bf16 v[56:59], v[136:139], v[156:159], v[56:59]
	v_mfma_f32_16x16x32_bf16 v[44:47], v[128:131], v[164:167], v[44:47]
	v_mfma_f32_16x16x32_bf16 v[40:43], v[136:139], v[164:167], v[40:43]
	v_mfma_f32_16x16x32_bf16 v[28:31], v[128:131], v[188:191], v[28:31]
	v_mfma_f32_16x16x32_bf16 v[24:27], v[136:139], v[188:191], v[24:27]
	v_mfma_f32_16x16x32_bf16 v[12:15], v[128:131], v[196:199], v[12:15]
	v_mfma_f32_16x16x32_bf16 v[8:11], v[136:139], v[196:199], v[8:11]
	v_mfma_f32_16x16x32_bf16 v[60:63], v[132:135], v[160:163], v[60:63]
	v_mfma_f32_16x16x32_bf16 v[56:59], v[140:143], v[160:163], v[56:59]
	v_mfma_f32_16x16x32_bf16 v[44:47], v[132:135], v[184:187], v[44:47]
	v_mfma_f32_16x16x32_bf16 v[40:43], v[140:143], v[184:187], v[40:43]
	v_mfma_f32_16x16x32_bf16 v[28:31], v[132:135], v[192:195], v[28:31]
	v_mfma_f32_16x16x32_bf16 v[24:27], v[140:143], v[192:195], v[24:27]
	v_mfma_f32_16x16x32_bf16 v[12:15], v[132:135], v[204:207], v[12:15]
	v_mfma_f32_16x16x32_bf16 v[8:11], v[140:143], v[204:207], v[8:11]
	s_setprio 0
	s_barrier
; #define G_STAGE(bufoff, gbase, voff) do { _Pragma("unroll") for (int _i = 0; _i < 2; ++_i) \
;         __builtin_amdgcn_global_load_lds((const unsigned*)((const char*)(gbase) + (voff)[_i]), (LAS unsigned*)(lds + (bufoff) + ldsw + _i * 8192), 16, 0, 0); } while (0)
; #define G_LDA(dst, b, h) do { _Pragma("unroll") for (int m = 0; m < 4; ++m) _Pragma("unroll") for (int k = 0; k < 2; ++k) dst[m][k] = *(const LAS bf16x8*)(lds + G_SA(b, h) + aoff + m * 2048 + k * 1024); } while (0)
; #define G_LDB(dst, b, h) do { _Pragma("unroll") for (int n = 0; n < 2; ++n) _Pragma("unroll") for (int k = 0; k < 2; ++k) dst[n][k] = *(const LAS bf16x8*)(lds + G_SB(b, h) + boff + n * 2048 + k * 1024); } while (0)
; #define G_MMA(ai, bj, At, Bt_) do { __builtin_amdgcn_s_setprio(1); _Pragma("unroll") for (int m = 0; m < 4; ++m) _Pragma("unroll") for (int n = 0; n < 2; ++n) _Pragma("unroll") for (int k = 0; k < 2; ++k) \
;         acc[ai][bj][m][n] = __builtin_amdgcn_mfma_f32_16x16x32_bf16(Bt_[n][k], At[m][k], acc[ai][bj][m][n], 0, 0, 0); __builtin_amdgcn_s_setprio(0); } while (0)
; #define G_WAIT_V(n) asm volatile("s_waitcnt vmcnt(" #n ")" ::: "memory")
; #define G_WAIT_L(n) asm volatile("s_waitcnt lgkmcnt(" #n ")" ::: "memory")
; #define G_BAR __builtin_amdgcn_s_barrier()
; #define G_SCHED __builtin_amdgcn_sched_barrier(0)
; template <class Epi, bool PERMROWS = false>
; DI void gemm_phase(LAS unsigned char* lds, const bf16_t* A, int lda, const bf16_t* Bt, int K, const Sched& S, const Epi& E) {
;     ...
;             G_WAIT_V(6); G_BAR; G_MMA(1, 1, At, B1); G_BAR;
;             G_LDB(B0, 1, 0); G_SCHED; G_LDA(At, 1, 0); G_STAGE(G_SA(0, 1), a2 + hstepA, voffA);
;             G_WAIT_L(8); G_BAR; G_WAIT_L(0); G_MMA(0, 0, At, B0); G_BAR; G_SCHED;
;             G_LDB(B1, 1, 1); G_STAGE(G_SB(1, 0), b3, voffB);
;             G_BAR; G_WAIT_L(0); G_MMA(0, 1, At, B1); G_BAR;
;             G_LDA(At, 1, 1); G_STAGE(G_SA(1, 0), a3, voffA);
;             G_BAR; G_WAIT_L(0); G_MMA(1, 0, At, B0); G_BAR; G_SCHED;
	s_add_u32 s74, s60, 0x80000
	s_addc_u32 s75, s61, 0
	s_add_i32 s29, s71, s22
	v_lshl_add_u64 v[128:129], s[74:75], 0, v[144:145]
	s_mov_b32 m0, s29
	s_nop 0
	global_load_lds_dwordx4 v[128:129], off
	v_lshl_add_u64 v[128:129], s[74:75], 0, v[146:147]
	s_add_i32 m0, s29, 0x2000
	s_nop 0
	global_load_lds_dwordx4 v[128:129], off
	s_waitcnt vmcnt(6)
	s_barrier
	s_setprio 1
	v_mfma_f32_16x16x32_bf16 v[52:55], v[208:211], v[156:159], v[52:55]
	v_mfma_f32_16x16x32_bf16 v[48:51], v[216:219], v[156:159], v[48:51]
	v_mfma_f32_16x16x32_bf16 v[36:39], v[208:211], v[164:167], v[36:39]
	v_mfma_f32_16x16x32_bf16 v[32:35], v[216:219], v[164:167], v[32:35]
	v_mfma_f32_16x16x32_bf16 v[20:23], v[208:211], v[188:191], v[20:23]
	v_mfma_f32_16x16x32_bf16 v[16:19], v[216:219], v[188:191], v[16:19]
	v_mfma_f32_16x16x32_bf16 v[4:7], v[208:211], v[196:199], v[4:7]
	v_mfma_f32_16x16x32_bf16 v[0:3], v[216:219], v[196:199], v[0:3]
	v_mfma_f32_16x16x32_bf16 v[52:55], v[212:215], v[160:163], v[52:55]
	v_mfma_f32_16x16x32_bf16 v[48:51], v[220:223], v[160:163], v[48:51]
	v_mfma_f32_16x16x32_bf16 v[36:39], v[212:215], v[184:187], v[36:39]
	v_mfma_f32_16x16x32_bf16 v[32:35], v[220:223], v[184:187], v[32:35]
	v_mfma_f32_16x16x32_bf16 v[20:23], v[212:215], v[192:195], v[20:23]
	v_mfma_f32_16x16x32_bf16 v[16:19], v[220:223], v[192:195], v[16:19]
	v_mfma_f32_16x16x32_bf16 v[4:7], v[212:215], v[204:207], v[4:7]
	v_mfma_f32_16x16x32_bf16 v[0:3], v[220:223], v[204:207], v[0:3]
	s_setprio 0
	s_add_i32 s29, 0, 0x18000
	v_add_u32_e32 v140, s29, v171
	s_barrier
	ds_read_b128 v[128:131], v140
	ds_read_b128 v[132:135], v140 offset:1024
	ds_read_b128 v[136:139], v140 offset:2048
	ds_read_b128 v[140:143], v140 offset:3072
	s_add_u32 s62, s62, 0x80000
	s_addc_u32 s63, s63, 0
	s_mov_b32 m0, s30
	v_lshl_add_u64 v[208:209], s[62:63], 0, v[144:145]
	ds_read_b128 v[156:159], v181 offset:32768
	ds_read_b128 v[160:163], v181 offset:33792
	ds_read_b128 v[164:167], v181 offset:34816
	ds_read_b128 v[184:187], v181 offset:35840
	ds_read_b128 v[188:191], v181 offset:36864
	ds_read_b128 v[192:195], v181 offset:37888
	ds_read_b128 v[196:199], v181 offset:38912
	ds_read_b128 v[204:207], v181 offset:39936
	global_load_lds_dwordx4 v[208:209], off
	v_lshl_add_u64 v[208:209], s[62:63], 0, v[146:147]
	s_mov_b32 m0, s31
	s_nop 0
	global_load_lds_dwordx4 v[208:209], off
	s_waitcnt lgkmcnt(8)
	s_barrier
	s_waitcnt lgkmcnt(0)
	s_setprio 1
	s_waitcnt lgkmcnt(0)
	v_mfma_f32_16x16x32_bf16 v[124:127], v[128:131], v[156:159], v[124:127]
	v_mfma_f32_16x16x32_bf16 v[120:123], v[136:139], v[156:159], v[120:123]
	v_mfma_f32_16x16x32_bf16 v[108:111], v[128:131], v[164:167], v[108:111]
	v_mfma_f32_16x16x32_bf16 v[104:107], v[136:139], v[164:167], v[104:107]
	v_mfma_f32_16x16x32_bf16 v[92:95], v[128:131], v[188:191], v[92:95]
	v_mfma_f32_16x16x32_bf16 v[88:91], v[136:139], v[188:191], v[88:91]
	v_mfma_f32_16x16x32_bf16 v[76:79], v[128:131], v[196:199], v[76:79]
	v_mfma_f32_16x16x32_bf16 v[72:75], v[136:139], v[196:199], v[72:75]
	v_mfma_f32_16x16x32_bf16 v[124:127], v[132:135], v[160:163], v[124:127]
	v_mfma_f32_16x16x32_bf16 v[120:123], v[140:143], v[160:163], v[120:123]
	v_mfma_f32_16x16x32_bf16 v[108:111], v[132:135], v[184:187], v[108:111]
	v_mfma_f32_16x16x32_bf16 v[104:107], v[140:143], v[184:187], v[104:107]
	v_mfma_f32_16x16x32_bf16 v[92:95], v[132:135], v[192:195], v[92:95]
	v_mfma_f32_16x16x32_bf16 v[88:91], v[140:143], v[192:195], v[88:91]
	v_mfma_f32_16x16x32_bf16 v[76:79], v[132:135], v[204:207], v[76:79]
	v_mfma_f32_16x16x32_bf16 v[72:75], v[140:143], v[204:207], v[72:75]
	s_setprio 0
	s_barrier
	s_add_i32 s62, 0, 0x1c000
	s_add_i32 s29, s29, s22
	v_add_u32_e32 v183, s62, v171
	v_lshl_add_u64 v[168:169], v[168:169], 0, s[0:1]
	s_mov_b32 m0, s29
	ds_read_b128 v[208:211], v183
	ds_read_b128 v[212:215], v183 offset:1024
	ds_read_b128 v[216:219], v183 offset:2048
	ds_read_b128 v[220:223], v183 offset:3072
	global_load_lds_dwordx4 v[168:169], off
	v_lshl_add_u64 v[168:169], v[200:201], 0, s[0:1]
	s_add_i32 m0, s29, 0x2000
	s_nop 0
	global_load_lds_dwordx4 v[168:169], off
	s_barrier
	s_waitcnt lgkmcnt(0)
	s_setprio 1
	s_waitcnt lgkmcnt(0)
	v_mfma_f32_16x16x32_bf16 v[116:119], v[208:211], v[156:159], v[116:119]
	v_mfma_f32_16x16x32_bf16 v[112:115], v[216:219], v[156:159], v[112:115]
	v_mfma_f32_16x16x32_bf16 v[100:103], v[208:211], v[164:167], v[100:103]
	v_mfma_f32_16x16x32_bf16 v[96:99], v[216:219], v[164:167], v[96:99]
	v_mfma_f32_16x16x32_bf16 v[84:87], v[208:211], v[188:191], v[84:87]
	v_mfma_f32_16x16x32_bf16 v[80:83], v[216:219], v[188:191], v[80:83]
	v_mfma_f32_16x16x32_bf16 v[68:71], v[208:211], v[196:199], v[68:71]
	v_mfma_f32_16x16x32_bf16 v[64:67], v[216:219], v[196:199], v[64:67]
	v_mfma_f32_16x16x32_bf16 v[116:119], v[212:215], v[160:163], v[116:119]
	v_mfma_f32_16x16x32_bf16 v[112:115], v[220:223], v[160:163], v[112:115]
	v_mfma_f32_16x16x32_bf16 v[100:103], v[212:215], v[184:187], v[100:103]
	v_mfma_f32_16x16x32_bf16 v[96:99], v[220:223], v[184:187], v[96:99]
	v_mfma_f32_16x16x32_bf16 v[84:87], v[212:215], v[192:195], v[84:87]
	v_mfma_f32_16x16x32_bf16 v[80:83], v[220:223], v[192:195], v[80:83]
	v_mfma_f32_16x16x32_bf16 v[68:71], v[212:215], v[204:207], v[68:71]
	v_mfma_f32_16x16x32_bf16 v[64:67], v[220:223], v[204:207], v[64:67]
	s_setprio 0
	s_mov_b32 m0, s68
	v_lshl_add_u64 v[168:169], v[224:225], 0, s[0:1]
	s_barrier
	ds_read_b128 v[156:159], v181 offset:49152
	ds_read_b128 v[160:163], v181 offset:50176
	ds_read_b128 v[164:167], v181 offset:51200
	ds_read_b128 v[184:187], v181 offset:52224
	ds_read_b128 v[188:191], v181 offset:53248
	ds_read_b128 v[192:195], v181 offset:54272
	ds_read_b128 v[196:199], v181 offset:55296
	ds_read_b128 v[204:207], v181 offset:56320
	global_load_lds_dwordx4 v[168:169], off
	v_lshl_add_u64 v[168:169], v[226:227], 0, s[0:1]
	s_mov_b32 m0, s69
	s_nop 0
	global_load_lds_dwordx4 v[168:169], off
	s_barrier
; #define G_STAGE(bufoff, gbase, voff) do { _Pragma("unroll") for (int _i = 0; _i < 2; ++_i) \
;         __builtin_amdgcn_global_load_lds((const unsigned*)((const char*)(gbase) + (voff)[_i]), (LAS unsigned*)(lds + (bufoff) + ldsw + _i * 8192), 16, 0, 0); } while (0)
; #define G_MMA(ai, bj, At, Bt_) do { __builtin_amdgcn_s_setprio(1); _Pragma("unroll") for (int m = 0; m < 4; ++m) _Pragma("unroll") for (int n = 0; n < 2; ++n) _Pragma("unroll") for (int k = 0; k < 2; ++k) \
;         acc[ai][bj][m][n] = __builtin_amdgcn_mfma_f32_16x16x32_bf16(Bt_[n][k], At[m][k], acc[ai][bj][m][n], 0, 0, 0); __builtin_amdgcn_s_setprio(0); } while (0)
; #define G_WAIT_V(n) asm volatile("s_waitcnt vmcnt(" #n ")" ::: "memory")
; #define G_WAIT_L(n) asm volatile("s_waitcnt lgkmcnt(" #n ")" ::: "memory")
; #define G_BAR __builtin_amdgcn_s_barrier()
; #define G_SCHED __builtin_amdgcn_sched_barrier(0)
; template <class Epi, bool PERMROWS = false>
; DI void gemm_phase(LAS unsigned char* lds, const bf16_t* A, int lda, const bf16_t* Bt, int K, const Sched& S, const Epi& E) {
;     ...
;             G_BAR; G_WAIT_L(0); G_MMA(1, 0, At, B0); G_BAR; G_SCHED;
;             G_STAGE(G_SB(1, 1), b3 + hstepB, voffB);
;             G_WAIT_V(6); G_BAR; G_MMA(1, 1, At, B1); G_BAR;
;     DI void operator()(const f32x4 (&acc)[2][2][4][2], const Unit& u, int wr, int wc, int fr, int fq) const {
;     ...
;         const float* g = gate + (size_t)s * 12288;
;         const float2* RS = (const float2*)(ws + WS_RSTAT);
; #pragma unroll
;         for (int ai = 0; ai < 2; ++ai)
; #pragma unroll
;             for (int m = 0; m < 4; ++m) {
;                 const int row = u.pm * BM + ai * HALF + wr * 64 + m * 16 + fr;
;                 float mu = 0.f, rs = 1.f;
;                 if (pg) { const float2 st = RS[row]; mu = st.x; rs = st.y; }
; #pragma unroll
;                 for (int bj = 0; bj < 2; ++bj)
; #pragma unroll
;                     for (int n = 0; n < 2; ++n) {
;                         const int col = u.pn * BM + bj * HALF + wc * 32 + n * 16 + 4 * fq;
;                         float* xp = X + (size_t)row * DM + col;
;                         f32x4 x4 = *(const f32x4*)xp; const f32x4 g4 = *(const f32x4*)(g + col);
	s_waitcnt lgkmcnt(0)
	s_setprio 1
	s_waitcnt lgkmcnt(0)
	v_mfma_f32_16x16x32_bf16 v[60:63], v[128:131], v[156:159], v[60:63]
	v_mfma_f32_16x16x32_bf16 v[56:59], v[136:139], v[156:159], v[56:59]
	v_mfma_f32_16x16x32_bf16 v[44:47], v[128:131], v[164:167], v[44:47]
	v_mfma_f32_16x16x32_bf16 v[40:43], v[136:139], v[164:167], v[40:43]
	v_mfma_f32_16x16x32_bf16 v[28:31], v[128:131], v[188:191], v[28:31]
	v_mfma_f32_16x16x32_bf16 v[24:27], v[136:139], v[188:191], v[24:27]
	v_mfma_f32_16x16x32_bf16 v[12:15], v[128:131], v[196:199], v[12:15]
	v_mfma_f32_16x16x32_bf16 v[8:11], v[136:139], v[196:199], v[8:11]
	v_mfma_f32_16x16x32_bf16 v[60:63], v[132:135], v[160:163], v[60:63]
	v_mfma_f32_16x16x32_bf16 v[56:59], v[140:143], v[160:163], v[56:59]
	v_mfma_f32_16x16x32_bf16 v[44:47], v[132:135], v[184:187], v[44:47]
	v_mfma_f32_16x16x32_bf16 v[40:43], v[140:143], v[184:187], v[40:43]
	v_mfma_f32_16x16x32_bf16 v[28:31], v[132:135], v[192:195], v[28:31]
	v_mfma_f32_16x16x32_bf16 v[24:27], v[140:143], v[192:195], v[24:27]
	v_mfma_f32_16x16x32_bf16 v[12:15], v[132:135], v[204:207], v[12:15]
	v_mfma_f32_16x16x32_bf16 v[8:11], v[140:143], v[204:207], v[8:11]
	s_setprio 0
	s_barrier
	s_add_u32 s60, s60, 0x80080
	s_addc_u32 s61, s61, 0
	s_add_i32 s29, s62, s22
	v_lshl_add_u64 v[128:129], s[60:61], 0, v[144:145]
	s_mov_b32 m0, s29
	s_nop 0
	global_load_lds_dwordx4 v[128:129], off
	v_lshl_add_u64 v[128:129], s[60:61], 0, v[146:147]
	s_add_i32 m0, s29, 0x2000
	s_nop 0
	global_load_lds_dwordx4 v[128:129], off
	s_waitcnt vmcnt(6)
	s_barrier
	s_setprio 1
	v_mfma_f32_16x16x32_bf16 v[52:55], v[208:211], v[156:159], v[52:55]
	v_mfma_f32_16x16x32_bf16 v[48:51], v[216:219], v[156:159], v[48:51]
	v_mfma_f32_16x16x32_bf16 v[36:39], v[208:211], v[164:167], v[36:39]
	v_mfma_f32_16x16x32_bf16 v[32:35], v[216:219], v[164:167], v[32:35]
	v_mfma_f32_16x16x32_bf16 v[20:23], v[208:211], v[188:191], v[20:23]
	v_mfma_f32_16x16x32_bf16 v[16:19], v[216:219], v[188:191], v[16:19]
	v_mfma_f32_16x16x32_bf16 v[4:7], v[208:211], v[196:199], v[4:7]
	v_mfma_f32_16x16x32_bf16 v[0:3], v[216:219], v[196:199], v[0:3]
	v_mfma_f32_16x16x32_bf16 v[52:55], v[212:215], v[160:163], v[52:55]
	v_mfma_f32_16x16x32_bf16 v[48:51], v[220:223], v[160:163], v[48:51]
	v_mfma_f32_16x16x32_bf16 v[36:39], v[212:215], v[184:187], v[36:39]
	v_mfma_f32_16x16x32_bf16 v[32:35], v[220:223], v[184:187], v[32:35]
	v_mfma_f32_16x16x32_bf16 v[20:23], v[212:215], v[192:195], v[20:23]
	v_mfma_f32_16x16x32_bf16 v[16:19], v[220:223], v[192:195], v[16:19]
	v_mfma_f32_16x16x32_bf16 v[4:7], v[212:215], v[204:207], v[4:7]
	v_mfma_f32_16x16x32_bf16 v[0:3], v[220:223], v[204:207], v[0:3]
	s_setprio 0
	s_add_i32 s28, s28, 2
	s_add_u32 s72, s72, 0x100
	s_addc_u32 s73, s73, 0
	s_add_u32 s4, s4, 0x100
	s_addc_u32 s5, s5, 0
	s_cmp_gt_u32 s28, 29
	s_barrier
	s_cbranch_scc0 .LBB0_2751
	v_and_b32_e32 v166, 15, v202
	v_bfe_u32 v167, v202, 8, 1
	v_lshl_add_u32 v166, v167, 6, v166
	v_lshlrev_b32_e32 v183, 3, v166
	v_bfe_u32 v167, v202, 6, 2
	v_lshlrev_b32_e32 v136, 7, v167
	v_bfe_u32 v167, v202, 4, 2
	v_lshl_add_u32 v136, v167, 4, v136
	s_lshl_b32 s29, s56, 10
	v_add_u32_e32 v136, s29, v136
	v_lshl_add_u32 v158, v166, 13, v136
	v_add_u32_e32 v159, 0x20000, v158
	v_add_u32_e32 v160, 0x40000, v158
	v_add_u32_e32 v161, 0x60000, v158
	v_add_u32_e32 v162, 0x100000, v158
	v_add_u32_e32 v163, 0x120000, v158
	v_add_u32_e32 v164, 0x140000, v158
	v_add_u32_e32 v165, 0x160000, v158
	s_mov_b32 s89, 0x3fb504f3
	s_mul_i32 s29, s58, 57
	s_lshr_b32 s29, s29, 9
	s_mul_i32 s32, s29, 9
	s_cmp_lg_u32 s32, s58
	s_cselect_b32 s43, s29, 4
	s_mul_i32 s43, s43, 0xc000
	s_add_u32 s74, s50, 0x48000
	s_addc_u32 s75, s51, 0
	s_add_u32 s74, s74, s43
	s_addc_u32 s75, s75, 0
	global_load_dwordx4 v[220:223], v136, s[74:75] offset:0
	global_load_dwordx4 v[224:227], v136, s[74:75] offset:64
	global_load_dwordx4 v[228:231], v136, s[74:75] offset:512
	global_load_dwordx4 v[232:235], v136, s[74:75] offset:576
	s_add_u32 s74, s44, 0x0
	s_addc_u32 s75, s45, 0
	global_load_dwordx4 v[204:207], v136, s[74:75] offset:0
	global_load_dwordx4 v[208:211], v136, s[74:75] offset:64
	global_load_dwordx4 v[212:215], v136, s[74:75] offset:512
	global_load_dwordx4 v[216:219], v136, s[74:75] offset:576
	s_add_u32 s74, s46, 0x0
	s_addc_u32 s75, s47, 0
	global_load_dwordx4 v[236:239], v136, s[74:75] offset:0
	global_load_dwordx4 v[240:243], v136, s[74:75] offset:64
	global_load_dwordx4 v[244:247], v136, s[74:75] offset:512
	global_load_dwordx4 v[248:251], v136, s[74:75] offset:576
	s_lshl_b32 s29, s58, 11
	s_add_u32 s74, s50, 0x260a0000
	s_addc_u32 s75, s51, 0
	s_add_u32 s74, s74, s29
	s_addc_u32 s75, s75, 0
	global_load_dwordx2 v[128:129], v183, s[74:75] offset:0
	global_load_dwordx2 v[130:131], v183, s[74:75] offset:128
	global_load_dwordx2 v[132:133], v183, s[74:75] offset:256
	global_load_dwordx2 v[134:135], v183, s[74:75] offset:384
	global_load_dwordx2 v[138:139], v183, s[74:75] offset:1024
	global_load_dwordx2 v[140:141], v183, s[74:75] offset:1152
	global_load_dwordx2 v[142:143], v183, s[74:75] offset:1280
	global_load_dwordx2 v[156:157], v183, s[74:75] offset:1408
	s_lshl_b32 s29, s58, 21
	s_add_u32 s72, s50, 0xcba0000
	s_addc_u32 s73, s51, 0
	s_add_u32 s72, s72, s29
	s_addc_u32 s73, s73, 0
	s_waitcnt vmcnt(0)
;     DI void operator()(const f32x4 (&acc)[2][2][4][2], const Unit& u, int wr, int wc, int fr, int fq) const {
;     ...
;                 const int row = u.pm * BM + ai * HALF + wr * 64 + m * 16 + fr;
;                 float mu = 0.f, rs = 1.f;
;                 if (pg) { const float2 st = RS[row]; mu = st.x; rs = st.y; }
; #pragma unroll
;                 for (int bj = 0; bj < 2; ++bj)
; #pragma unroll
;                     for (int n = 0; n < 2; ++n) {
;                         const int col = u.pn * BM + bj * HALF + wc * 32 + n * 16 + 4 * fq;
;                         float* xp = X + (size_t)row * DM + col;
;                         f32x4 x4 = *(const f32x4*)xp; const f32x4 g4 = *(const f32x4*)(g + col);
;                         if (pg) x4 = (x4 - mu) * rs * *(const f32x4*)(pg + col) + *(const f32x4*)(pb + col);
;                         *(f32x4*)xp = x4 * ALPHA + g4 * acc[ai][bj][m][n];
	v_mul_f32_e32 v204, s89, v204
	v_mul_f32_e32 v236, s89, v236
	v_mul_f32_e32 v205, s89, v205
	v_mul_f32_e32 v237, s89, v237
	v_mul_f32_e32 v206, s89, v206
	v_mul_f32_e32 v238, s89, v238
	v_mul_f32_e32 v207, s89, v207
	v_mul_f32_e32 v239, s89, v239
	v_mul_f32_e32 v208, s89, v208
	v_mul_f32_e32 v240, s89, v240
	v_mul_f32_e32 v209, s89, v209
	v_mul_f32_e32 v241, s89, v241
	v_mul_f32_e32 v210, s89, v210
	v_mul_f32_e32 v242, s89, v242
	v_mul_f32_e32 v211, s89, v211
	v_mul_f32_e32 v243, s89, v243
	v_mul_f32_e32 v212, s89, v212
	v_mul_f32_e32 v244, s89, v244
	v_mul_f32_e32 v213, s89, v213
	v_mul_f32_e32 v245, s89, v245
	v_mul_f32_e32 v214, s89, v214
	v_mul_f32_e32 v246, s89, v246
	v_mul_f32_e32 v215, s89, v215
	v_mul_f32_e32 v247, s89, v247
	v_mul_f32_e32 v216, s89, v216
	v_mul_f32_e32 v248, s89, v248
	v_mul_f32_e32 v217, s89, v217
	v_mul_f32_e32 v249, s89, v249
	v_mul_f32_e32 v218, s89, v218
	v_mul_f32_e32 v250, s89, v250
	v_mul_f32_e32 v219, s89, v219
	v_mul_f32_e32 v251, s89, v251
	v_fma_f32 v124, v220, v124, v236
	v_fma_f32 v125, v221, v125, v237
	v_fma_f32 v126, v222, v126, v238
	v_fma_f32 v127, v223, v127, v239
	v_fma_f32 v120, v224, v120, v240
	v_fma_f32 v121, v225, v121, v241
	v_fma_f32 v122, v226, v122, v242
	v_fma_f32 v123, v227, v123, v243
	v_fma_f32 v116, v228, v116, v244
	v_fma_f32 v117, v229, v117, v245
	v_fma_f32 v118, v230, v118, v246
	v_fma_f32 v119, v231, v119, v247
	v_fma_f32 v112, v232, v112, v248
	v_fma_f32 v113, v233, v113, v249
	v_fma_f32 v114, v234, v114, v250
	v_fma_f32 v115, v235, v115, v251
	v_fma_f32 v108, v220, v108, v236
	v_fma_f32 v109, v221, v109, v237
	v_fma_f32 v110, v222, v110, v238
	v_fma_f32 v111, v223, v111, v239
	v_fma_f32 v104, v224, v104, v240
	v_fma_f32 v105, v225, v105, v241
	v_fma_f32 v106, v226, v106, v242
	v_fma_f32 v107, v227, v107, v243
	v_fma_f32 v100, v228, v100, v244
	v_fma_f32 v101, v229, v101, v245
	v_fma_f32 v102, v230, v102, v246
	v_fma_f32 v103, v231, v103, v247
	v_fma_f32 v96, v232, v96, v248
	v_fma_f32 v97, v233, v97, v249
	v_fma_f32 v98, v234, v98, v250
	v_fma_f32 v99, v235, v99, v251
	v_fma_f32 v92, v220, v92, v236
	v_fma_f32 v93, v221, v93, v237
	v_fma_f32 v94, v222, v94, v238
	v_fma_f32 v95, v223, v95, v239
	v_fma_f32 v88, v224, v88, v240
	v_fma_f32 v89, v225, v89, v241
	v_fma_f32 v90, v226, v90, v242
	v_fma_f32 v91, v227, v91, v243
	v_fma_f32 v84, v228, v84, v244
	v_fma_f32 v85, v229, v85, v245
	v_fma_f32 v86, v230, v86, v246
	v_fma_f32 v87, v231, v87, v247
	v_fma_f32 v80, v232, v80, v248
	v_fma_f32 v81, v233, v81, v249
	v_fma_f32 v82, v234, v82, v250
	v_fma_f32 v83, v235, v83, v251
	v_fma_f32 v76, v220, v76, v236
	v_fma_f32 v77, v221, v77, v237
	v_fma_f32 v78, v222, v78, v238
	v_fma_f32 v79, v223, v79, v239
	v_fma_f32 v72, v224, v72, v240
	v_fma_f32 v73, v225, v73, v241
	v_fma_f32 v74, v226, v74, v242
	v_fma_f32 v75, v227, v75, v243
	v_fma_f32 v68, v228, v68, v244
	v_fma_f32 v69, v229, v69, v245
	v_fma_f32 v70, v230, v70, v246
	v_fma_f32 v71, v231, v71, v247
	v_fma_f32 v64, v232, v64, v248
	v_fma_f32 v65, v233, v65, v249
	v_fma_f32 v66, v234, v66, v250
	v_fma_f32 v67, v235, v67, v251
	v_fma_f32 v60, v220, v60, v236
	v_fma_f32 v61, v221, v61, v237
	v_fma_f32 v62, v222, v62, v238
	v_fma_f32 v63, v223, v63, v239
	v_fma_f32 v56, v224, v56, v240
	v_fma_f32 v57, v225, v57, v241
	v_fma_f32 v58, v226, v58, v242
	v_fma_f32 v59, v227, v59, v243
	v_fma_f32 v52, v228, v52, v244
	v_fma_f32 v53, v229, v53, v245
	v_fma_f32 v54, v230, v54, v246
	v_fma_f32 v55, v231, v55, v247
	v_fma_f32 v48, v232, v48, v248
	v_fma_f32 v49, v233, v49, v249
	v_fma_f32 v50, v234, v50, v250
	v_fma_f32 v51, v235, v51, v251
	v_fma_f32 v44, v220, v44, v236
	v_fma_f32 v45, v221, v45, v237
	v_fma_f32 v46, v222, v46, v238
	v_fma_f32 v47, v223, v47, v239
	v_fma_f32 v40, v224, v40, v240
	v_fma_f32 v41, v225, v41, v241
	v_fma_f32 v42, v226, v42, v242
	v_fma_f32 v43, v227, v43, v243
	v_fma_f32 v36, v228, v36, v244
	v_fma_f32 v37, v229, v37, v245
	v_fma_f32 v38, v230, v38, v246
	v_fma_f32 v39, v231, v39, v247
	v_fma_f32 v32, v232, v32, v248
	v_fma_f32 v33, v233, v33, v249
	v_fma_f32 v34, v234, v34, v250
	v_fma_f32 v35, v235, v35, v251
	v_fma_f32 v28, v220, v28, v236
	v_fma_f32 v29, v221, v29, v237
	v_fma_f32 v30, v222, v30, v238
	v_fma_f32 v31, v223, v31, v239
	v_fma_f32 v24, v224, v24, v240
	v_fma_f32 v25, v225, v25, v241
	v_fma_f32 v26, v226, v26, v242
	v_fma_f32 v27, v227, v27, v243
	v_fma_f32 v20, v228, v20, v244
	v_fma_f32 v21, v229, v21, v245
	v_fma_f32 v22, v230, v22, v246
	v_fma_f32 v23, v231, v23, v247
	v_fma_f32 v16, v232, v16, v248
	v_fma_f32 v17, v233, v17, v249
	v_fma_f32 v18, v234, v18, v250
	v_fma_f32 v19, v235, v19, v251
	v_fma_f32 v12, v220, v12, v236
	v_fma_f32 v13, v221, v13, v237
	v_fma_f32 v14, v222, v14, v238
	v_fma_f32 v15, v223, v15, v239
	v_fma_f32 v8, v224, v8, v240
	v_fma_f32 v9, v225, v9, v241
	v_fma_f32 v10, v226, v10, v242
	v_fma_f32 v11, v227, v11, v243
	v_fma_f32 v4, v228, v4, v244
	v_fma_f32 v5, v229, v5, v245
	v_fma_f32 v6, v230, v6, v246
	v_fma_f32 v7, v231, v7, v247
	v_fma_f32 v0, v232, v0, v248
	v_fma_f32 v1, v233, v1, v249
	v_fma_f32 v2, v234, v2, v250
	v_fma_f32 v3, v235, v3, v251
	global_load_dwordx4 v[220:223], v158, s[72:73] offset:0 nt
	global_load_dwordx4 v[224:227], v158, s[72:73] offset:64 nt
	global_load_dwordx4 v[228:231], v158, s[72:73] offset:512 nt
	global_load_dwordx4 v[232:235], v158, s[72:73] offset:576 nt
	global_load_dwordx4 v[236:239], v159, s[72:73] offset:0 nt
	global_load_dwordx4 v[240:243], v159, s[72:73] offset:64 nt
	global_load_dwordx4 v[244:247], v159, s[72:73] offset:512 nt
	global_load_dwordx4 v[248:251], v159, s[72:73] offset:576 nt
	s_waitcnt vmcnt(0)
;     DI void operator()(const f32x4 (&acc)[2][2][4][2], const Unit& u, int wr, int wc, int fr, int fq) const {
;     ...
;                     for (int n = 0; n < 2; ++n) {
;                         const int col = u.pn * BM + bj * HALF + wc * 32 + n * 16 + 4 * fq;
;                         float* xp = X + (size_t)row * DM + col;
;                         f32x4 x4 = *(const f32x4*)xp; const f32x4 g4 = *(const f32x4*)(g + col);
;                         if (pg) x4 = (x4 - mu) * rs * *(const f32x4*)(pg + col) + *(const f32x4*)(pb + col);
;                         *(f32x4*)xp = x4 * ALPHA + g4 * acc[ai][bj][m][n];
	v_sub_f32_e32 v220, v220, v128
	v_mul_f32_e32 v220, v220, v129
	v_fma_f32 v220, v220, v204, v124
	v_sub_f32_e32 v221, v221, v128
	v_mul_f32_e32 v221, v221, v129
	v_fma_f32 v221, v221, v205, v125
	v_sub_f32_e32 v222, v222, v128
	v_mul_f32_e32 v222, v222, v129
	v_fma_f32 v222, v222, v206, v126
	v_sub_f32_e32 v223, v223, v128
	v_mul_f32_e32 v223, v223, v129
	v_fma_f32 v223, v223, v207, v127
	v_sub_f32_e32 v224, v224, v128
	v_mul_f32_e32 v224, v224, v129
	v_fma_f32 v224, v224, v208, v120
	v_sub_f32_e32 v225, v225, v128
	v_mul_f32_e32 v225, v225, v129
	v_fma_f32 v225, v225, v209, v121
	v_sub_f32_e32 v226, v226, v128
	v_mul_f32_e32 v226, v226, v129
	v_fma_f32 v226, v226, v210, v122
	v_sub_f32_e32 v227, v227, v128
	v_mul_f32_e32 v227, v227, v129
	v_fma_f32 v227, v227, v211, v123
	v_sub_f32_e32 v228, v228, v128
	v_mul_f32_e32 v228, v228, v129
	v_fma_f32 v228, v228, v212, v116
	v_sub_f32_e32 v229, v229, v128
	v_mul_f32_e32 v229, v229, v129
	v_fma_f32 v229, v229, v213, v117
	v_sub_f32_e32 v230, v230, v128
	v_mul_f32_e32 v230, v230, v129
	v_fma_f32 v230, v230, v214, v118
	v_sub_f32_e32 v231, v231, v128
	v_mul_f32_e32 v231, v231, v129
	v_fma_f32 v231, v231, v215, v119
	v_sub_f32_e32 v232, v232, v128
	v_mul_f32_e32 v232, v232, v129
	v_fma_f32 v232, v232, v216, v112
	v_sub_f32_e32 v233, v233, v128
	v_mul_f32_e32 v233, v233, v129
	v_fma_f32 v233, v233, v217, v113
	v_sub_f32_e32 v234, v234, v128
	v_mul_f32_e32 v234, v234, v129
	v_fma_f32 v234, v234, v218, v114
	v_sub_f32_e32 v235, v235, v128
	v_mul_f32_e32 v235, v235, v129
	v_fma_f32 v235, v235, v219, v115
	v_sub_f32_e32 v236, v236, v130
	v_mul_f32_e32 v236, v236, v131
	v_fma_f32 v236, v236, v204, v108
	v_sub_f32_e32 v237, v237, v130
	v_mul_f32_e32 v237, v237, v131
	v_fma_f32 v237, v237, v205, v109
	v_sub_f32_e32 v238, v238, v130
	v_mul_f32_e32 v238, v238, v131
	v_fma_f32 v238, v238, v206, v110
	v_sub_f32_e32 v239, v239, v130
	v_mul_f32_e32 v239, v239, v131
	v_fma_f32 v239, v239, v207, v111
	v_sub_f32_e32 v240, v240, v130
	v_mul_f32_e32 v240, v240, v131
	v_fma_f32 v240, v240, v208, v104
	v_sub_f32_e32 v241, v241, v130
	v_mul_f32_e32 v241, v241, v131
	v_fma_f32 v241, v241, v209, v105
	v_sub_f32_e32 v242, v242, v130
	v_mul_f32_e32 v242, v242, v131
	v_fma_f32 v242, v242, v210, v106
	v_sub_f32_e32 v243, v243, v130
	v_mul_f32_e32 v243, v243, v131
	v_fma_f32 v243, v243, v211, v107
	v_sub_f32_e32 v244, v244, v130
	v_mul_f32_e32 v244, v244, v131
	v_fma_f32 v244, v244, v212, v100
	v_sub_f32_e32 v245, v245, v130
	v_mul_f32_e32 v245, v245, v131
	v_fma_f32 v245, v245, v213, v101
	v_sub_f32_e32 v246, v246, v130
	v_mul_f32_e32 v246, v246, v131
	v_fma_f32 v246, v246, v214, v102
	v_sub_f32_e32 v247, v247, v130
	v_mul_f32_e32 v247, v247, v131
	v_fma_f32 v247, v247, v215, v103
	v_sub_f32_e32 v248, v248, v130
	v_mul_f32_e32 v248, v248, v131
	v_fma_f32 v248, v248, v216, v96
	v_sub_f32_e32 v249, v249, v130
	v_mul_f32_e32 v249, v249, v131
	v_fma_f32 v249, v249, v217, v97
	v_sub_f32_e32 v250, v250, v130
	v_mul_f32_e32 v250, v250, v131
	v_fma_f32 v250, v250, v218, v98
	v_sub_f32_e32 v251, v251, v130
	v_mul_f32_e32 v251, v251, v131
	v_fma_f32 v251, v251, v219, v99
	global_load_dwordx4 v[124:127], v160, s[72:73] offset:0 nt
	global_load_dwordx4 v[120:123], v160, s[72:73] offset:64 nt
	global_load_dwordx4 v[116:119], v160, s[72:73] offset:512 nt
	global_load_dwordx4 v[112:115], v160, s[72:73] offset:576 nt
	global_load_dwordx4 v[108:111], v161, s[72:73] offset:0 nt
	global_load_dwordx4 v[104:107], v161, s[72:73] offset:64 nt
	global_load_dwordx4 v[100:103], v161, s[72:73] offset:512 nt
	global_load_dwordx4 v[96:99], v161, s[72:73] offset:576 nt
	global_store_dwordx4 v158, v[220:223], s[72:73] offset:0
	global_store_dwordx4 v158, v[224:227], s[72:73] offset:64
	global_store_dwordx4 v158, v[228:231], s[72:73] offset:512
	global_store_dwordx4 v158, v[232:235], s[72:73] offset:576
	global_store_dwordx4 v159, v[236:239], s[72:73] offset:0
	global_store_dwordx4 v159, v[240:243], s[72:73] offset:64
	global_store_dwordx4 v159, v[244:247], s[72:73] offset:512
	global_store_dwordx4 v159, v[248:251], s[72:73] offset:576
	global_load_dwordx4 v[220:223], v162, s[72:73] offset:0 nt
	global_load_dwordx4 v[224:227], v162, s[72:73] offset:64 nt
	global_load_dwordx4 v[228:231], v162, s[72:73] offset:512 nt
	global_load_dwordx4 v[232:235], v162, s[72:73] offset:576 nt
	global_load_dwordx4 v[236:239], v163, s[72:73] offset:0 nt
	global_load_dwordx4 v[240:243], v163, s[72:73] offset:64 nt
	global_load_dwordx4 v[244:247], v163, s[72:73] offset:512 nt
	global_load_dwordx4 v[248:251], v163, s[72:73] offset:576 nt
	s_waitcnt vmcnt(0)
;     DI void operator()(const f32x4 (&acc)[2][2][4][2], const Unit& u, int wr, int wc, int fr, int fq) const {
;     ...
;                     for (int n = 0; n < 2; ++n) {
;                         const int col = u.pn * BM + bj * HALF + wc * 32 + n * 16 + 4 * fq;
;                         float* xp = X + (size_t)row * DM + col;
;                         f32x4 x4 = *(const f32x4*)xp; const f32x4 g4 = *(const f32x4*)(g + col);
;                         if (pg) x4 = (x4 - mu) * rs * *(const f32x4*)(pg + col) + *(const f32x4*)(pb + col);
;                         *(f32x4*)xp = x4 * ALPHA + g4 * acc[ai][bj][m][n];
	v_sub_f32_e32 v124, v124, v132
	v_mul_f32_e32 v124, v124, v133
	v_fma_f32 v124, v124, v204, v92
	v_sub_f32_e32 v125, v125, v132
	v_mul_f32_e32 v125, v125, v133
	v_fma_f32 v125, v125, v205, v93
	v_sub_f32_e32 v126, v126, v132
	v_mul_f32_e32 v126, v126, v133
	v_fma_f32 v126, v126, v206, v94
	v_sub_f32_e32 v127, v127, v132
	v_mul_f32_e32 v127, v127, v133
	v_fma_f32 v127, v127, v207, v95
	v_sub_f32_e32 v120, v120, v132
	v_mul_f32_e32 v120, v120, v133
	v_fma_f32 v120, v120, v208, v88
	v_sub_f32_e32 v121, v121, v132
	v_mul_f32_e32 v121, v121, v133
	v_fma_f32 v121, v121, v209, v89
	v_sub_f32_e32 v122, v122, v132
	v_mul_f32_e32 v122, v122, v133
	v_fma_f32 v122, v122, v210, v90
	v_sub_f32_e32 v123, v123, v132
	v_mul_f32_e32 v123, v123, v133
	v_fma_f32 v123, v123, v211, v91
	v_sub_f32_e32 v116, v116, v132
	v_mul_f32_e32 v116, v116, v133
	v_fma_f32 v116, v116, v212, v84
	v_sub_f32_e32 v117, v117, v132
	v_mul_f32_e32 v117, v117, v133
	v_fma_f32 v117, v117, v213, v85
	v_sub_f32_e32 v118, v118, v132
	v_mul_f32_e32 v118, v118, v133
	v_fma_f32 v118, v118, v214, v86
	v_sub_f32_e32 v119, v119, v132
	v_mul_f32_e32 v119, v119, v133
	v_fma_f32 v119, v119, v215, v87
	v_sub_f32_e32 v112, v112, v132
	v_mul_f32_e32 v112, v112, v133
	v_fma_f32 v112, v112, v216, v80
	v_sub_f32_e32 v113, v113, v132
	v_mul_f32_e32 v113, v113, v133
	v_fma_f32 v113, v113, v217, v81
	v_sub_f32_e32 v114, v114, v132
	v_mul_f32_e32 v114, v114, v133
	v_fma_f32 v114, v114, v218, v82
	v_sub_f32_e32 v115, v115, v132
	v_mul_f32_e32 v115, v115, v133
	v_fma_f32 v115, v115, v219, v83
	v_sub_f32_e32 v108, v108, v134
	v_mul_f32_e32 v108, v108, v135
	v_fma_f32 v108, v108, v204, v76
	v_sub_f32_e32 v109, v109, v134
	v_mul_f32_e32 v109, v109, v135
	v_fma_f32 v109, v109, v205, v77
	v_sub_f32_e32 v110, v110, v134
	v_mul_f32_e32 v110, v110, v135
	v_fma_f32 v110, v110, v206, v78
	v_sub_f32_e32 v111, v111, v134
	v_mul_f32_e32 v111, v111, v135
	v_fma_f32 v111, v111, v207, v79
	v_sub_f32_e32 v104, v104, v134
	v_mul_f32_e32 v104, v104, v135
	v_fma_f32 v104, v104, v208, v72
	v_sub_f32_e32 v105, v105, v134
	v_mul_f32_e32 v105, v105, v135
	v_fma_f32 v105, v105, v209, v73
	v_sub_f32_e32 v106, v106, v134
	v_mul_f32_e32 v106, v106, v135
	v_fma_f32 v106, v106, v210, v74
	v_sub_f32_e32 v107, v107, v134
	v_mul_f32_e32 v107, v107, v135
	v_fma_f32 v107, v107, v211, v75
	v_sub_f32_e32 v100, v100, v134
	v_mul_f32_e32 v100, v100, v135
	v_fma_f32 v100, v100, v212, v68
	v_sub_f32_e32 v101, v101, v134
	v_mul_f32_e32 v101, v101, v135
	v_fma_f32 v101, v101, v213, v69
	v_sub_f32_e32 v102, v102, v134
	v_mul_f32_e32 v102, v102, v135
	v_fma_f32 v102, v102, v214, v70
	v_sub_f32_e32 v103, v103, v134
	v_mul_f32_e32 v103, v103, v135
	v_fma_f32 v103, v103, v215, v71
	v_sub_f32_e32 v96, v96, v134
	v_mul_f32_e32 v96, v96, v135
	v_fma_f32 v96, v96, v216, v64
	v_sub_f32_e32 v97, v97, v134
	v_mul_f32_e32 v97, v97, v135
	v_fma_f32 v97, v97, v217, v65
	v_sub_f32_e32 v98, v98, v134
	v_mul_f32_e32 v98, v98, v135
	v_fma_f32 v98, v98, v218, v66
	v_sub_f32_e32 v99, v99, v134
	v_mul_f32_e32 v99, v99, v135
	v_fma_f32 v99, v99, v219, v67
	v_sub_f32_e32 v220, v220, v138
	v_mul_f32_e32 v220, v220, v139
	v_fma_f32 v220, v220, v204, v60
	v_sub_f32_e32 v221, v221, v138
	v_mul_f32_e32 v221, v221, v139
	v_fma_f32 v221, v221, v205, v61
	v_sub_f32_e32 v222, v222, v138
	v_mul_f32_e32 v222, v222, v139
	v_fma_f32 v222, v222, v206, v62
	v_sub_f32_e32 v223, v223, v138
	v_mul_f32_e32 v223, v223, v139
	v_fma_f32 v223, v223, v207, v63
	v_sub_f32_e32 v224, v224, v138
	v_mul_f32_e32 v224, v224, v139
	v_fma_f32 v224, v224, v208, v56
	v_sub_f32_e32 v225, v225, v138
	v_mul_f32_e32 v225, v225, v139
	v_fma_f32 v225, v225, v209, v57
	v_sub_f32_e32 v226, v226, v138
	v_mul_f32_e32 v226, v226, v139
	v_fma_f32 v226, v226, v210, v58
	v_sub_f32_e32 v227, v227, v138
	v_mul_f32_e32 v227, v227, v139
	v_fma_f32 v227, v227, v211, v59
	v_sub_f32_e32 v228, v228, v138
	v_mul_f32_e32 v228, v228, v139
	v_fma_f32 v228, v228, v212, v52
	v_sub_f32_e32 v229, v229, v138
	v_mul_f32_e32 v229, v229, v139
	v_fma_f32 v229, v229, v213, v53
	v_sub_f32_e32 v230, v230, v138
	v_mul_f32_e32 v230, v230, v139
	v_fma_f32 v230, v230, v214, v54
	v_sub_f32_e32 v231, v231, v138
	v_mul_f32_e32 v231, v231, v139
	v_fma_f32 v231, v231, v215, v55
	v_sub_f32_e32 v232, v232, v138
	v_mul_f32_e32 v232, v232, v139
	v_fma_f32 v232, v232, v216, v48
	v_sub_f32_e32 v233, v233, v138
	v_mul_f32_e32 v233, v233, v139
	v_fma_f32 v233, v233, v217, v49
	v_sub_f32_e32 v234, v234, v138
	v_mul_f32_e32 v234, v234, v139
	v_fma_f32 v234, v234, v218, v50
	v_sub_f32_e32 v235, v235, v138
	v_mul_f32_e32 v235, v235, v139
	v_fma_f32 v235, v235, v219, v51
	v_sub_f32_e32 v236, v236, v140
	v_mul_f32_e32 v236, v236, v141
	v_fma_f32 v236, v236, v204, v44
	v_sub_f32_e32 v237, v237, v140
	v_mul_f32_e32 v237, v237, v141
	v_fma_f32 v237, v237, v205, v45
	v_sub_f32_e32 v238, v238, v140
	v_mul_f32_e32 v238, v238, v141
	v_fma_f32 v238, v238, v206, v46
	v_sub_f32_e32 v239, v239, v140
	v_mul_f32_e32 v239, v239, v141
	v_fma_f32 v239, v239, v207, v47
	v_sub_f32_e32 v240, v240, v140
	v_mul_f32_e32 v240, v240, v141
	v_fma_f32 v240, v240, v208, v40
	v_sub_f32_e32 v241, v241, v140
	v_mul_f32_e32 v241, v241, v141
	v_fma_f32 v241, v241, v209, v41
	v_sub_f32_e32 v242, v242, v140
	v_mul_f32_e32 v242, v242, v141
	v_fma_f32 v242, v242, v210, v42
	v_sub_f32_e32 v243, v243, v140
	v_mul_f32_e32 v243, v243, v141
	v_fma_f32 v243, v243, v211, v43
	v_sub_f32_e32 v244, v244, v140
	v_mul_f32_e32 v244, v244, v141
	v_fma_f32 v244, v244, v212, v36
;     DI void operator()(const f32x4 (&acc)[2][2][4][2], const Unit& u, int wr, int wc, int fr, int fq) const {
;     ...
;                     for (int n = 0; n < 2; ++n) {
;                         const int col = u.pn * BM + bj * HALF + wc * 32 + n * 16 + 4 * fq;
;                         float* xp = X + (size_t)row * DM + col;
;                         f32x4 x4 = *(const f32x4*)xp; const f32x4 g4 = *(const f32x4*)(g + col);
;                         if (pg) x4 = (x4 - mu) * rs * *(const f32x4*)(pg + col) + *(const f32x4*)(pb + col);
;                         *(f32x4*)xp = x4 * ALPHA + g4 * acc[ai][bj][m][n];
	v_sub_f32_e32 v245, v245, v140
	v_mul_f32_e32 v245, v245, v141
	v_fma_f32 v245, v245, v213, v37
	v_sub_f32_e32 v246, v246, v140
	v_mul_f32_e32 v246, v246, v141
	v_fma_f32 v246, v246, v214, v38
	v_sub_f32_e32 v247, v247, v140
	v_mul_f32_e32 v247, v247, v141
	v_fma_f32 v247, v247, v215, v39
	v_sub_f32_e32 v248, v248, v140
	v_mul_f32_e32 v248, v248, v141
	v_fma_f32 v248, v248, v216, v32
	v_sub_f32_e32 v249, v249, v140
	v_mul_f32_e32 v249, v249, v141
	v_fma_f32 v249, v249, v217, v33
	v_sub_f32_e32 v250, v250, v140
	v_mul_f32_e32 v250, v250, v141
	v_fma_f32 v250, v250, v218, v34
	v_sub_f32_e32 v251, v251, v140
	v_mul_f32_e32 v251, v251, v141
	v_fma_f32 v251, v251, v219, v35
	global_load_dwordx4 v[92:95], v164, s[72:73] offset:0 nt
	global_load_dwordx4 v[88:91], v164, s[72:73] offset:64 nt
	global_load_dwordx4 v[84:87], v164, s[72:73] offset:512 nt
	global_load_dwordx4 v[80:83], v164, s[72:73] offset:576 nt
	global_load_dwordx4 v[76:79], v165, s[72:73] offset:0 nt
	global_load_dwordx4 v[72:75], v165, s[72:73] offset:64 nt
	global_load_dwordx4 v[68:71], v165, s[72:73] offset:512 nt
	global_load_dwordx4 v[64:67], v165, s[72:73] offset:576 nt
	global_store_dwordx4 v160, v[124:127], s[72:73] offset:0
	global_store_dwordx4 v160, v[120:123], s[72:73] offset:64
	global_store_dwordx4 v160, v[116:119], s[72:73] offset:512
	global_store_dwordx4 v160, v[112:115], s[72:73] offset:576
	global_store_dwordx4 v161, v[108:111], s[72:73] offset:0
	global_store_dwordx4 v161, v[104:107], s[72:73] offset:64
	global_store_dwordx4 v161, v[100:103], s[72:73] offset:512
	global_store_dwordx4 v161, v[96:99], s[72:73] offset:576
	global_store_dwordx4 v162, v[220:223], s[72:73] offset:0
	global_store_dwordx4 v162, v[224:227], s[72:73] offset:64
	global_store_dwordx4 v162, v[228:231], s[72:73] offset:512
	global_store_dwordx4 v162, v[232:235], s[72:73] offset:576
	global_store_dwordx4 v163, v[236:239], s[72:73] offset:0
	global_store_dwordx4 v163, v[240:243], s[72:73] offset:64
	global_store_dwordx4 v163, v[244:247], s[72:73] offset:512
	global_store_dwordx4 v163, v[248:251], s[72:73] offset:576
	s_waitcnt vmcnt(16)
	v_sub_f32_e32 v92, v92, v142
	v_mul_f32_e32 v92, v92, v143
	v_fma_f32 v92, v92, v204, v28
	v_sub_f32_e32 v93, v93, v142
	v_mul_f32_e32 v93, v93, v143
	v_fma_f32 v93, v93, v205, v29
	v_sub_f32_e32 v94, v94, v142
	v_mul_f32_e32 v94, v94, v143
	v_fma_f32 v94, v94, v206, v30
	v_sub_f32_e32 v95, v95, v142
	v_mul_f32_e32 v95, v95, v143
	v_fma_f32 v95, v95, v207, v31
	v_sub_f32_e32 v88, v88, v142
	v_mul_f32_e32 v88, v88, v143
	v_fma_f32 v88, v88, v208, v24
	v_sub_f32_e32 v89, v89, v142
	v_mul_f32_e32 v89, v89, v143
	v_fma_f32 v89, v89, v209, v25
	v_sub_f32_e32 v90, v90, v142
	v_mul_f32_e32 v90, v90, v143
	v_fma_f32 v90, v90, v210, v26
	v_sub_f32_e32 v91, v91, v142
	v_mul_f32_e32 v91, v91, v143
	v_fma_f32 v91, v91, v211, v27
	v_sub_f32_e32 v84, v84, v142
	v_mul_f32_e32 v84, v84, v143
	v_fma_f32 v84, v84, v212, v20
	v_sub_f32_e32 v85, v85, v142
	v_mul_f32_e32 v85, v85, v143
	v_fma_f32 v85, v85, v213, v21
	v_sub_f32_e32 v86, v86, v142
	v_mul_f32_e32 v86, v86, v143
	v_fma_f32 v86, v86, v214, v22
	v_sub_f32_e32 v87, v87, v142
	v_mul_f32_e32 v87, v87, v143
	v_fma_f32 v87, v87, v215, v23
	v_sub_f32_e32 v80, v80, v142
	v_mul_f32_e32 v80, v80, v143
	v_fma_f32 v80, v80, v216, v16
	v_sub_f32_e32 v81, v81, v142
	v_mul_f32_e32 v81, v81, v143
	v_fma_f32 v81, v81, v217, v17
	v_sub_f32_e32 v82, v82, v142
	v_mul_f32_e32 v82, v82, v143
	v_fma_f32 v82, v82, v218, v18
	v_sub_f32_e32 v83, v83, v142
	v_mul_f32_e32 v83, v83, v143
	v_fma_f32 v83, v83, v219, v19
	v_sub_f32_e32 v76, v76, v156
	v_mul_f32_e32 v76, v76, v157
	v_fma_f32 v76, v76, v204, v12
	v_sub_f32_e32 v77, v77, v156
	v_mul_f32_e32 v77, v77, v157
	v_fma_f32 v77, v77, v205, v13
	v_sub_f32_e32 v78, v78, v156
	v_mul_f32_e32 v78, v78, v157
	v_fma_f32 v78, v78, v206, v14
	v_sub_f32_e32 v79, v79, v156
	v_mul_f32_e32 v79, v79, v157
	v_fma_f32 v79, v79, v207, v15
	v_sub_f32_e32 v72, v72, v156
	v_mul_f32_e32 v72, v72, v157
	v_fma_f32 v72, v72, v208, v8
	v_sub_f32_e32 v73, v73, v156
	v_mul_f32_e32 v73, v73, v157
	v_fma_f32 v73, v73, v209, v9
	v_sub_f32_e32 v74, v74, v156
	v_mul_f32_e32 v74, v74, v157
	v_fma_f32 v74, v74, v210, v10
	v_sub_f32_e32 v75, v75, v156
	v_mul_f32_e32 v75, v75, v157
	v_fma_f32 v75, v75, v211, v11
	v_sub_f32_e32 v68, v68, v156
	v_mul_f32_e32 v68, v68, v157
	v_fma_f32 v68, v68, v212, v4
	v_sub_f32_e32 v69, v69, v156
	v_mul_f32_e32 v69, v69, v157
	v_fma_f32 v69, v69, v213, v5
	v_sub_f32_e32 v70, v70, v156
	v_mul_f32_e32 v70, v70, v157
	v_fma_f32 v70, v70, v214, v6
	v_sub_f32_e32 v71, v71, v156
	v_mul_f32_e32 v71, v71, v157
	v_fma_f32 v71, v71, v215, v7
	v_sub_f32_e32 v64, v64, v156
	v_mul_f32_e32 v64, v64, v157
	v_fma_f32 v64, v64, v216, v0
	v_sub_f32_e32 v65, v65, v156
	v_mul_f32_e32 v65, v65, v157
	v_fma_f32 v65, v65, v217, v1
	v_sub_f32_e32 v66, v66, v156
	v_mul_f32_e32 v66, v66, v157
	v_fma_f32 v66, v66, v218, v2
	v_sub_f32_e32 v67, v67, v156
	v_mul_f32_e32 v67, v67, v157
	v_fma_f32 v67, v67, v219, v3
	global_store_dwordx4 v164, v[92:95], s[72:73] offset:0
	global_store_dwordx4 v164, v[88:91], s[72:73] offset:64
	global_store_dwordx4 v164, v[84:87], s[72:73] offset:512
	global_store_dwordx4 v164, v[80:83], s[72:73] offset:576
	global_store_dwordx4 v165, v[76:79], s[72:73] offset:0
	global_store_dwordx4 v165, v[72:75], s[72:73] offset:64
	global_store_dwordx4 v165, v[68:71], s[72:73] offset:512
	global_store_dwordx4 v165, v[64:67], s[72:73] offset:576
	s_branch .LBB0_2743

; DI void phase_ln(const Params& p, const float* gam, const float* bet, const float* modnext  , bool skip_ctx, bool final_out,
;                  const float* cgate  , const float* pg, const float* pb  ) {
;     ...
;     for (int rowA = gw; rowA < MR; rowA += 2 * nw) {
;         f32x4 v[2][8]; float sum[2] = {0.f, 0.f}; bool act[2]; int rows[2];
; #pragma unroll
;         for (int q = 0; q < 2; ++q) {
;             const int row = rowA + q * nw; rows[q] = row;
;             const int b = row / RB, r = row % RB;
;             act[q] = row < MR && !(skip_ctx && r < CL);
;             if (act[q]) {
;                 const bool cpart = cgate && r < CL;
;                 float pmu = 0.f, prs = 1.f;
;                 if (cpart && pg) { const float2 st = RS[row]; pmu = st.x; prs = st.y; }
; #pragma unroll
;                 for (int i = 0; i < 8; ++i) {
;                     const int col = (i * 64 + lane) * 4;
;                     v[q][i] = *(const f32x4*)(X + (size_t)row * DM + col);
;                     if (cpart) {
;                         if (pg) v[q][i] = (v[q][i] - pmu) * prs * *(const f32x4*)(pg + col) + *(const f32x4*)(pb + col);
;                         const float* pt = (const float*)(p.ws + WS_PART) + ((size_t)b * 256 + r) * DM + col;
;                         const f32x4 ps = *(const f32x4*)pt + *(const f32x4*)(pt + (size_t)1024 * DM) + *(const f32x4*)(pt + (size_t)2048 * DM) + *(const f32x4*)(pt + (size_t)3072 * DM);
;                         v[q][i] = v[q][i] * ALPHA + *(const f32x4*)(cgate + col) * ps;
;                         *(f32x4*)(X + (size_t)row * DM + col) = v[q][i];
;                     }
;                 }
;             } else {
; #pragma unroll
;                 for (int i = 0; i < 8; ++i) v[q][i] = (f32x4){0.f, 0.f, 0.f, 0.f};
;             }
;         }
; #pragma unroll
;         for (int q = 0; q < 2; ++q)
; #pragma unroll
;             for (int i = 0; i < 8; ++i) sum[q] += v[q][i][0] + v[q][i][1] + v[q][i][2] + v[q][i][3];
;         float mu[2], sq[2] = {0.f, 0.f}, rs[2];
; #pragma unroll
;         for (int o = 32; o > 0; o >>= 1) { sum[0] += __shfl_xor(sum[0], o); sum[1] += __shfl_xor(sum[1], o); }
; #pragma unroll
;         for (int q = 0; q < 2; ++q) {
;             mu[q] = sum[q] * (1.f / 2048.f);
; #pragma unroll
.Ll1a_row:
	s_cmpk_ge_u32 s9, 0x2400
	s_cbranch_scc1 .Ll1a_done
	s_lshr_b32 s35, s9, 8
	s_mul_i32 s27, s35, 57
	s_lshr_b32 s27, s27, 9
	s_mul_i32 s35, s27, 0x900
	s_sub_u32 s29, s9, s35
	s_cmpk_lt_u32 s29, 0x100
	s_cbranch_scc1 .Ll1a_next
	s_mov_b32 s32, s27
	s_lshl_b32 s35, s9, 13
	s_add_u32 s2, s50, 0xcba0000
	s_addc_u32 s3, s51, 0
	s_add_u32 s2, s2, s35
	s_addc_u32 s3, s3, 0
	global_load_dwordx4 v[88:91], v76, s[2:3] offset:0 nt
	global_load_dwordx4 v[92:95], v76, s[2:3] offset:1024 nt
	global_load_dwordx4 v[96:99], v76, s[2:3] offset:2048 nt
	global_load_dwordx4 v[100:103], v76, s[2:3] offset:3072 nt
	global_load_dwordx4 v[104:107], v77, s[2:3] offset:0 nt
	global_load_dwordx4 v[108:111], v77, s[2:3] offset:1024 nt
	global_load_dwordx4 v[112:115], v77, s[2:3] offset:2048 nt
	global_load_dwordx4 v[116:119], v77, s[2:3] offset:3072 nt
	s_mul_i32 s35, s32, 0xc000
	s_add_u32 s4, s50, 0x4a000
	s_addc_u32 s5, s51, 0
	s_add_u32 s4, s4, s35
	s_addc_u32 s5, s5, 0
	global_load_dwordx4 v[140:143], v76, s[4:5] offset:0
	global_load_dwordx4 v[144:147], v76, s[4:5] offset:1024
	global_load_dwordx4 v[148:151], v76, s[4:5] offset:2048
	global_load_dwordx4 v[152:155], v76, s[4:5] offset:3072
	global_load_dwordx4 v[156:159], v77, s[4:5] offset:0
	global_load_dwordx4 v[160:163], v77, s[4:5] offset:1024
	global_load_dwordx4 v[164:167], v77, s[4:5] offset:2048
	global_load_dwordx4 v[168:171], v77, s[4:5] offset:3072
	s_add_u32 s4, s4, 0x2000
	s_addc_u32 s5, s5, 0
	global_load_dwordx4 v[204:207], v76, s[4:5] offset:0
	global_load_dwordx4 v[208:211], v76, s[4:5] offset:1024
	global_load_dwordx4 v[212:215], v76, s[4:5] offset:2048
	global_load_dwordx4 v[216:219], v76, s[4:5] offset:3072
	global_load_dwordx4 v[220:223], v77, s[4:5] offset:0
	global_load_dwordx4 v[224:227], v77, s[4:5] offset:1024
	global_load_dwordx4 v[228:231], v77, s[4:5] offset:2048
	global_load_dwordx4 v[232:235], v77, s[4:5] offset:3072
	s_waitcnt vmcnt(16)
	v_add_f32_e32 v80, v88, v92
	v_add_f32_e32 v81, v89, v93
	v_add_f32_e32 v82, v90, v94
	v_add_f32_e32 v83, v91, v95
	v_add_f32_e32 v80, v96, v80
	v_add_f32_e32 v81, v97, v81
	v_add_f32_e32 v82, v98, v82
	v_add_f32_e32 v83, v99, v83
	v_add_f32_e32 v80, v100, v80
	v_add_f32_e32 v81, v101, v81
	v_add_f32_e32 v82, v102, v82
	v_add_f32_e32 v83, v103, v83
	v_add_f32_e32 v80, v104, v80
	v_add_f32_e32 v81, v105, v81
	v_add_f32_e32 v82, v106, v82
	v_add_f32_e32 v83, v107, v83
	v_add_f32_e32 v80, v108, v80
	v_add_f32_e32 v81, v109, v81
	v_add_f32_e32 v82, v110, v82
	v_add_f32_e32 v83, v111, v83
	v_add_f32_e32 v80, v112, v80
	v_add_f32_e32 v81, v113, v81
	v_add_f32_e32 v82, v114, v82
	v_add_f32_e32 v83, v115, v83
	v_add_f32_e32 v80, v116, v80
	v_add_f32_e32 v81, v117, v81
	v_add_f32_e32 v82, v118, v82
	v_add_f32_e32 v83, v119, v83
	v_add_f32_e32 v80, v80, v81
	v_add_f32_e32 v82, v82, v83
	v_add_f32_e32 v80, v80, v82
	s_nop 1
	v_add_f32_dpp v86, v80, v80 quad_perm:[1,0,3,2] row_mask:0xf bank_mask:0xf
	s_nop 1
	v_add_f32_dpp v86, v86, v86 quad_perm:[2,3,0,1] row_mask:0xf bank_mask:0xf
	s_nop 1
	v_add_f32_dpp v86, v86, v86 row_half_mirror row_mask:0xf bank_mask:0xf
	s_nop 1
	v_add_f32_dpp v86, v86, v86 row_mirror row_mask:0xf bank_mask:0xf
	s_nop 1
	v_readlane_b32 s69, v86, 0
	v_readlane_b32 s71, v86, 16
	v_readlane_b32 s73, v86, 32
	v_readlane_b32 s81, v86, 48
	s_nop 3
	v_mov_b32_e32 v84, s69
	v_add_f32_e32 v84, s71, v84
	v_add_f32_e32 v84, s73, v84
	v_add_f32_e32 v84, s81, v84
	v_mul_f32_e32 v236, s82, v84
	v_sub_f32_e32 v88, v88, v236
	v_sub_f32_e32 v89, v89, v236
	v_sub_f32_e32 v90, v90, v236
	v_sub_f32_e32 v91, v91, v236
	v_sub_f32_e32 v92, v92, v236
	v_sub_f32_e32 v93, v93, v236
	v_sub_f32_e32 v94, v94, v236
	v_sub_f32_e32 v95, v95, v236
	v_sub_f32_e32 v96, v96, v236
	v_sub_f32_e32 v97, v97, v236
	v_sub_f32_e32 v98, v98, v236
	v_sub_f32_e32 v99, v99, v236
	v_sub_f32_e32 v100, v100, v236
	v_sub_f32_e32 v101, v101, v236
	v_sub_f32_e32 v102, v102, v236
	v_sub_f32_e32 v103, v103, v236
	v_sub_f32_e32 v104, v104, v236
	v_sub_f32_e32 v105, v105, v236
	v_sub_f32_e32 v106, v106, v236
	v_sub_f32_e32 v107, v107, v236
	v_sub_f32_e32 v108, v108, v236
	v_sub_f32_e32 v109, v109, v236
	v_sub_f32_e32 v110, v110, v236
	v_sub_f32_e32 v111, v111, v236
	v_sub_f32_e32 v112, v112, v236
	v_sub_f32_e32 v113, v113, v236
	v_sub_f32_e32 v114, v114, v236
	v_sub_f32_e32 v115, v115, v236
	v_sub_f32_e32 v116, v116, v236
	v_sub_f32_e32 v117, v117, v236
	v_sub_f32_e32 v118, v118, v236
	v_sub_f32_e32 v119, v119, v236
	v_mul_f32_e32 v80, v88, v88
	v_mul_f32_e32 v81, v89, v89
	v_mul_f32_e32 v82, v90, v90
	v_mul_f32_e32 v83, v91, v91
	v_fmac_f32_e32 v80, v92, v92
	v_fmac_f32_e32 v81, v93, v93
	v_fmac_f32_e32 v82, v94, v94
	v_fmac_f32_e32 v83, v95, v95
	v_fmac_f32_e32 v80, v96, v96
	v_fmac_f32_e32 v81, v97, v97
	v_fmac_f32_e32 v82, v98, v98
	v_fmac_f32_e32 v83, v99, v99
	v_fmac_f32_e32 v80, v100, v100
	v_fmac_f32_e32 v81, v101, v101
	v_fmac_f32_e32 v82, v102, v102
	v_fmac_f32_e32 v83, v103, v103
	v_fmac_f32_e32 v80, v104, v104
	v_fmac_f32_e32 v81, v105, v105
	v_fmac_f32_e32 v82, v106, v106
	v_fmac_f32_e32 v83, v107, v107
	v_fmac_f32_e32 v80, v108, v108
	v_fmac_f32_e32 v81, v109, v109
	v_fmac_f32_e32 v82, v110, v110
	v_fmac_f32_e32 v83, v111, v111
	v_fmac_f32_e32 v80, v112, v112
	v_fmac_f32_e32 v81, v113, v113
	v_fmac_f32_e32 v82, v114, v114
	v_fmac_f32_e32 v83, v115, v115
	v_fmac_f32_e32 v80, v116, v116
	v_fmac_f32_e32 v81, v117, v117
	v_fmac_f32_e32 v82, v118, v118
	v_fmac_f32_e32 v83, v119, v119
	v_add_f32_e32 v80, v80, v81
	v_add_f32_e32 v82, v82, v83
	v_add_f32_e32 v80, v80, v82
	s_nop 1
	v_add_f32_dpp v86, v80, v80 quad_perm:[1,0,3,2] row_mask:0xf bank_mask:0xf
	s_nop 1
	v_add_f32_dpp v86, v86, v86 quad_perm:[2,3,0,1] row_mask:0xf bank_mask:0xf
	s_nop 1
	v_add_f32_dpp v86, v86, v86 row_half_mirror row_mask:0xf bank_mask:0xf
	s_nop 1
	v_add_f32_dpp v86, v86, v86 row_mirror row_mask:0xf bank_mask:0xf
	s_nop 1
	v_readlane_b32 s69, v86, 0
	v_readlane_b32 s71, v86, 16
	v_readlane_b32 s73, v86, 32
	v_readlane_b32 s81, v86, 48
	s_nop 3
	v_mov_b32_e32 v84, s69
	v_add_f32_e32 v84, s71, v84
	v_add_f32_e32 v84, s73, v84
	v_add_f32_e32 v84, s81, v84
	v_mov_b32_e32 v86, s83
	v_fmac_f32_e32 v86, s82, v84
	v_rsq_f32_e32 v237, v86
	s_nop 0
	s_lshl_b32 s35, s9, 3
	s_add_u32 s22, s50, 0x260a0000
	s_addc_u32 s23, s51, 0
	s_add_u32 s22, s22, s35
	s_addc_u32 s23, s23, 0
	s_mov_b64 s[74:75], exec
	s_mov_b64 exec, 1
	global_store_dwordx2 v79, v[236:237], s[22:23]
	s_mov_b64 exec, s[74:75]
	s_lshl_b32 s35, s9, 12
	s_add_u32 s6, s50, 0x23ca0000
	s_addc_u32 s7, s51, 0
	s_add_u32 s6, s6, s35
	s_addc_u32 s7, s7, 0
	s_waitcnt vmcnt(1)
; DI void st_bf16x4(bf16_t* p, f32x4 v) { u32x2 w; w.x = cvt_pk_bf16(v[0], v[1]); w.y = cvt_pk_bf16(v[2], v[3]); *(u32x2*)p = w; }
; DI void phase_ln(const Params& p, const float* gam, const float* bet, const float* modnext  , bool skip_ctx, bool final_out,
;                  const float* cgate  , const float* pg, const float* pb  ) {
;     ...
; #pragma unroll
;             for (int i = 0; i < 8; ++i) {
;                 const int col = (i * 64 + lane) * 4;
;                 const f32x4 o = v[q][i] * rs[q] * *(const f32x4*)(gam + col) + *(const f32x4*)(bet + col);
;                 if (final_out) { *(f32x4*)(p.out + ((size_t)b * TL + (r - CL)) * DM + col) = o; }
;                 else {
;                     const f32x4 s4 = *(const f32x4*)(modnext + (size_t)s * 12288 + col), c4 = *(const f32x4*)(modnext + (size_t)s * 12288 + 2048 + col);
;                     st_bf16x4(H + (size_t)row * DM + col, o * (c4 + 1.f) + s4);
;                 }
	v_mul_f32_e32 v88, v88, v237
	v_mul_f32_e32 v89, v89, v237
	v_mul_f32_e32 v90, v90, v237
	v_mul_f32_e32 v91, v91, v237
	v_fma_f32 v88, v88, v12, v44
	v_fma_f32 v89, v89, v13, v45
	v_fma_f32 v90, v90, v14, v46
	v_fma_f32 v91, v91, v15, v47
	v_add_f32_e32 v204, 1.0, v204
	v_add_f32_e32 v205, 1.0, v205
	v_add_f32_e32 v206, 1.0, v206
	v_add_f32_e32 v207, 1.0, v207
	v_fma_f32 v88, v88, v204, v140
	v_fma_f32 v89, v89, v205, v141
	v_fma_f32 v90, v90, v206, v142
	v_fma_f32 v91, v91, v207, v143
	v_cvt_pk_bf16_f32 v88, v88, v89
	v_cvt_pk_bf16_f32 v89, v90, v91
	global_store_dwordx2 v78, v[88:89], s[6:7] offset:0
	v_mul_f32_e32 v92, v92, v237
	v_mul_f32_e32 v93, v93, v237
	v_mul_f32_e32 v94, v94, v237
	v_mul_f32_e32 v95, v95, v237
	v_fma_f32 v92, v92, v16, v48
	v_fma_f32 v93, v93, v17, v49
	v_fma_f32 v94, v94, v18, v50
	v_fma_f32 v95, v95, v19, v51
	v_add_f32_e32 v208, 1.0, v208
	v_add_f32_e32 v209, 1.0, v209
	v_add_f32_e32 v210, 1.0, v210
	v_add_f32_e32 v211, 1.0, v211
	v_fma_f32 v92, v92, v208, v144
	v_fma_f32 v93, v93, v209, v145
	v_fma_f32 v94, v94, v210, v146
	v_fma_f32 v95, v95, v211, v147
	v_cvt_pk_bf16_f32 v92, v92, v93
	v_cvt_pk_bf16_f32 v93, v94, v95
	global_store_dwordx2 v78, v[92:93], s[6:7] offset:512
	v_mul_f32_e32 v96, v96, v237
	v_mul_f32_e32 v97, v97, v237
	v_mul_f32_e32 v98, v98, v237
	v_mul_f32_e32 v99, v99, v237
	v_fma_f32 v96, v96, v20, v52
	v_fma_f32 v97, v97, v21, v53
	v_fma_f32 v98, v98, v22, v54
	v_fma_f32 v99, v99, v23, v55
	v_add_f32_e32 v212, 1.0, v212
	v_add_f32_e32 v213, 1.0, v213
	v_add_f32_e32 v214, 1.0, v214
	v_add_f32_e32 v215, 1.0, v215
	v_fma_f32 v96, v96, v212, v148
	v_fma_f32 v97, v97, v213, v149
	v_fma_f32 v98, v98, v214, v150
	v_fma_f32 v99, v99, v215, v151
	v_cvt_pk_bf16_f32 v96, v96, v97
	v_cvt_pk_bf16_f32 v97, v98, v99
	global_store_dwordx2 v78, v[96:97], s[6:7] offset:1024
	v_mul_f32_e32 v100, v100, v237
	v_mul_f32_e32 v101, v101, v237
	v_mul_f32_e32 v102, v102, v237
	v_mul_f32_e32 v103, v103, v237
	v_fma_f32 v100, v100, v24, v56
	v_fma_f32 v101, v101, v25, v57
	v_fma_f32 v102, v102, v26, v58
	v_fma_f32 v103, v103, v27, v59
	v_add_f32_e32 v216, 1.0, v216
	v_add_f32_e32 v217, 1.0, v217
	v_add_f32_e32 v218, 1.0, v218
	v_add_f32_e32 v219, 1.0, v219
	v_fma_f32 v100, v100, v216, v152
	v_fma_f32 v101, v101, v217, v153
	v_fma_f32 v102, v102, v218, v154
	v_fma_f32 v103, v103, v219, v155
	v_cvt_pk_bf16_f32 v100, v100, v101
	v_cvt_pk_bf16_f32 v101, v102, v103
	global_store_dwordx2 v78, v[100:101], s[6:7] offset:1536
	v_mul_f32_e32 v104, v104, v237
	v_mul_f32_e32 v105, v105, v237
	v_mul_f32_e32 v106, v106, v237
	v_mul_f32_e32 v107, v107, v237
	v_fma_f32 v104, v104, v28, v60
	v_fma_f32 v105, v105, v29, v61
	v_fma_f32 v106, v106, v30, v62
	v_fma_f32 v107, v107, v31, v63
	v_add_f32_e32 v220, 1.0, v220
	v_add_f32_e32 v221, 1.0, v221
	v_add_f32_e32 v222, 1.0, v222
	v_add_f32_e32 v223, 1.0, v223
	v_fma_f32 v104, v104, v220, v156
	v_fma_f32 v105, v105, v221, v157
	v_fma_f32 v106, v106, v222, v158
	v_fma_f32 v107, v107, v223, v159
	v_cvt_pk_bf16_f32 v104, v104, v105
	v_cvt_pk_bf16_f32 v105, v106, v107
	global_store_dwordx2 v78, v[104:105], s[6:7] offset:2048
	v_mul_f32_e32 v108, v108, v237
	v_mul_f32_e32 v109, v109, v237
	v_mul_f32_e32 v110, v110, v237
	v_mul_f32_e32 v111, v111, v237
	v_fma_f32 v108, v108, v32, v64
	v_fma_f32 v109, v109, v33, v65
	v_fma_f32 v110, v110, v34, v66
	v_fma_f32 v111, v111, v35, v67
	v_add_f32_e32 v224, 1.0, v224
	v_add_f32_e32 v225, 1.0, v225
	v_add_f32_e32 v226, 1.0, v226
	v_add_f32_e32 v227, 1.0, v227
	v_fma_f32 v108, v108, v224, v160
	v_fma_f32 v109, v109, v225, v161
	v_fma_f32 v110, v110, v226, v162
	v_fma_f32 v111, v111, v227, v163
	v_cvt_pk_bf16_f32 v108, v108, v109
	v_cvt_pk_bf16_f32 v109, v110, v111
	global_store_dwordx2 v78, v[108:109], s[6:7] offset:2560
	v_mul_f32_e32 v112, v112, v237
	v_mul_f32_e32 v113, v113, v237
	v_mul_f32_e32 v114, v114, v237
	v_mul_f32_e32 v115, v115, v237
	v_fma_f32 v112, v112, v36, v68
	v_fma_f32 v113, v113, v37, v69
	v_fma_f32 v114, v114, v38, v70
	v_fma_f32 v115, v115, v39, v71
	v_add_f32_e32 v228, 1.0, v228
	v_add_f32_e32 v229, 1.0, v229
	v_add_f32_e32 v230, 1.0, v230
	v_add_f32_e32 v231, 1.0, v231
	v_fma_f32 v112, v112, v228, v164
	v_fma_f32 v113, v113, v229, v165
	v_fma_f32 v114, v114, v230, v166
	v_fma_f32 v115, v115, v231, v167
	v_cvt_pk_bf16_f32 v112, v112, v113
	v_cvt_pk_bf16_f32 v113, v114, v115
	global_store_dwordx2 v78, v[112:113], s[6:7] offset:3072
	v_mul_f32_e32 v116, v116, v237
	v_mul_f32_e32 v117, v117, v237
	v_mul_f32_e32 v118, v118, v237
	v_mul_f32_e32 v119, v119, v237
	v_fma_f32 v116, v116, v40, v72
	v_fma_f32 v117, v117, v41, v73
	v_fma_f32 v118, v118, v42, v74
	v_fma_f32 v119, v119, v43, v75
	v_add_f32_e32 v232, 1.0, v232
	v_add_f32_e32 v233, 1.0, v233
	v_add_f32_e32 v234, 1.0, v234
	v_add_f32_e32 v235, 1.0, v235
	v_fma_f32 v116, v116, v232, v168
	v_fma_f32 v117, v117, v233, v169
	v_fma_f32 v118, v118, v234, v170
	v_fma_f32 v119, v119, v235, v171
	v_cvt_pk_bf16_f32 v116, v116, v117
	v_cvt_pk_bf16_f32 v117, v118, v119
	global_store_dwordx2 v78, v[116:117], s[6:7] offset:3584

; #define G_STAGE(bufoff, gbase, voff) do { _Pragma("unroll") for (int _i = 0; _i < 2; ++_i) \
;         __builtin_amdgcn_global_load_lds((const unsigned*)((const char*)(gbase) + (voff)[_i]), (LAS unsigned*)(lds + (bufoff) + ldsw + _i * 8192), 16, 0, 0); } while (0)
; #define G_LDA(dst, b, h) do { _Pragma("unroll") for (int m = 0; m < 4; ++m) _Pragma("unroll") for (int k = 0; k < 2; ++k) dst[m][k] = *(const LAS bf16x8*)(lds + G_SA(b, h) + aoff + m * 2048 + k * 1024); } while (0)
; #define G_LDB(dst, b, h) do { _Pragma("unroll") for (int n = 0; n < 2; ++n) _Pragma("unroll") for (int k = 0; k < 2; ++k) dst[n][k] = *(const LAS bf16x8*)(lds + G_SB(b, h) + boff + n * 2048 + k * 1024); } while (0)
; #define G_MMA(ai, bj, At, Bt_) do { __builtin_amdgcn_s_setprio(1); _Pragma("unroll") for (int m = 0; m < 4; ++m) _Pragma("unroll") for (int n = 0; n < 2; ++n) _Pragma("unroll") for (int k = 0; k < 2; ++k) \
;         acc[ai][bj][m][n] = __builtin_amdgcn_mfma_f32_16x16x32_bf16(Bt_[n][k], At[m][k], acc[ai][bj][m][n], 0, 0, 0); __builtin_amdgcn_s_setprio(0); } while (0)
; #define G_WAIT_V(n) asm volatile("s_waitcnt vmcnt(" #n ")" ::: "memory")
; #define G_WAIT_L(n) asm volatile("s_waitcnt lgkmcnt(" #n ")" ::: "memory")
; #define G_BAR __builtin_amdgcn_s_barrier()
; #define G_SCHED __builtin_amdgcn_sched_barrier(0)
; template <class Epi, bool PERMROWS = false>
; DI void gemm_phase(LAS unsigned char* lds, const bf16_t* A, int lda, const bf16_t* Bt, int K, const Sched& S, const Epi& E) {
;     ...
;             G_LDB(B0, 0, 0); G_SCHED; G_LDA(At, 0, 0); G_STAGE(G_SA(1, 1), a1 + hstepA, voffA);
;             G_WAIT_L(8); G_BAR; G_WAIT_L(0); G_MMA(0, 0, At, B0); G_BAR; G_SCHED;
;             G_LDB(B1, 0, 1); G_STAGE(G_SB(0, 0), b2, voffB);
;             G_BAR; G_WAIT_L(0); G_MMA(0, 1, At, B1); G_BAR;
;             G_LDA(At, 0, 1); G_STAGE(G_SA(0, 0), a2, voffA);
;             G_BAR; G_WAIT_L(0); G_MMA(1, 0, At, B0); G_BAR; G_SCHED;
;             G_STAGE(G_SB(0, 1), b2 + hstepB, voffB);
;             G_WAIT_V(6); G_BAR; G_MMA(1, 1, At, B1); G_BAR;
.LBB0_3113:
	ds_read_b128 v[140:143], v160
	ds_read_b128 v[144:147], v160 offset:1024
	ds_read_b128 v[148:151], v160 offset:2048
	ds_read_b128 v[164:167], v160 offset:3072
	s_add_u32 s22, s20, 0x100
	s_addc_u32 s23, s21, 0
	s_cmpk_eq_i32 s29, 0x54
	s_cselect_b32 s35, s5, s23
	s_cselect_b32 s34, s4, s22
	s_cselect_b32 s31, s1, s28
	s_cselect_b32 s30, s0, s61
	v_lshl_add_u64 v[152:153], s[20:21], 0, v[134:135]
	s_add_i32 m0, s38, 0xc000
	ds_read_b128 v[168:171], v161
	ds_read_b128 v[172:175], v161 offset:1024
	ds_read_b128 v[176:179], v161 offset:2048
	ds_read_b128 v[180:183], v161 offset:3072
	ds_read_b128 v[184:187], v161 offset:4096
	ds_read_b128 v[188:191], v161 offset:5120
	ds_read_b128 v[192:195], v161 offset:6144
	ds_read_b128 v[196:199], v161 offset:7168
	global_load_lds_dwordx4 v[152:153], off
	v_lshl_add_u64 v[152:153], s[20:21], 0, v[132:133]
	s_add_i32 m0, s38, 0xe000
	s_nop 0
	global_load_lds_dwordx4 v[152:153], off
	s_waitcnt lgkmcnt(8)
	s_barrier
	s_waitcnt lgkmcnt(0)
	s_setprio 1
	s_waitcnt lgkmcnt(0)
	v_mfma_f32_16x16x32_bf16 v[124:127], v[140:143], v[168:171], v[124:127]
	v_mfma_f32_16x16x32_bf16 v[120:123], v[148:151], v[168:171], v[120:123]
	v_mfma_f32_16x16x32_bf16 v[108:111], v[140:143], v[176:179], v[108:111]
	v_mfma_f32_16x16x32_bf16 v[104:107], v[148:151], v[176:179], v[104:107]
	v_mfma_f32_16x16x32_bf16 v[92:95], v[140:143], v[184:187], v[92:95]
	v_mfma_f32_16x16x32_bf16 v[88:91], v[148:151], v[184:187], v[88:91]
	v_mfma_f32_16x16x32_bf16 v[76:79], v[140:143], v[192:195], v[76:79]
	v_mfma_f32_16x16x32_bf16 v[72:75], v[148:151], v[192:195], v[72:75]
	v_mfma_f32_16x16x32_bf16 v[124:127], v[144:147], v[172:175], v[124:127]
	v_mfma_f32_16x16x32_bf16 v[120:123], v[164:167], v[172:175], v[120:123]
	v_mfma_f32_16x16x32_bf16 v[108:111], v[144:147], v[180:183], v[108:111]
	v_mfma_f32_16x16x32_bf16 v[104:107], v[164:167], v[180:183], v[104:107]
	v_mfma_f32_16x16x32_bf16 v[92:95], v[144:147], v[188:191], v[92:95]
	v_mfma_f32_16x16x32_bf16 v[88:91], v[164:167], v[188:191], v[88:91]
	v_mfma_f32_16x16x32_bf16 v[76:79], v[144:147], v[196:199], v[76:79]
	v_mfma_f32_16x16x32_bf16 v[72:75], v[164:167], v[196:199], v[72:75]
	s_setprio 0
	s_barrier
	s_add_i32 s20, s52, s37
	v_lshl_add_u64 v[152:153], s[30:31], 0, v[128:129]
	s_mov_b32 m0, s20
	ds_read_b128 v[204:207], v162
	ds_read_b128 v[208:211], v162 offset:1024
	ds_read_b128 v[212:215], v162 offset:2048
	ds_read_b128 v[216:219], v162 offset:3072
	global_load_lds_dwordx4 v[152:153], off
	v_lshl_add_u64 v[200:201], s[30:31], 0, v[130:131]
	s_add_i32 m0, s20, 0x2000
	s_nop 0
	global_load_lds_dwordx4 v[200:201], off
	s_barrier
	s_waitcnt lgkmcnt(0)
	s_setprio 1
	s_waitcnt lgkmcnt(0)
	v_mfma_f32_16x16x32_bf16 v[116:119], v[204:207], v[168:171], v[116:119]
	v_mfma_f32_16x16x32_bf16 v[112:115], v[212:215], v[168:171], v[112:115]
	v_mfma_f32_16x16x32_bf16 v[100:103], v[204:207], v[176:179], v[100:103]
	v_mfma_f32_16x16x32_bf16 v[96:99], v[212:215], v[176:179], v[96:99]
	v_mfma_f32_16x16x32_bf16 v[84:87], v[204:207], v[184:187], v[84:87]
	v_mfma_f32_16x16x32_bf16 v[80:83], v[212:215], v[184:187], v[80:83]
	v_mfma_f32_16x16x32_bf16 v[68:71], v[204:207], v[192:195], v[68:71]
	v_mfma_f32_16x16x32_bf16 v[64:67], v[212:215], v[192:195], v[64:67]
	v_mfma_f32_16x16x32_bf16 v[116:119], v[208:211], v[172:175], v[116:119]
	v_mfma_f32_16x16x32_bf16 v[112:115], v[216:219], v[172:175], v[112:115]
	v_mfma_f32_16x16x32_bf16 v[100:103], v[208:211], v[180:183], v[100:103]
	v_mfma_f32_16x16x32_bf16 v[96:99], v[216:219], v[180:183], v[96:99]
	v_mfma_f32_16x16x32_bf16 v[84:87], v[208:211], v[188:191], v[84:87]
	v_mfma_f32_16x16x32_bf16 v[80:83], v[216:219], v[188:191], v[80:83]
	v_mfma_f32_16x16x32_bf16 v[68:71], v[208:211], v[196:199], v[68:71]
	v_mfma_f32_16x16x32_bf16 v[64:67], v[216:219], v[196:199], v[64:67]
	s_setprio 0
	s_mov_b32 m0, s38
	v_lshl_add_u64 v[220:221], s[34:35], 0, v[128:129]
	s_barrier
	ds_read_b128 v[168:171], v161 offset:16384
	ds_read_b128 v[172:175], v161 offset:17408
	ds_read_b128 v[176:179], v161 offset:18432
	ds_read_b128 v[180:183], v161 offset:19456
	ds_read_b128 v[184:187], v161 offset:20480
	ds_read_b128 v[188:191], v161 offset:21504
	ds_read_b128 v[192:195], v161 offset:22528
	ds_read_b128 v[196:199], v161 offset:23552
	global_load_lds_dwordx4 v[220:221], off
	v_lshl_add_u64 v[222:223], s[34:35], 0, v[130:131]
	s_mov_b32 m0, s39
	s_nop 0
	global_load_lds_dwordx4 v[222:223], off
	s_barrier
	s_waitcnt lgkmcnt(0)
	s_setprio 1
	s_waitcnt lgkmcnt(0)
	v_mfma_f32_16x16x32_bf16 v[60:63], v[140:143], v[168:171], v[60:63]
	v_mfma_f32_16x16x32_bf16 v[56:59], v[148:151], v[168:171], v[56:59]
	v_mfma_f32_16x16x32_bf16 v[44:47], v[140:143], v[176:179], v[44:47]
	v_mfma_f32_16x16x32_bf16 v[40:43], v[148:151], v[176:179], v[40:43]
	v_mfma_f32_16x16x32_bf16 v[28:31], v[140:143], v[184:187], v[28:31]
	v_mfma_f32_16x16x32_bf16 v[24:27], v[148:151], v[184:187], v[24:27]
	v_mfma_f32_16x16x32_bf16 v[16:19], v[140:143], v[192:195], v[16:19]
	v_mfma_f32_16x16x32_bf16 v[8:11], v[148:151], v[192:195], v[8:11]
	v_mfma_f32_16x16x32_bf16 v[60:63], v[144:147], v[172:175], v[60:63]
	v_mfma_f32_16x16x32_bf16 v[56:59], v[164:167], v[172:175], v[56:59]
	v_mfma_f32_16x16x32_bf16 v[44:47], v[144:147], v[180:183], v[44:47]
	v_mfma_f32_16x16x32_bf16 v[40:43], v[164:167], v[180:183], v[40:43]
	v_mfma_f32_16x16x32_bf16 v[28:31], v[144:147], v[188:191], v[28:31]
	v_mfma_f32_16x16x32_bf16 v[24:27], v[164:167], v[188:191], v[24:27]
	v_mfma_f32_16x16x32_bf16 v[16:19], v[144:147], v[196:199], v[16:19]
	v_mfma_f32_16x16x32_bf16 v[8:11], v[164:167], v[196:199], v[8:11]
	s_setprio 0
	s_barrier
; #define G_STAGE(bufoff, gbase, voff) do { _Pragma("unroll") for (int _i = 0; _i < 2; ++_i) \
;         __builtin_amdgcn_global_load_lds((const unsigned*)((const char*)(gbase) + (voff)[_i]), (LAS unsigned*)(lds + (bufoff) + ldsw + _i * 8192), 16, 0, 0); } while (0)
; #define G_LDA(dst, b, h) do { _Pragma("unroll") for (int m = 0; m < 4; ++m) _Pragma("unroll") for (int k = 0; k < 2; ++k) dst[m][k] = *(const LAS bf16x8*)(lds + G_SA(b, h) + aoff + m * 2048 + k * 1024); } while (0)
; #define G_LDB(dst, b, h) do { _Pragma("unroll") for (int n = 0; n < 2; ++n) _Pragma("unroll") for (int k = 0; k < 2; ++k) dst[n][k] = *(const LAS bf16x8*)(lds + G_SB(b, h) + boff + n * 2048 + k * 1024); } while (0)
; #define G_MMA(ai, bj, At, Bt_) do { __builtin_amdgcn_s_setprio(1); _Pragma("unroll") for (int m = 0; m < 4; ++m) _Pragma("unroll") for (int n = 0; n < 2; ++n) _Pragma("unroll") for (int k = 0; k < 2; ++k) \
;         acc[ai][bj][m][n] = __builtin_amdgcn_mfma_f32_16x16x32_bf16(Bt_[n][k], At[m][k], acc[ai][bj][m][n], 0, 0, 0); __builtin_amdgcn_s_setprio(0); } while (0)
; #define G_WAIT_V(n) asm volatile("s_waitcnt vmcnt(" #n ")" ::: "memory")
; #define G_WAIT_L(n) asm volatile("s_waitcnt lgkmcnt(" #n ")" ::: "memory")
; #define G_BAR __builtin_amdgcn_s_barrier()
; #define G_SCHED __builtin_amdgcn_sched_barrier(0)
; template <class Epi, bool PERMROWS = false>
; DI void gemm_phase(LAS unsigned char* lds, const bf16_t* A, int lda, const bf16_t* Bt, int K, const Sched& S, const Epi& E) {
;     ...
;             G_WAIT_V(6); G_BAR; G_MMA(1, 1, At, B1); G_BAR;
;             G_LDB(B0, 1, 0); G_SCHED; G_LDA(At, 1, 0); G_STAGE(G_SA(0, 1), a2 + hstepA, voffA);
;             G_WAIT_L(8); G_BAR; G_WAIT_L(0); G_MMA(0, 0, At, B0); G_BAR; G_SCHED;
;             G_LDB(B1, 1, 1); G_STAGE(G_SB(1, 0), b3, voffB);
;             G_BAR; G_WAIT_L(0); G_MMA(0, 1, At, B1); G_BAR;
;             G_LDA(At, 1, 1); G_STAGE(G_SA(1, 0), a3, voffA);
;             G_BAR; G_WAIT_L(0); G_MMA(1, 0, At, B0); G_BAR; G_SCHED;
	s_add_u32 s20, s30, 0x160000
	s_addc_u32 s21, s31, 0
	s_add_i32 s62, s53, s37
	v_lshl_add_u64 v[140:141], s[20:21], 0, v[128:129]
	s_mov_b32 m0, s62
	s_nop 0
	global_load_lds_dwordx4 v[140:141], off
	v_lshl_add_u64 v[140:141], s[20:21], 0, v[130:131]
	s_add_i32 m0, s62, 0x2000
	s_nop 0
	global_load_lds_dwordx4 v[140:141], off
	s_waitcnt vmcnt(6)
	s_barrier
	s_setprio 1
	v_mfma_f32_16x16x32_bf16 v[52:55], v[204:207], v[168:171], v[52:55]
	v_mfma_f32_16x16x32_bf16 v[48:51], v[212:215], v[168:171], v[48:51]
	v_mfma_f32_16x16x32_bf16 v[36:39], v[204:207], v[176:179], v[36:39]
	v_mfma_f32_16x16x32_bf16 v[32:35], v[212:215], v[176:179], v[32:35]
	v_mfma_f32_16x16x32_bf16 v[20:23], v[204:207], v[184:187], v[20:23]
	v_mfma_f32_16x16x32_bf16 v[12:15], v[212:215], v[184:187], v[12:15]
	v_mfma_f32_16x16x32_bf16 v[4:7], v[204:207], v[192:195], v[4:7]
	v_mfma_f32_16x16x32_bf16 v[0:3], v[212:215], v[192:195], v[0:3]
	v_mfma_f32_16x16x32_bf16 v[52:55], v[208:211], v[172:175], v[52:55]
	v_mfma_f32_16x16x32_bf16 v[48:51], v[216:219], v[172:175], v[48:51]
	v_mfma_f32_16x16x32_bf16 v[36:39], v[208:211], v[180:183], v[36:39]
	v_mfma_f32_16x16x32_bf16 v[32:35], v[216:219], v[180:183], v[32:35]
	v_mfma_f32_16x16x32_bf16 v[20:23], v[208:211], v[188:191], v[20:23]
	v_mfma_f32_16x16x32_bf16 v[12:15], v[216:219], v[188:191], v[12:15]
	v_mfma_f32_16x16x32_bf16 v[4:7], v[208:211], v[196:199], v[4:7]
	v_mfma_f32_16x16x32_bf16 v[0:3], v[216:219], v[196:199], v[0:3]
	s_setprio 0
	s_add_i32 s62, 0, 0x18000
	v_add_u32_e32 v163, s62, v155
	s_barrier
	ds_read_b128 v[140:143], v163
	ds_read_b128 v[144:147], v163 offset:1024
	ds_read_b128 v[148:151], v163 offset:2048
	ds_read_b128 v[164:167], v163 offset:3072
	s_add_u32 s20, s34, 0x160000
	s_addc_u32 s21, s35, 0
	s_mov_b32 m0, s40
	v_lshl_add_u64 v[204:205], s[20:21], 0, v[128:129]
	ds_read_b128 v[168:171], v161 offset:32768
	ds_read_b128 v[172:175], v161 offset:33792
	ds_read_b128 v[176:179], v161 offset:34816
	ds_read_b128 v[180:183], v161 offset:35840
	ds_read_b128 v[184:187], v161 offset:36864
	ds_read_b128 v[188:191], v161 offset:37888
	ds_read_b128 v[192:195], v161 offset:38912
	ds_read_b128 v[196:199], v161 offset:39936
	global_load_lds_dwordx4 v[204:205], off
	v_lshl_add_u64 v[204:205], s[20:21], 0, v[130:131]
	s_mov_b32 m0, s41
	s_nop 0
	global_load_lds_dwordx4 v[204:205], off
	s_waitcnt lgkmcnt(8)
	s_barrier
	s_waitcnt lgkmcnt(0)
	s_setprio 1
	s_waitcnt lgkmcnt(0)
	v_mfma_f32_16x16x32_bf16 v[124:127], v[140:143], v[168:171], v[124:127]
	v_mfma_f32_16x16x32_bf16 v[120:123], v[148:151], v[168:171], v[120:123]
	v_mfma_f32_16x16x32_bf16 v[108:111], v[140:143], v[176:179], v[108:111]
	v_mfma_f32_16x16x32_bf16 v[104:107], v[148:151], v[176:179], v[104:107]
	v_mfma_f32_16x16x32_bf16 v[92:95], v[140:143], v[184:187], v[92:95]
	v_mfma_f32_16x16x32_bf16 v[88:91], v[148:151], v[184:187], v[88:91]
	v_mfma_f32_16x16x32_bf16 v[76:79], v[140:143], v[192:195], v[76:79]
	v_mfma_f32_16x16x32_bf16 v[72:75], v[148:151], v[192:195], v[72:75]
	v_mfma_f32_16x16x32_bf16 v[124:127], v[144:147], v[172:175], v[124:127]
	v_mfma_f32_16x16x32_bf16 v[120:123], v[164:167], v[172:175], v[120:123]
	v_mfma_f32_16x16x32_bf16 v[108:111], v[144:147], v[180:183], v[108:111]
	v_mfma_f32_16x16x32_bf16 v[104:107], v[164:167], v[180:183], v[104:107]
	v_mfma_f32_16x16x32_bf16 v[92:95], v[144:147], v[188:191], v[92:95]
	v_mfma_f32_16x16x32_bf16 v[88:91], v[164:167], v[188:191], v[88:91]
	v_mfma_f32_16x16x32_bf16 v[76:79], v[144:147], v[196:199], v[76:79]
	v_mfma_f32_16x16x32_bf16 v[72:75], v[164:167], v[196:199], v[72:75]
	s_setprio 0
	s_barrier
	s_add_i32 s34, 0, 0x1c000
	s_add_i32 s20, s62, s37
	v_add_u32_e32 v163, s34, v155
	v_lshl_add_u64 v[152:153], v[152:153], 0, s[10:11]
	s_mov_b32 m0, s20
	ds_read_b128 v[204:207], v163
	ds_read_b128 v[208:211], v163 offset:1024
	ds_read_b128 v[212:215], v163 offset:2048
	ds_read_b128 v[216:219], v163 offset:3072
	global_load_lds_dwordx4 v[152:153], off
	v_lshl_add_u64 v[152:153], v[200:201], 0, s[10:11]
	s_add_i32 m0, s20, 0x2000
	s_nop 0
	global_load_lds_dwordx4 v[152:153], off
	s_barrier
	s_waitcnt lgkmcnt(0)
	s_setprio 1
	s_waitcnt lgkmcnt(0)
	v_mfma_f32_16x16x32_bf16 v[116:119], v[204:207], v[168:171], v[116:119]
	v_mfma_f32_16x16x32_bf16 v[112:115], v[212:215], v[168:171], v[112:115]
	v_mfma_f32_16x16x32_bf16 v[100:103], v[204:207], v[176:179], v[100:103]
	v_mfma_f32_16x16x32_bf16 v[96:99], v[212:215], v[176:179], v[96:99]
	v_mfma_f32_16x16x32_bf16 v[84:87], v[204:207], v[184:187], v[84:87]
	v_mfma_f32_16x16x32_bf16 v[80:83], v[212:215], v[184:187], v[80:83]
	v_mfma_f32_16x16x32_bf16 v[68:71], v[204:207], v[192:195], v[68:71]
	v_mfma_f32_16x16x32_bf16 v[64:67], v[212:215], v[192:195], v[64:67]
	v_mfma_f32_16x16x32_bf16 v[116:119], v[208:211], v[172:175], v[116:119]
	v_mfma_f32_16x16x32_bf16 v[112:115], v[216:219], v[172:175], v[112:115]
	v_mfma_f32_16x16x32_bf16 v[100:103], v[208:211], v[180:183], v[100:103]
	v_mfma_f32_16x16x32_bf16 v[96:99], v[216:219], v[180:183], v[96:99]
	v_mfma_f32_16x16x32_bf16 v[84:87], v[208:211], v[188:191], v[84:87]
	v_mfma_f32_16x16x32_bf16 v[80:83], v[216:219], v[188:191], v[80:83]
	v_mfma_f32_16x16x32_bf16 v[68:71], v[208:211], v[196:199], v[68:71]
	v_mfma_f32_16x16x32_bf16 v[64:67], v[216:219], v[196:199], v[64:67]
	s_setprio 0
	s_mov_b32 m0, s55
	v_lshl_add_u64 v[152:153], v[220:221], 0, s[10:11]
	s_barrier
	ds_read_b128 v[168:171], v161 offset:49152
	ds_read_b128 v[172:175], v161 offset:50176
	ds_read_b128 v[176:179], v161 offset:51200
	ds_read_b128 v[180:183], v161 offset:52224
	ds_read_b128 v[184:187], v161 offset:53248
	ds_read_b128 v[188:191], v161 offset:54272
	ds_read_b128 v[192:195], v161 offset:55296
	ds_read_b128 v[196:199], v161 offset:56320
	global_load_lds_dwordx4 v[152:153], off
	v_lshl_add_u64 v[152:153], v[222:223], 0, s[10:11]
	s_mov_b32 m0, s56
	s_nop 0
	global_load_lds_dwordx4 v[152:153], off
	s_barrier
; #define G_STAGE(bufoff, gbase, voff) do { _Pragma("unroll") for (int _i = 0; _i < 2; ++_i) \
;         __builtin_amdgcn_global_load_lds((const unsigned*)((const char*)(gbase) + (voff)[_i]), (LAS unsigned*)(lds + (bufoff) + ldsw + _i * 8192), 16, 0, 0); } while (0)
; #define G_MMA(ai, bj, At, Bt_) do { __builtin_amdgcn_s_setprio(1); _Pragma("unroll") for (int m = 0; m < 4; ++m) _Pragma("unroll") for (int n = 0; n < 2; ++n) _Pragma("unroll") for (int k = 0; k < 2; ++k) \
;         acc[ai][bj][m][n] = __builtin_amdgcn_mfma_f32_16x16x32_bf16(Bt_[n][k], At[m][k], acc[ai][bj][m][n], 0, 0, 0); __builtin_amdgcn_s_setprio(0); } while (0)
; #define G_WAIT_V(n) asm volatile("s_waitcnt vmcnt(" #n ")" ::: "memory")
; #define G_WAIT_L(n) asm volatile("s_waitcnt lgkmcnt(" #n ")" ::: "memory")
; #define G_BAR __builtin_amdgcn_s_barrier()
; #define G_SCHED __builtin_amdgcn_sched_barrier(0)
; template <class Epi, bool PERMROWS = false>
; DI void gemm_phase(LAS unsigned char* lds, const bf16_t* A, int lda, const bf16_t* Bt, int K, const Sched& S, const Epi& E) {
;     ...
;             G_BAR; G_WAIT_L(0); G_MMA(1, 0, At, B0); G_BAR; G_SCHED;
;             G_STAGE(G_SB(1, 1), b3 + hstepB, voffB);
;             G_WAIT_V(6); G_BAR; G_MMA(1, 1, At, B1); G_BAR;
;     DI void operator()(const f32x4 (&acc)[2][2][4][2], const Unit& u, int wr, int wc, int fr, int fq) const {
;     ...
;         const float* g = gate + (size_t)s * 12288;
;         const float2* RS = (const float2*)(ws + WS_RSTAT);
; #pragma unroll
;         for (int ai = 0; ai < 2; ++ai)
; #pragma unroll
;             for (int m = 0; m < 4; ++m) {
;                 const int row = u.pm * BM + ai * HALF + wr * 64 + m * 16 + fr;
;                 float mu = 0.f, rs = 1.f;
;                 if (pg) { const float2 st = RS[row]; mu = st.x; rs = st.y; }
; #pragma unroll
;                 for (int bj = 0; bj < 2; ++bj)
; #pragma unroll
;                     for (int n = 0; n < 2; ++n) {
;                         const int col = u.pn * BM + bj * HALF + wc * 32 + n * 16 + 4 * fq;
;                         float* xp = X + (size_t)row * DM + col;
;                         f32x4 x4 = *(const f32x4*)xp; const f32x4 g4 = *(const f32x4*)(g + col);
	s_waitcnt lgkmcnt(0)
	s_setprio 1
	s_waitcnt lgkmcnt(0)
	v_mfma_f32_16x16x32_bf16 v[60:63], v[140:143], v[168:171], v[60:63]
	v_mfma_f32_16x16x32_bf16 v[56:59], v[148:151], v[168:171], v[56:59]
	v_mfma_f32_16x16x32_bf16 v[44:47], v[140:143], v[176:179], v[44:47]
	v_mfma_f32_16x16x32_bf16 v[40:43], v[148:151], v[176:179], v[40:43]
	v_mfma_f32_16x16x32_bf16 v[28:31], v[140:143], v[184:187], v[28:31]
	v_mfma_f32_16x16x32_bf16 v[24:27], v[148:151], v[184:187], v[24:27]
	v_mfma_f32_16x16x32_bf16 v[16:19], v[140:143], v[192:195], v[16:19]
	v_mfma_f32_16x16x32_bf16 v[8:11], v[148:151], v[192:195], v[8:11]
	v_mfma_f32_16x16x32_bf16 v[60:63], v[144:147], v[172:175], v[60:63]
	v_mfma_f32_16x16x32_bf16 v[56:59], v[164:167], v[172:175], v[56:59]
	v_mfma_f32_16x16x32_bf16 v[44:47], v[144:147], v[180:183], v[44:47]
	v_mfma_f32_16x16x32_bf16 v[40:43], v[164:167], v[180:183], v[40:43]
	v_mfma_f32_16x16x32_bf16 v[28:31], v[144:147], v[188:191], v[28:31]
	v_mfma_f32_16x16x32_bf16 v[24:27], v[164:167], v[188:191], v[24:27]
	v_mfma_f32_16x16x32_bf16 v[16:19], v[144:147], v[196:199], v[16:19]
	v_mfma_f32_16x16x32_bf16 v[8:11], v[164:167], v[196:199], v[8:11]
	s_setprio 0
	s_barrier
	s_add_u32 s20, s30, 0x160080
	s_addc_u32 s21, s31, 0
	s_add_i32 s30, s34, s37
	v_lshl_add_u64 v[140:141], s[20:21], 0, v[128:129]
	s_mov_b32 m0, s30
	s_nop 0
	global_load_lds_dwordx4 v[140:141], off
	v_lshl_add_u64 v[140:141], s[20:21], 0, v[130:131]
	s_add_i32 m0, s30, 0x2000
	s_nop 0
	global_load_lds_dwordx4 v[140:141], off
	s_waitcnt vmcnt(6)
	s_barrier
	s_setprio 1
	v_mfma_f32_16x16x32_bf16 v[52:55], v[204:207], v[168:171], v[52:55]
	v_mfma_f32_16x16x32_bf16 v[48:51], v[212:215], v[168:171], v[48:51]
	v_mfma_f32_16x16x32_bf16 v[36:39], v[204:207], v[176:179], v[36:39]
	v_mfma_f32_16x16x32_bf16 v[32:35], v[212:215], v[176:179], v[32:35]
	v_mfma_f32_16x16x32_bf16 v[20:23], v[204:207], v[184:187], v[20:23]
	v_mfma_f32_16x16x32_bf16 v[12:15], v[212:215], v[184:187], v[12:15]
	v_mfma_f32_16x16x32_bf16 v[4:7], v[204:207], v[192:195], v[4:7]
	v_mfma_f32_16x16x32_bf16 v[0:3], v[212:215], v[192:195], v[0:3]
	v_mfma_f32_16x16x32_bf16 v[52:55], v[208:211], v[172:175], v[52:55]
	v_mfma_f32_16x16x32_bf16 v[48:51], v[216:219], v[172:175], v[48:51]
	v_mfma_f32_16x16x32_bf16 v[36:39], v[208:211], v[180:183], v[36:39]
	v_mfma_f32_16x16x32_bf16 v[32:35], v[216:219], v[180:183], v[32:35]
	v_mfma_f32_16x16x32_bf16 v[20:23], v[208:211], v[188:191], v[20:23]
	v_mfma_f32_16x16x32_bf16 v[12:15], v[216:219], v[188:191], v[12:15]
	v_mfma_f32_16x16x32_bf16 v[4:7], v[208:211], v[196:199], v[4:7]
	v_mfma_f32_16x16x32_bf16 v[0:3], v[216:219], v[196:199], v[0:3]
	s_setprio 0
	s_add_i32 s29, s29, 2
	s_add_u32 s61, s61, 0x100
	s_addc_u32 s28, s28, 0
	s_cmpk_gt_u32 s29, 0x55
	s_mov_b64 s[20:21], s[22:23]
	s_barrier
	s_cbranch_scc0 .LBB0_3113
	v_and_b32_e32 v175, 15, v202
	v_bfe_u32 v176, v202, 8, 1
	v_lshl_add_u32 v175, v176, 6, v175
	v_lshlrev_b32_e32 v166, 3, v175
	v_bfe_u32 v176, v202, 6, 2
	v_lshlrev_b32_e32 v163, 7, v176
	v_bfe_u32 v176, v202, 4, 2
	v_lshl_add_u32 v163, v176, 4, v163
	s_lshl_b32 s29, s60, 10
	v_add_u32_e32 v163, s29, v163
	v_lshl_add_u32 v167, v175, 13, v163
	v_add_u32_e32 v168, 0x20000, v167
	v_add_u32_e32 v169, 0x40000, v167
	v_add_u32_e32 v170, 0x60000, v167
	v_add_u32_e32 v171, 0x100000, v167
	v_add_u32_e32 v172, 0x120000, v167
	v_add_u32_e32 v173, 0x140000, v167
	v_add_u32_e32 v174, 0x160000, v167
	s_mov_b32 s89, 0x3fb504f3
	s_mul_i32 s29, s59, 57
	s_lshr_b32 s29, s29, 9
	s_mul_i32 s32, s29, 9
	s_cmp_lg_u32 s32, s59
	s_cselect_b32 s28, s29, 4
	s_mul_i32 s28, s28, 0xc000
	s_add_u32 s74, s50, 0x4e000
	s_addc_u32 s75, s51, 0
	s_add_u32 s74, s74, s28
	s_addc_u32 s75, s75, 0
	global_load_dwordx4 v[220:223], v163, s[74:75] offset:0
	global_load_dwordx4 v[224:227], v163, s[74:75] offset:64
	global_load_dwordx4 v[228:231], v163, s[74:75] offset:512
	global_load_dwordx4 v[232:235], v163, s[74:75] offset:576
	s_add_u32 s74, s64, 0x2000
	s_addc_u32 s75, s65, 0
	global_load_dwordx4 v[204:207], v163, s[74:75] offset:0
	global_load_dwordx4 v[208:211], v163, s[74:75] offset:64
	global_load_dwordx4 v[212:215], v163, s[74:75] offset:512
	global_load_dwordx4 v[216:219], v163, s[74:75] offset:576
	s_add_u32 s74, s66, 0x2000
	s_addc_u32 s75, s67, 0
	global_load_dwordx4 v[236:239], v163, s[74:75] offset:0
	global_load_dwordx4 v[240:243], v163, s[74:75] offset:64
	global_load_dwordx4 v[244:247], v163, s[74:75] offset:512
	global_load_dwordx4 v[248:251], v163, s[74:75] offset:576
	s_lshl_b32 s29, s59, 11
	s_add_u32 s74, s50, 0x260a0000
	s_addc_u32 s75, s51, 0
	s_add_u32 s74, s74, s29
	s_addc_u32 s75, s75, 0
	global_load_dwordx2 v[140:141], v166, s[74:75] offset:0
	global_load_dwordx2 v[142:143], v166, s[74:75] offset:128
	global_load_dwordx2 v[144:145], v166, s[74:75] offset:256
	global_load_dwordx2 v[146:147], v166, s[74:75] offset:384
	global_load_dwordx2 v[148:149], v166, s[74:75] offset:1024
	global_load_dwordx2 v[150:151], v166, s[74:75] offset:1152
	global_load_dwordx2 v[152:153], v166, s[74:75] offset:1280
	global_load_dwordx2 v[164:165], v166, s[74:75] offset:1408
	s_lshl_b32 s29, s59, 21
	s_add_u32 s72, s50, 0xcba0000
	s_addc_u32 s73, s51, 0
	s_add_u32 s72, s72, s29
	s_addc_u32 s73, s73, 0
	s_waitcnt vmcnt(0)
;     DI void operator()(const f32x4 (&acc)[2][2][4][2], const Unit& u, int wr, int wc, int fr, int fq) const {
;     ...
;                 const int row = u.pm * BM + ai * HALF + wr * 64 + m * 16 + fr;
;                 float mu = 0.f, rs = 1.f;
;                 if (pg) { const float2 st = RS[row]; mu = st.x; rs = st.y; }
; #pragma unroll
;                 for (int bj = 0; bj < 2; ++bj)
; #pragma unroll
;                     for (int n = 0; n < 2; ++n) {
;                         const int col = u.pn * BM + bj * HALF + wc * 32 + n * 16 + 4 * fq;
;                         float* xp = X + (size_t)row * DM + col;
;                         f32x4 x4 = *(const f32x4*)xp; const f32x4 g4 = *(const f32x4*)(g + col);
;                         if (pg) x4 = (x4 - mu) * rs * *(const f32x4*)(pg + col) + *(const f32x4*)(pb + col);
;                         *(f32x4*)xp = x4 * ALPHA + g4 * acc[ai][bj][m][n];
	v_mul_f32_e32 v204, s89, v204
	v_mul_f32_e32 v236, s89, v236
	v_mul_f32_e32 v205, s89, v205
	v_mul_f32_e32 v237, s89, v237
	v_mul_f32_e32 v206, s89, v206
	v_mul_f32_e32 v238, s89, v238
	v_mul_f32_e32 v207, s89, v207
	v_mul_f32_e32 v239, s89, v239
	v_mul_f32_e32 v208, s89, v208
	v_mul_f32_e32 v240, s89, v240
	v_mul_f32_e32 v209, s89, v209
	v_mul_f32_e32 v241, s89, v241
	v_mul_f32_e32 v210, s89, v210
	v_mul_f32_e32 v242, s89, v242
	v_mul_f32_e32 v211, s89, v211
	v_mul_f32_e32 v243, s89, v243
	v_mul_f32_e32 v212, s89, v212
	v_mul_f32_e32 v244, s89, v244
	v_mul_f32_e32 v213, s89, v213
	v_mul_f32_e32 v245, s89, v245
	v_mul_f32_e32 v214, s89, v214
	v_mul_f32_e32 v246, s89, v246
	v_mul_f32_e32 v215, s89, v215
	v_mul_f32_e32 v247, s89, v247
	v_mul_f32_e32 v216, s89, v216
	v_mul_f32_e32 v248, s89, v248
	v_mul_f32_e32 v217, s89, v217
	v_mul_f32_e32 v249, s89, v249
	v_mul_f32_e32 v218, s89, v218
	v_mul_f32_e32 v250, s89, v250
	v_mul_f32_e32 v219, s89, v219
	v_mul_f32_e32 v251, s89, v251
	v_fma_f32 v124, v220, v124, v236
	v_fma_f32 v125, v221, v125, v237
	v_fma_f32 v126, v222, v126, v238
	v_fma_f32 v127, v223, v127, v239
	v_fma_f32 v120, v224, v120, v240
	v_fma_f32 v121, v225, v121, v241
	v_fma_f32 v122, v226, v122, v242
	v_fma_f32 v123, v227, v123, v243
	v_fma_f32 v116, v228, v116, v244
	v_fma_f32 v117, v229, v117, v245
	v_fma_f32 v118, v230, v118, v246
	v_fma_f32 v119, v231, v119, v247
	v_fma_f32 v112, v232, v112, v248
	v_fma_f32 v113, v233, v113, v249
	v_fma_f32 v114, v234, v114, v250
	v_fma_f32 v115, v235, v115, v251
	v_fma_f32 v108, v220, v108, v236
	v_fma_f32 v109, v221, v109, v237
	v_fma_f32 v110, v222, v110, v238
	v_fma_f32 v111, v223, v111, v239
	v_fma_f32 v104, v224, v104, v240
	v_fma_f32 v105, v225, v105, v241
	v_fma_f32 v106, v226, v106, v242
	v_fma_f32 v107, v227, v107, v243
	v_fma_f32 v100, v228, v100, v244
	v_fma_f32 v101, v229, v101, v245
	v_fma_f32 v102, v230, v102, v246
	v_fma_f32 v103, v231, v103, v247
	v_fma_f32 v96, v232, v96, v248
	v_fma_f32 v97, v233, v97, v249
	v_fma_f32 v98, v234, v98, v250
	v_fma_f32 v99, v235, v99, v251
	v_fma_f32 v92, v220, v92, v236
	v_fma_f32 v93, v221, v93, v237
	v_fma_f32 v94, v222, v94, v238
	v_fma_f32 v95, v223, v95, v239
	v_fma_f32 v88, v224, v88, v240
	v_fma_f32 v89, v225, v89, v241
	v_fma_f32 v90, v226, v90, v242
	v_fma_f32 v91, v227, v91, v243
	v_fma_f32 v84, v228, v84, v244
	v_fma_f32 v85, v229, v85, v245
	v_fma_f32 v86, v230, v86, v246
	v_fma_f32 v87, v231, v87, v247
	v_fma_f32 v80, v232, v80, v248
	v_fma_f32 v81, v233, v81, v249
	v_fma_f32 v82, v234, v82, v250
	v_fma_f32 v83, v235, v83, v251
	v_fma_f32 v76, v220, v76, v236
	v_fma_f32 v77, v221, v77, v237
	v_fma_f32 v78, v222, v78, v238
	v_fma_f32 v79, v223, v79, v239
	v_fma_f32 v72, v224, v72, v240
	v_fma_f32 v73, v225, v73, v241
	v_fma_f32 v74, v226, v74, v242
	v_fma_f32 v75, v227, v75, v243
	v_fma_f32 v68, v228, v68, v244
	v_fma_f32 v69, v229, v69, v245
	v_fma_f32 v70, v230, v70, v246
	v_fma_f32 v71, v231, v71, v247
	v_fma_f32 v64, v232, v64, v248
	v_fma_f32 v65, v233, v65, v249
	v_fma_f32 v66, v234, v66, v250
	v_fma_f32 v67, v235, v67, v251
	v_fma_f32 v60, v220, v60, v236
	v_fma_f32 v61, v221, v61, v237
	v_fma_f32 v62, v222, v62, v238
	v_fma_f32 v63, v223, v63, v239
	v_fma_f32 v56, v224, v56, v240
	v_fma_f32 v57, v225, v57, v241
	v_fma_f32 v58, v226, v58, v242
	v_fma_f32 v59, v227, v59, v243
	v_fma_f32 v52, v228, v52, v244
	v_fma_f32 v53, v229, v53, v245
	v_fma_f32 v54, v230, v54, v246
	v_fma_f32 v55, v231, v55, v247
	v_fma_f32 v48, v232, v48, v248
	v_fma_f32 v49, v233, v49, v249
	v_fma_f32 v50, v234, v50, v250
	v_fma_f32 v51, v235, v51, v251
	v_fma_f32 v44, v220, v44, v236
	v_fma_f32 v45, v221, v45, v237
	v_fma_f32 v46, v222, v46, v238
	v_fma_f32 v47, v223, v47, v239
	v_fma_f32 v40, v224, v40, v240
	v_fma_f32 v41, v225, v41, v241
	v_fma_f32 v42, v226, v42, v242
	v_fma_f32 v43, v227, v43, v243
	v_fma_f32 v36, v228, v36, v244
	v_fma_f32 v37, v229, v37, v245
	v_fma_f32 v38, v230, v38, v246
	v_fma_f32 v39, v231, v39, v247
	v_fma_f32 v32, v232, v32, v248
	v_fma_f32 v33, v233, v33, v249
	v_fma_f32 v34, v234, v34, v250
	v_fma_f32 v35, v235, v35, v251
	v_fma_f32 v28, v220, v28, v236
	v_fma_f32 v29, v221, v29, v237
	v_fma_f32 v30, v222, v30, v238
	v_fma_f32 v31, v223, v31, v239
	v_fma_f32 v24, v224, v24, v240
	v_fma_f32 v25, v225, v25, v241
	v_fma_f32 v26, v226, v26, v242
	v_fma_f32 v27, v227, v27, v243
	v_fma_f32 v20, v228, v20, v244
	v_fma_f32 v21, v229, v21, v245
	v_fma_f32 v22, v230, v22, v246
	v_fma_f32 v23, v231, v23, v247
	v_fma_f32 v12, v232, v12, v248
	v_fma_f32 v13, v233, v13, v249
	v_fma_f32 v14, v234, v14, v250
	v_fma_f32 v15, v235, v15, v251
	v_fma_f32 v16, v220, v16, v236
	v_fma_f32 v17, v221, v17, v237
	v_fma_f32 v18, v222, v18, v238
	v_fma_f32 v19, v223, v19, v239
	v_fma_f32 v8, v224, v8, v240
	v_fma_f32 v9, v225, v9, v241
	v_fma_f32 v10, v226, v10, v242
	v_fma_f32 v11, v227, v11, v243
	v_fma_f32 v4, v228, v4, v244
	v_fma_f32 v5, v229, v5, v245
	v_fma_f32 v6, v230, v6, v246
	v_fma_f32 v7, v231, v7, v247
	v_fma_f32 v0, v232, v0, v248
	v_fma_f32 v1, v233, v1, v249
	v_fma_f32 v2, v234, v2, v250
	v_fma_f32 v3, v235, v3, v251
	global_load_dwordx4 v[220:223], v167, s[72:73] offset:0 nt
	global_load_dwordx4 v[224:227], v167, s[72:73] offset:64 nt
	global_load_dwordx4 v[228:231], v167, s[72:73] offset:512 nt
	global_load_dwordx4 v[232:235], v167, s[72:73] offset:576 nt
	global_load_dwordx4 v[236:239], v168, s[72:73] offset:0 nt
	global_load_dwordx4 v[240:243], v168, s[72:73] offset:64 nt
	global_load_dwordx4 v[244:247], v168, s[72:73] offset:512 nt
	global_load_dwordx4 v[248:251], v168, s[72:73] offset:576 nt
	s_waitcnt vmcnt(0)
;     DI void operator()(const f32x4 (&acc)[2][2][4][2], const Unit& u, int wr, int wc, int fr, int fq) const {
;     ...
;         for (int ai = 0; ai < 2; ++ai)
; #pragma unroll
;             for (int m = 0; m < 4; ++m) {
;                 const int row = u.pm * BM + ai * HALF + wr * 64 + m * 16 + fr;
;                 float mu = 0.f, rs = 1.f;
;                 if (pg) { const float2 st = RS[row]; mu = st.x; rs = st.y; }
; #pragma unroll
;                 for (int bj = 0; bj < 2; ++bj)
; #pragma unroll
;                     for (int n = 0; n < 2; ++n) {
;                         const int col = u.pn * BM + bj * HALF + wc * 32 + n * 16 + 4 * fq;
;                         float* xp = X + (size_t)row * DM + col;
;                         f32x4 x4 = *(const f32x4*)xp; const f32x4 g4 = *(const f32x4*)(g + col);
;                         if (pg) x4 = (x4 - mu) * rs * *(const f32x4*)(pg + col) + *(const f32x4*)(pb + col);
;                         *(f32x4*)xp = x4 * ALPHA + g4 * acc[ai][bj][m][n];
;                     }
	v_sub_f32_e32 v220, v220, v140
	v_mul_f32_e32 v220, v220, v141
	v_fma_f32 v220, v220, v204, v124
	v_sub_f32_e32 v221, v221, v140
	v_mul_f32_e32 v221, v221, v141
	v_fma_f32 v221, v221, v205, v125
	v_sub_f32_e32 v222, v222, v140
	v_mul_f32_e32 v222, v222, v141
	v_fma_f32 v222, v222, v206, v126
	v_sub_f32_e32 v223, v223, v140
	v_mul_f32_e32 v223, v223, v141
	v_fma_f32 v223, v223, v207, v127
	v_sub_f32_e32 v224, v224, v140
	v_mul_f32_e32 v224, v224, v141
	v_fma_f32 v224, v224, v208, v120
	v_sub_f32_e32 v225, v225, v140
	v_mul_f32_e32 v225, v225, v141
	v_fma_f32 v225, v225, v209, v121
	v_sub_f32_e32 v226, v226, v140
	v_mul_f32_e32 v226, v226, v141
	v_fma_f32 v226, v226, v210, v122
	v_sub_f32_e32 v227, v227, v140
	v_mul_f32_e32 v227, v227, v141
	v_fma_f32 v227, v227, v211, v123
	v_sub_f32_e32 v228, v228, v140
	v_mul_f32_e32 v228, v228, v141
	v_fma_f32 v228, v228, v212, v116
	v_sub_f32_e32 v229, v229, v140
	v_mul_f32_e32 v229, v229, v141
	v_fma_f32 v229, v229, v213, v117
	v_sub_f32_e32 v230, v230, v140
	v_mul_f32_e32 v230, v230, v141
	v_fma_f32 v230, v230, v214, v118
	v_sub_f32_e32 v231, v231, v140
	v_mul_f32_e32 v231, v231, v141
	v_fma_f32 v231, v231, v215, v119
	v_sub_f32_e32 v232, v232, v140
	v_mul_f32_e32 v232, v232, v141
	v_fma_f32 v232, v232, v216, v112
	v_sub_f32_e32 v233, v233, v140
	v_mul_f32_e32 v233, v233, v141
	v_fma_f32 v233, v233, v217, v113
	v_sub_f32_e32 v234, v234, v140
	v_mul_f32_e32 v234, v234, v141
	v_fma_f32 v234, v234, v218, v114
	v_sub_f32_e32 v235, v235, v140
	v_mul_f32_e32 v235, v235, v141
	v_fma_f32 v235, v235, v219, v115
	v_sub_f32_e32 v236, v236, v142
	v_mul_f32_e32 v236, v236, v143
	v_fma_f32 v236, v236, v204, v108
	v_sub_f32_e32 v237, v237, v142
	v_mul_f32_e32 v237, v237, v143
	v_fma_f32 v237, v237, v205, v109
	v_sub_f32_e32 v238, v238, v142
	v_mul_f32_e32 v238, v238, v143
	v_fma_f32 v238, v238, v206, v110
	v_sub_f32_e32 v239, v239, v142
	v_mul_f32_e32 v239, v239, v143
	v_fma_f32 v239, v239, v207, v111
	v_sub_f32_e32 v240, v240, v142
	v_mul_f32_e32 v240, v240, v143
	v_fma_f32 v240, v240, v208, v104
	v_sub_f32_e32 v241, v241, v142
	v_mul_f32_e32 v241, v241, v143
	v_fma_f32 v241, v241, v209, v105
	v_sub_f32_e32 v242, v242, v142
	v_mul_f32_e32 v242, v242, v143
	v_fma_f32 v242, v242, v210, v106
	v_sub_f32_e32 v243, v243, v142
	v_mul_f32_e32 v243, v243, v143
	v_fma_f32 v243, v243, v211, v107
	v_sub_f32_e32 v244, v244, v142
	v_mul_f32_e32 v244, v244, v143
	v_fma_f32 v244, v244, v212, v100
	v_sub_f32_e32 v245, v245, v142
	v_mul_f32_e32 v245, v245, v143
	v_fma_f32 v245, v245, v213, v101
	v_sub_f32_e32 v246, v246, v142
	v_mul_f32_e32 v246, v246, v143
	v_fma_f32 v246, v246, v214, v102
	v_sub_f32_e32 v247, v247, v142
	v_mul_f32_e32 v247, v247, v143
	v_fma_f32 v247, v247, v215, v103
	v_sub_f32_e32 v248, v248, v142
	v_mul_f32_e32 v248, v248, v143
	v_fma_f32 v248, v248, v216, v96
	v_sub_f32_e32 v249, v249, v142
	v_mul_f32_e32 v249, v249, v143
	v_fma_f32 v249, v249, v217, v97
	v_sub_f32_e32 v250, v250, v142
	v_mul_f32_e32 v250, v250, v143
	v_fma_f32 v250, v250, v218, v98
	v_sub_f32_e32 v251, v251, v142
	v_mul_f32_e32 v251, v251, v143
	v_fma_f32 v251, v251, v219, v99
	global_load_dwordx4 v[124:127], v169, s[72:73] offset:0 nt
	global_load_dwordx4 v[120:123], v169, s[72:73] offset:64 nt
	global_load_dwordx4 v[116:119], v169, s[72:73] offset:512 nt
	global_load_dwordx4 v[112:115], v169, s[72:73] offset:576 nt
	global_load_dwordx4 v[108:111], v170, s[72:73] offset:0 nt
	global_load_dwordx4 v[104:107], v170, s[72:73] offset:64 nt
	global_load_dwordx4 v[100:103], v170, s[72:73] offset:512 nt
	global_load_dwordx4 v[96:99], v170, s[72:73] offset:576 nt
	global_store_dwordx4 v167, v[220:223], s[72:73] offset:0
	global_store_dwordx4 v167, v[224:227], s[72:73] offset:64
	global_store_dwordx4 v167, v[228:231], s[72:73] offset:512
	global_store_dwordx4 v167, v[232:235], s[72:73] offset:576
	global_store_dwordx4 v168, v[236:239], s[72:73] offset:0
	global_store_dwordx4 v168, v[240:243], s[72:73] offset:64
	global_store_dwordx4 v168, v[244:247], s[72:73] offset:512
	global_store_dwordx4 v168, v[248:251], s[72:73] offset:576
	global_load_dwordx4 v[220:223], v171, s[72:73] offset:0 nt
	global_load_dwordx4 v[224:227], v171, s[72:73] offset:64 nt
	global_load_dwordx4 v[228:231], v171, s[72:73] offset:512 nt
	global_load_dwordx4 v[232:235], v171, s[72:73] offset:576 nt
	global_load_dwordx4 v[236:239], v172, s[72:73] offset:0 nt
	global_load_dwordx4 v[240:243], v172, s[72:73] offset:64 nt
	global_load_dwordx4 v[244:247], v172, s[72:73] offset:512 nt
	global_load_dwordx4 v[248:251], v172, s[72:73] offset:576 nt
	s_waitcnt vmcnt(0)
;     DI void operator()(const f32x4 (&acc)[2][2][4][2], const Unit& u, int wr, int wc, int fr, int fq) const {
;     ...
;                 for (int bj = 0; bj < 2; ++bj)
; #pragma unroll
;                     for (int n = 0; n < 2; ++n) {
;                         const int col = u.pn * BM + bj * HALF + wc * 32 + n * 16 + 4 * fq;
;                         float* xp = X + (size_t)row * DM + col;
;                         f32x4 x4 = *(const f32x4*)xp; const f32x4 g4 = *(const f32x4*)(g + col);
;                         if (pg) x4 = (x4 - mu) * rs * *(const f32x4*)(pg + col) + *(const f32x4*)(pb + col);
;                         *(f32x4*)xp = x4 * ALPHA + g4 * acc[ai][bj][m][n];
;                     }
	v_sub_f32_e32 v124, v124, v144
	v_mul_f32_e32 v124, v124, v145
	v_fma_f32 v124, v124, v204, v92
	v_sub_f32_e32 v125, v125, v144
	v_mul_f32_e32 v125, v125, v145
	v_fma_f32 v125, v125, v205, v93
	v_sub_f32_e32 v126, v126, v144
	v_mul_f32_e32 v126, v126, v145
	v_fma_f32 v126, v126, v206, v94
	v_sub_f32_e32 v127, v127, v144
	v_mul_f32_e32 v127, v127, v145
	v_fma_f32 v127, v127, v207, v95
	v_sub_f32_e32 v120, v120, v144
	v_mul_f32_e32 v120, v120, v145
	v_fma_f32 v120, v120, v208, v88
	v_sub_f32_e32 v121, v121, v144
	v_mul_f32_e32 v121, v121, v145
	v_fma_f32 v121, v121, v209, v89
	v_sub_f32_e32 v122, v122, v144
	v_mul_f32_e32 v122, v122, v145
	v_fma_f32 v122, v122, v210, v90
	v_sub_f32_e32 v123, v123, v144
	v_mul_f32_e32 v123, v123, v145
	v_fma_f32 v123, v123, v211, v91
	v_sub_f32_e32 v116, v116, v144
	v_mul_f32_e32 v116, v116, v145
	v_fma_f32 v116, v116, v212, v84
	v_sub_f32_e32 v117, v117, v144
	v_mul_f32_e32 v117, v117, v145
	v_fma_f32 v117, v117, v213, v85
	v_sub_f32_e32 v118, v118, v144
	v_mul_f32_e32 v118, v118, v145
	v_fma_f32 v118, v118, v214, v86
	v_sub_f32_e32 v119, v119, v144
	v_mul_f32_e32 v119, v119, v145
	v_fma_f32 v119, v119, v215, v87
	v_sub_f32_e32 v112, v112, v144
	v_mul_f32_e32 v112, v112, v145
	v_fma_f32 v112, v112, v216, v80
	v_sub_f32_e32 v113, v113, v144
	v_mul_f32_e32 v113, v113, v145
	v_fma_f32 v113, v113, v217, v81
	v_sub_f32_e32 v114, v114, v144
	v_mul_f32_e32 v114, v114, v145
	v_fma_f32 v114, v114, v218, v82
	v_sub_f32_e32 v115, v115, v144
	v_mul_f32_e32 v115, v115, v145
	v_fma_f32 v115, v115, v219, v83
	v_sub_f32_e32 v108, v108, v146
	v_mul_f32_e32 v108, v108, v147
	v_fma_f32 v108, v108, v204, v76
	v_sub_f32_e32 v109, v109, v146
	v_mul_f32_e32 v109, v109, v147
	v_fma_f32 v109, v109, v205, v77
	v_sub_f32_e32 v110, v110, v146
	v_mul_f32_e32 v110, v110, v147
	v_fma_f32 v110, v110, v206, v78
	v_sub_f32_e32 v111, v111, v146
	v_mul_f32_e32 v111, v111, v147
	v_fma_f32 v111, v111, v207, v79
	v_sub_f32_e32 v104, v104, v146
	v_mul_f32_e32 v104, v104, v147
	v_fma_f32 v104, v104, v208, v72
	v_sub_f32_e32 v105, v105, v146
	v_mul_f32_e32 v105, v105, v147
	v_fma_f32 v105, v105, v209, v73
	v_sub_f32_e32 v106, v106, v146
	v_mul_f32_e32 v106, v106, v147
	v_fma_f32 v106, v106, v210, v74
	v_sub_f32_e32 v107, v107, v146
	v_mul_f32_e32 v107, v107, v147
	v_fma_f32 v107, v107, v211, v75
	v_sub_f32_e32 v100, v100, v146
	v_mul_f32_e32 v100, v100, v147
	v_fma_f32 v100, v100, v212, v68
	v_sub_f32_e32 v101, v101, v146
	v_mul_f32_e32 v101, v101, v147
	v_fma_f32 v101, v101, v213, v69
	v_sub_f32_e32 v102, v102, v146
	v_mul_f32_e32 v102, v102, v147
	v_fma_f32 v102, v102, v214, v70
	v_sub_f32_e32 v103, v103, v146
	v_mul_f32_e32 v103, v103, v147
	v_fma_f32 v103, v103, v215, v71
	v_sub_f32_e32 v96, v96, v146
	v_mul_f32_e32 v96, v96, v147
	v_fma_f32 v96, v96, v216, v64
	v_sub_f32_e32 v97, v97, v146
	v_mul_f32_e32 v97, v97, v147
	v_fma_f32 v97, v97, v217, v65
	v_sub_f32_e32 v98, v98, v146
	v_mul_f32_e32 v98, v98, v147
	v_fma_f32 v98, v98, v218, v66
	v_sub_f32_e32 v99, v99, v146
	v_mul_f32_e32 v99, v99, v147
	v_fma_f32 v99, v99, v219, v67
	v_sub_f32_e32 v220, v220, v148
	v_mul_f32_e32 v220, v220, v149
	v_fma_f32 v220, v220, v204, v60
	v_sub_f32_e32 v221, v221, v148
	v_mul_f32_e32 v221, v221, v149
	v_fma_f32 v221, v221, v205, v61
	v_sub_f32_e32 v222, v222, v148
	v_mul_f32_e32 v222, v222, v149
	v_fma_f32 v222, v222, v206, v62
	v_sub_f32_e32 v223, v223, v148
	v_mul_f32_e32 v223, v223, v149
	v_fma_f32 v223, v223, v207, v63
	v_sub_f32_e32 v224, v224, v148
	v_mul_f32_e32 v224, v224, v149
	v_fma_f32 v224, v224, v208, v56
	v_sub_f32_e32 v225, v225, v148
	v_mul_f32_e32 v225, v225, v149
	v_fma_f32 v225, v225, v209, v57
	v_sub_f32_e32 v226, v226, v148
	v_mul_f32_e32 v226, v226, v149
	v_fma_f32 v226, v226, v210, v58
	v_sub_f32_e32 v227, v227, v148
	v_mul_f32_e32 v227, v227, v149
	v_fma_f32 v227, v227, v211, v59
	v_sub_f32_e32 v228, v228, v148
	v_mul_f32_e32 v228, v228, v149
	v_fma_f32 v228, v228, v212, v52
	v_sub_f32_e32 v229, v229, v148
	v_mul_f32_e32 v229, v229, v149
	v_fma_f32 v229, v229, v213, v53
	v_sub_f32_e32 v230, v230, v148
	v_mul_f32_e32 v230, v230, v149
	v_fma_f32 v230, v230, v214, v54
	v_sub_f32_e32 v231, v231, v148
	v_mul_f32_e32 v231, v231, v149
	v_fma_f32 v231, v231, v215, v55
	v_sub_f32_e32 v232, v232, v148
	v_mul_f32_e32 v232, v232, v149
	v_fma_f32 v232, v232, v216, v48
	v_sub_f32_e32 v233, v233, v148
	v_mul_f32_e32 v233, v233, v149
	v_fma_f32 v233, v233, v217, v49
	v_sub_f32_e32 v234, v234, v148
	v_mul_f32_e32 v234, v234, v149
	v_fma_f32 v234, v234, v218, v50
	v_sub_f32_e32 v235, v235, v148
	v_mul_f32_e32 v235, v235, v149
	v_fma_f32 v235, v235, v219, v51
	v_sub_f32_e32 v236, v236, v150
	v_mul_f32_e32 v236, v236, v151
	v_fma_f32 v236, v236, v204, v44
	v_sub_f32_e32 v237, v237, v150
	v_mul_f32_e32 v237, v237, v151
	v_fma_f32 v237, v237, v205, v45
	v_sub_f32_e32 v238, v238, v150
	v_mul_f32_e32 v238, v238, v151
	v_fma_f32 v238, v238, v206, v46
	v_sub_f32_e32 v239, v239, v150
	v_mul_f32_e32 v239, v239, v151
	v_fma_f32 v239, v239, v207, v47
	v_sub_f32_e32 v240, v240, v150
	v_mul_f32_e32 v240, v240, v151
	v_fma_f32 v240, v240, v208, v40
	v_sub_f32_e32 v241, v241, v150
	v_mul_f32_e32 v241, v241, v151
	v_fma_f32 v241, v241, v209, v41
	v_sub_f32_e32 v242, v242, v150
	v_mul_f32_e32 v242, v242, v151
	v_fma_f32 v242, v242, v210, v42
	v_sub_f32_e32 v243, v243, v150
	v_mul_f32_e32 v243, v243, v151
	v_fma_f32 v243, v243, v211, v43
	v_sub_f32_e32 v244, v244, v150
	v_mul_f32_e32 v244, v244, v151
	v_fma_f32 v244, v244, v212, v36
	v_sub_f32_e32 v245, v245, v150
	v_mul_f32_e32 v245, v245, v151
	v_fma_f32 v245, v245, v213, v37
; #define G_WAIT_V(n) asm volatile("s_waitcnt vmcnt(" #n ")" ::: "memory")
; #define G_BAR __builtin_amdgcn_s_barrier()
; template <class Epi, bool PERMROWS = false>
; DI void gemm_phase(LAS unsigned char* lds, const bf16_t* A, int lda, const bf16_t* Bt, int K, const Sched& S, const Epi& E) {
;     ...
;     G_WAIT_V(0);
;     if (wr == 0) G_BAR;
;     G_BAR;
;     DI void operator()(const f32x4 (&acc)[2][2][4][2], const Unit& u, int wr, int wc, int fr, int fq) const {
;     ...
;         for (int ai = 0; ai < 2; ++ai)
; #pragma unroll
;             for (int m = 0; m < 4; ++m) {
;                 const int row = u.pm * BM + ai * HALF + wr * 64 + m * 16 + fr;
;                 float mu = 0.f, rs = 1.f;
;                 if (pg) { const float2 st = RS[row]; mu = st.x; rs = st.y; }
; #pragma unroll
;                 for (int bj = 0; bj < 2; ++bj)
; #pragma unroll
;                     for (int n = 0; n < 2; ++n) {
;                         const int col = u.pn * BM + bj * HALF + wc * 32 + n * 16 + 4 * fq;
;                         float* xp = X + (size_t)row * DM + col;
;                         f32x4 x4 = *(const f32x4*)xp; const f32x4 g4 = *(const f32x4*)(g + col);
;                         if (pg) x4 = (x4 - mu) * rs * *(const f32x4*)(pg + col) + *(const f32x4*)(pb + col);
;                         *(f32x4*)xp = x4 * ALPHA + g4 * acc[ai][bj][m][n];
;                     }
	v_sub_f32_e32 v246, v246, v150
	v_mul_f32_e32 v246, v246, v151
	v_fma_f32 v246, v246, v214, v38
	v_sub_f32_e32 v247, v247, v150
	v_mul_f32_e32 v247, v247, v151
	v_fma_f32 v247, v247, v215, v39
	v_sub_f32_e32 v248, v248, v150
	v_mul_f32_e32 v248, v248, v151
	v_fma_f32 v248, v248, v216, v32
	v_sub_f32_e32 v249, v249, v150
	v_mul_f32_e32 v249, v249, v151
	v_fma_f32 v249, v249, v217, v33
	v_sub_f32_e32 v250, v250, v150
	v_mul_f32_e32 v250, v250, v151
	v_fma_f32 v250, v250, v218, v34
	v_sub_f32_e32 v251, v251, v150
	v_mul_f32_e32 v251, v251, v151
	v_fma_f32 v251, v251, v219, v35
	global_load_dwordx4 v[92:95], v173, s[72:73] offset:0 nt
	global_load_dwordx4 v[88:91], v173, s[72:73] offset:64 nt
	global_load_dwordx4 v[84:87], v173, s[72:73] offset:512 nt
	global_load_dwordx4 v[80:83], v173, s[72:73] offset:576 nt
	global_load_dwordx4 v[76:79], v174, s[72:73] offset:0 nt
	global_load_dwordx4 v[72:75], v174, s[72:73] offset:64 nt
	global_load_dwordx4 v[68:71], v174, s[72:73] offset:512 nt
	global_load_dwordx4 v[64:67], v174, s[72:73] offset:576 nt
	global_store_dwordx4 v169, v[124:127], s[72:73] offset:0
	global_store_dwordx4 v169, v[120:123], s[72:73] offset:64
	global_store_dwordx4 v169, v[116:119], s[72:73] offset:512
	global_store_dwordx4 v169, v[112:115], s[72:73] offset:576
	global_store_dwordx4 v170, v[108:111], s[72:73] offset:0
	global_store_dwordx4 v170, v[104:107], s[72:73] offset:64
	global_store_dwordx4 v170, v[100:103], s[72:73] offset:512
	global_store_dwordx4 v170, v[96:99], s[72:73] offset:576
	global_store_dwordx4 v171, v[220:223], s[72:73] offset:0
	global_store_dwordx4 v171, v[224:227], s[72:73] offset:64
	global_store_dwordx4 v171, v[228:231], s[72:73] offset:512
	global_store_dwordx4 v171, v[232:235], s[72:73] offset:576
	global_store_dwordx4 v172, v[236:239], s[72:73] offset:0
	global_store_dwordx4 v172, v[240:243], s[72:73] offset:64
	global_store_dwordx4 v172, v[244:247], s[72:73] offset:512
	global_store_dwordx4 v172, v[248:251], s[72:73] offset:576
	s_waitcnt vmcnt(16)
	v_sub_f32_e32 v92, v92, v152
	v_mul_f32_e32 v92, v92, v153
	v_fma_f32 v92, v92, v204, v28
	v_sub_f32_e32 v93, v93, v152
	v_mul_f32_e32 v93, v93, v153
	v_fma_f32 v93, v93, v205, v29
	v_sub_f32_e32 v94, v94, v152
	v_mul_f32_e32 v94, v94, v153
	v_fma_f32 v94, v94, v206, v30
	v_sub_f32_e32 v95, v95, v152
	v_mul_f32_e32 v95, v95, v153
	v_fma_f32 v95, v95, v207, v31
	v_sub_f32_e32 v88, v88, v152
	v_mul_f32_e32 v88, v88, v153
	v_fma_f32 v88, v88, v208, v24
	v_sub_f32_e32 v89, v89, v152
	v_mul_f32_e32 v89, v89, v153
	v_fma_f32 v89, v89, v209, v25
	v_sub_f32_e32 v90, v90, v152
	v_mul_f32_e32 v90, v90, v153
	v_fma_f32 v90, v90, v210, v26
	v_sub_f32_e32 v91, v91, v152
	v_mul_f32_e32 v91, v91, v153
	v_fma_f32 v91, v91, v211, v27
	v_sub_f32_e32 v84, v84, v152
	v_mul_f32_e32 v84, v84, v153
	v_fma_f32 v84, v84, v212, v20
	v_sub_f32_e32 v85, v85, v152
	v_mul_f32_e32 v85, v85, v153
	v_fma_f32 v85, v85, v213, v21
	v_sub_f32_e32 v86, v86, v152
	v_mul_f32_e32 v86, v86, v153
	v_fma_f32 v86, v86, v214, v22
	v_sub_f32_e32 v87, v87, v152
	v_mul_f32_e32 v87, v87, v153
	v_fma_f32 v87, v87, v215, v23
	v_sub_f32_e32 v80, v80, v152
	v_mul_f32_e32 v80, v80, v153
	v_fma_f32 v80, v80, v216, v12
	v_sub_f32_e32 v81, v81, v152
	v_mul_f32_e32 v81, v81, v153
	v_fma_f32 v81, v81, v217, v13
	v_sub_f32_e32 v82, v82, v152
	v_mul_f32_e32 v82, v82, v153
	v_fma_f32 v82, v82, v218, v14
	v_sub_f32_e32 v83, v83, v152
	v_mul_f32_e32 v83, v83, v153
	v_fma_f32 v83, v83, v219, v15
	v_sub_f32_e32 v76, v76, v164
	v_mul_f32_e32 v76, v76, v165
	v_fma_f32 v76, v76, v204, v16
	v_sub_f32_e32 v77, v77, v164
	v_mul_f32_e32 v77, v77, v165
	v_fma_f32 v77, v77, v205, v17
	v_sub_f32_e32 v78, v78, v164
	v_mul_f32_e32 v78, v78, v165
	v_fma_f32 v78, v78, v206, v18
	v_sub_f32_e32 v79, v79, v164
	v_mul_f32_e32 v79, v79, v165
	v_fma_f32 v79, v79, v207, v19
	v_sub_f32_e32 v72, v72, v164
	v_mul_f32_e32 v72, v72, v165
	v_fma_f32 v72, v72, v208, v8
	v_sub_f32_e32 v73, v73, v164
	v_mul_f32_e32 v73, v73, v165
	v_fma_f32 v73, v73, v209, v9
	v_sub_f32_e32 v74, v74, v164
	v_mul_f32_e32 v74, v74, v165
	v_fma_f32 v74, v74, v210, v10
	v_sub_f32_e32 v75, v75, v164
	v_mul_f32_e32 v75, v75, v165
	v_fma_f32 v75, v75, v211, v11
	v_sub_f32_e32 v68, v68, v164
	v_mul_f32_e32 v68, v68, v165
	v_fma_f32 v68, v68, v212, v4
	v_sub_f32_e32 v69, v69, v164
	v_mul_f32_e32 v69, v69, v165
	v_fma_f32 v69, v69, v213, v5
	v_sub_f32_e32 v70, v70, v164
	v_mul_f32_e32 v70, v70, v165
	v_fma_f32 v70, v70, v214, v6
	v_sub_f32_e32 v71, v71, v164
	v_mul_f32_e32 v71, v71, v165
	v_fma_f32 v71, v71, v215, v7
	v_sub_f32_e32 v64, v64, v164
	v_mul_f32_e32 v64, v64, v165
	v_fma_f32 v64, v64, v216, v0
	v_sub_f32_e32 v65, v65, v164
	v_mul_f32_e32 v65, v65, v165
	v_fma_f32 v65, v65, v217, v1
	v_sub_f32_e32 v66, v66, v164
	v_mul_f32_e32 v66, v66, v165
	v_fma_f32 v66, v66, v218, v2
	v_sub_f32_e32 v67, v67, v164
	v_mul_f32_e32 v67, v67, v165
	v_fma_f32 v67, v67, v219, v3
	global_store_dwordx4 v173, v[92:95], s[72:73] offset:0
	global_store_dwordx4 v173, v[88:91], s[72:73] offset:64
	global_store_dwordx4 v173, v[84:87], s[72:73] offset:512
	global_store_dwordx4 v173, v[80:83], s[72:73] offset:576
	global_store_dwordx4 v174, v[76:79], s[72:73] offset:0
	global_store_dwordx4 v174, v[72:75], s[72:73] offset:64
	global_store_dwordx4 v174, v[68:71], s[72:73] offset:512
	global_store_dwordx4 v174, v[64:67], s[72:73] offset:576
	s_mov_b32 s60, s57
	s_mov_b64 s[22:23], s[0:1]
	s_and_b64 vcc, exec, s[2:3]
	s_mov_b32 s59, s58
	s_mov_b64 s[20:21], s[4:5]
	s_cbranch_vccz .LBB0_3102
	s_waitcnt vmcnt(0)
	s_cmpk_gt_u32 s19, 0xff
	s_cbranch_scc1 .LBB0_3117
	s_barrier

; DI void phase_ln(const Params& p, const float* gam, const float* bet, const float* modnext  , bool skip_ctx, bool final_out,
;                  const float* cgate  , const float* pg, const float* pb  ) {
;     ...
;     for (int rowA = gw; rowA < MR; rowA += 2 * nw) {
;         f32x4 v[2][8]; float sum[2] = {0.f, 0.f}; bool act[2]; int rows[2];
; #pragma unroll
;         for (int q = 0; q < 2; ++q) {
;             const int row = rowA + q * nw; rows[q] = row;
;             const int b = row / RB, r = row % RB;
;             act[q] = row < MR && !(skip_ctx && r < CL);
;             if (act[q]) {
;                 const bool cpart = cgate && r < CL;
;                 float pmu = 0.f, prs = 1.f;
;                 if (cpart && pg) { const float2 st = RS[row]; pmu = st.x; prs = st.y; }
; #pragma unroll
;                 for (int i = 0; i < 8; ++i) {
;                     const int col = (i * 64 + lane) * 4;
;                     v[q][i] = *(const f32x4*)(X + (size_t)row * DM + col);
.Lfin_row:
	s_cmpk_ge_u32 s9, 0x2400
	s_cbranch_scc1 .Lfin_done
	s_lshr_b32 s35, s9, 8
	s_mul_i32 s27, s35, 57
	s_lshr_b32 s27, s27, 9
	s_mul_i32 s35, s27, 0x900
	s_sub_u32 s29, s9, s35
	s_cmpk_lt_u32 s29, 0x100
	s_cbranch_scc1 .Lfin_next
	s_mov_b32 s32, s27
	s_lshl_b32 s35, s9, 13
	s_add_u32 s2, s50, 0xcba0000
	s_addc_u32 s3, s51, 0
	s_add_u32 s2, s2, s35
	s_addc_u32 s3, s3, 0
	global_load_dwordx4 v[88:91], v76, s[2:3] offset:0 nt
	global_load_dwordx4 v[92:95], v76, s[2:3] offset:1024 nt
	global_load_dwordx4 v[96:99], v76, s[2:3] offset:2048 nt
	global_load_dwordx4 v[100:103], v76, s[2:3] offset:3072 nt
	global_load_dwordx4 v[104:107], v77, s[2:3] offset:0 nt
	global_load_dwordx4 v[108:111], v77, s[2:3] offset:1024 nt
	global_load_dwordx4 v[112:115], v77, s[2:3] offset:2048 nt
	global_load_dwordx4 v[116:119], v77, s[2:3] offset:3072 nt
	s_waitcnt vmcnt(0)
; DI void phase_ln(const Params& p, const float* gam, const float* bet, const float* modnext  , bool skip_ctx, bool final_out,
;                  const float* cgate  , const float* pg, const float* pb  ) {
;     ...
;         for (int q = 0; q < 2; ++q)
; #pragma unroll
;             for (int i = 0; i < 8; ++i) sum[q] += v[q][i][0] + v[q][i][1] + v[q][i][2] + v[q][i][3];
;         float mu[2], sq[2] = {0.f, 0.f}, rs[2];
; #pragma unroll
;         for (int o = 32; o > 0; o >>= 1) { sum[0] += __shfl_xor(sum[0], o); sum[1] += __shfl_xor(sum[1], o); }
; #pragma unroll
;         for (int q = 0; q < 2; ++q) {
;             mu[q] = sum[q] * (1.f / 2048.f);
; #pragma unroll
;             for (int i = 0; i < 8; ++i) { v[q][i] -= mu[q]; sq[q] += v[q][i][0] * v[q][i][0] + v[q][i][1] * v[q][i][1] + v[q][i][2] * v[q][i][2] + v[q][i][3] * v[q][i][3]; }
;         }
; #pragma unroll
;         for (int o = 32; o > 0; o >>= 1) { sq[0] += __shfl_xor(sq[0], o); sq[1] += __shfl_xor(sq[1], o); }
; #pragma unroll
;         for (int q = 0; q < 2; ++q) {
;             if (!act[q]) continue;
;             rs[q] = rsqrtf(sq[q] * (1.f / 2048.f) + 1e-5f);
;             const int row = rows[q]; const int b = row / RB, r = row % RB; const int s = r < CL ? 4 : b;
;             if (lane == 0 && !final_out) RS[row] = make_float2(mu[q], rs[q]);
; #pragma unroll
;             for (int i = 0; i < 8; ++i) {
;                 const int col = (i * 64 + lane) * 4;
;                 const f32x4 o = v[q][i] * rs[q] * *(const f32x4*)(gam + col) + *(const f32x4*)(bet + col);
;                 if (final_out) { *(f32x4*)(p.out + ((size_t)b * TL + (r - CL)) * DM + col) = o; }
	v_add_f32_e32 v80, v88, v92
	v_add_f32_e32 v81, v89, v93
	v_add_f32_e32 v82, v90, v94
	v_add_f32_e32 v83, v91, v95
	v_add_f32_e32 v80, v96, v80
	v_add_f32_e32 v81, v97, v81
	v_add_f32_e32 v82, v98, v82
	v_add_f32_e32 v83, v99, v83
	v_add_f32_e32 v80, v100, v80
	v_add_f32_e32 v81, v101, v81
	v_add_f32_e32 v82, v102, v82
	v_add_f32_e32 v83, v103, v83
	v_add_f32_e32 v80, v104, v80
	v_add_f32_e32 v81, v105, v81
	v_add_f32_e32 v82, v106, v82
	v_add_f32_e32 v83, v107, v83
	v_add_f32_e32 v80, v108, v80
	v_add_f32_e32 v81, v109, v81
	v_add_f32_e32 v82, v110, v82
	v_add_f32_e32 v83, v111, v83
	v_add_f32_e32 v80, v112, v80
	v_add_f32_e32 v81, v113, v81
	v_add_f32_e32 v82, v114, v82
	v_add_f32_e32 v83, v115, v83
	v_add_f32_e32 v80, v116, v80
	v_add_f32_e32 v81, v117, v81
	v_add_f32_e32 v82, v118, v82
	v_add_f32_e32 v83, v119, v83
	v_add_f32_e32 v80, v80, v81
	v_add_f32_e32 v82, v82, v83
	v_add_f32_e32 v80, v80, v82
	s_nop 1
	v_add_f32_dpp v86, v80, v80 quad_perm:[1,0,3,2] row_mask:0xf bank_mask:0xf
	s_nop 1
	v_add_f32_dpp v86, v86, v86 quad_perm:[2,3,0,1] row_mask:0xf bank_mask:0xf
	s_nop 1
	v_add_f32_dpp v86, v86, v86 row_half_mirror row_mask:0xf bank_mask:0xf
	s_nop 1
	v_add_f32_dpp v86, v86, v86 row_mirror row_mask:0xf bank_mask:0xf
	s_nop 1
	v_readlane_b32 s69, v86, 0
	v_readlane_b32 s71, v86, 16
	v_readlane_b32 s73, v86, 32
	v_readlane_b32 s81, v86, 48
	s_nop 3
	v_mov_b32_e32 v84, s69
	v_add_f32_e32 v84, s71, v84
	v_add_f32_e32 v84, s73, v84
	v_add_f32_e32 v84, s81, v84
	v_mul_f32_e32 v236, s82, v84
	v_sub_f32_e32 v88, v88, v236
	v_sub_f32_e32 v89, v89, v236
	v_sub_f32_e32 v90, v90, v236
	v_sub_f32_e32 v91, v91, v236
	v_sub_f32_e32 v92, v92, v236
	v_sub_f32_e32 v93, v93, v236
	v_sub_f32_e32 v94, v94, v236
	v_sub_f32_e32 v95, v95, v236
	v_sub_f32_e32 v96, v96, v236
	v_sub_f32_e32 v97, v97, v236
	v_sub_f32_e32 v98, v98, v236
	v_sub_f32_e32 v99, v99, v236
	v_sub_f32_e32 v100, v100, v236
	v_sub_f32_e32 v101, v101, v236
	v_sub_f32_e32 v102, v102, v236
	v_sub_f32_e32 v103, v103, v236
	v_sub_f32_e32 v104, v104, v236
	v_sub_f32_e32 v105, v105, v236
	v_sub_f32_e32 v106, v106, v236
	v_sub_f32_e32 v107, v107, v236
	v_sub_f32_e32 v108, v108, v236
	v_sub_f32_e32 v109, v109, v236
	v_sub_f32_e32 v110, v110, v236
	v_sub_f32_e32 v111, v111, v236
	v_sub_f32_e32 v112, v112, v236
	v_sub_f32_e32 v113, v113, v236
	v_sub_f32_e32 v114, v114, v236
	v_sub_f32_e32 v115, v115, v236
	v_sub_f32_e32 v116, v116, v236
	v_sub_f32_e32 v117, v117, v236
	v_sub_f32_e32 v118, v118, v236
	v_sub_f32_e32 v119, v119, v236
	v_mul_f32_e32 v80, v88, v88
	v_mul_f32_e32 v81, v89, v89
	v_mul_f32_e32 v82, v90, v90
	v_mul_f32_e32 v83, v91, v91
	v_fmac_f32_e32 v80, v92, v92
	v_fmac_f32_e32 v81, v93, v93
	v_fmac_f32_e32 v82, v94, v94
	v_fmac_f32_e32 v83, v95, v95
	v_fmac_f32_e32 v80, v96, v96
	v_fmac_f32_e32 v81, v97, v97
	v_fmac_f32_e32 v82, v98, v98
	v_fmac_f32_e32 v83, v99, v99
	v_fmac_f32_e32 v80, v100, v100
	v_fmac_f32_e32 v81, v101, v101
	v_fmac_f32_e32 v82, v102, v102
	v_fmac_f32_e32 v83, v103, v103
	v_fmac_f32_e32 v80, v104, v104
	v_fmac_f32_e32 v81, v105, v105
	v_fmac_f32_e32 v82, v106, v106
	v_fmac_f32_e32 v83, v107, v107
	v_fmac_f32_e32 v80, v108, v108
	v_fmac_f32_e32 v81, v109, v109
	v_fmac_f32_e32 v82, v110, v110
	v_fmac_f32_e32 v83, v111, v111
	v_fmac_f32_e32 v80, v112, v112
	v_fmac_f32_e32 v81, v113, v113
	v_fmac_f32_e32 v82, v114, v114
	v_fmac_f32_e32 v83, v115, v115
	v_fmac_f32_e32 v80, v116, v116
	v_fmac_f32_e32 v81, v117, v117
	v_fmac_f32_e32 v82, v118, v118
	v_fmac_f32_e32 v83, v119, v119
	v_add_f32_e32 v80, v80, v81
	v_add_f32_e32 v82, v82, v83
	v_add_f32_e32 v80, v80, v82
	s_nop 1
	v_add_f32_dpp v86, v80, v80 quad_perm:[1,0,3,2] row_mask:0xf bank_mask:0xf
	s_nop 1
	v_add_f32_dpp v86, v86, v86 quad_perm:[2,3,0,1] row_mask:0xf bank_mask:0xf
	s_nop 1
	v_add_f32_dpp v86, v86, v86 row_half_mirror row_mask:0xf bank_mask:0xf
	s_nop 1
	v_add_f32_dpp v86, v86, v86 row_mirror row_mask:0xf bank_mask:0xf
	s_nop 1
	v_readlane_b32 s69, v86, 0
	v_readlane_b32 s71, v86, 16
	v_readlane_b32 s73, v86, 32
	v_readlane_b32 s81, v86, 48
	s_nop 3
	v_mov_b32_e32 v84, s69
	v_add_f32_e32 v84, s71, v84
	v_add_f32_e32 v84, s73, v84
	v_add_f32_e32 v84, s81, v84
	v_mov_b32_e32 v86, s83
	v_fmac_f32_e32 v86, s82, v84
	v_rsq_f32_e32 v237, v86
	s_nop 0
	s_lshl_b32 s35, s27, 11
	s_add_u32 s35, s35, s29
	s_sub_u32 s35, s35, 0x100
	s_lshl_b32 s35, s35, 13
	s_add_u32 s6, s48, s35
	s_addc_u32 s7, s49, 0
	v_mul_f32_e32 v88, v88, v237
	v_mul_f32_e32 v89, v89, v237
	v_mul_f32_e32 v90, v90, v237
	v_mul_f32_e32 v91, v91, v237
	v_fma_f32 v88, v88, v12, v44
	v_fma_f32 v89, v89, v13, v45
	v_fma_f32 v90, v90, v14, v46
	v_fma_f32 v91, v91, v15, v47
	global_store_dwordx4 v76, v[88:91], s[6:7] offset:0
	v_mul_f32_e32 v92, v92, v237
	v_mul_f32_e32 v93, v93, v237
	v_mul_f32_e32 v94, v94, v237
	v_mul_f32_e32 v95, v95, v237
	v_fma_f32 v92, v92, v16, v48
	v_fma_f32 v93, v93, v17, v49
	v_fma_f32 v94, v94, v18, v50
	v_fma_f32 v95, v95, v19, v51
	global_store_dwordx4 v76, v[92:95], s[6:7] offset:1024
	v_mul_f32_e32 v96, v96, v237
	v_mul_f32_e32 v97, v97, v237
	v_mul_f32_e32 v98, v98, v237
	v_mul_f32_e32 v99, v99, v237
	v_fma_f32 v96, v96, v20, v52
	v_fma_f32 v97, v97, v21, v53
	v_fma_f32 v98, v98, v22, v54
	v_fma_f32 v99, v99, v23, v55
	global_store_dwordx4 v76, v[96:99], s[6:7] offset:2048
	v_mul_f32_e32 v100, v100, v237
	v_mul_f32_e32 v101, v101, v237
	v_mul_f32_e32 v102, v102, v237
	v_mul_f32_e32 v103, v103, v237
	v_fma_f32 v100, v100, v24, v56
	v_fma_f32 v101, v101, v25, v57
	v_fma_f32 v102, v102, v26, v58
	v_fma_f32 v103, v103, v27, v59
	global_store_dwordx4 v76, v[100:103], s[6:7] offset:3072
	v_mul_f32_e32 v104, v104, v237
	v_mul_f32_e32 v105, v105, v237
	v_mul_f32_e32 v106, v106, v237
	v_mul_f32_e32 v107, v107, v237
	v_fma_f32 v104, v104, v28, v60
	v_fma_f32 v105, v105, v29, v61
	v_fma_f32 v106, v106, v30, v62
	v_fma_f32 v107, v107, v31, v63
	global_store_dwordx4 v77, v[104:107], s[6:7] offset:0
	v_mul_f32_e32 v108, v108, v237
	v_mul_f32_e32 v109, v109, v237
	v_mul_f32_e32 v110, v110, v237
	v_mul_f32_e32 v111, v111, v237
	v_fma_f32 v108, v108, v32, v64
	v_fma_f32 v109, v109, v33, v65
	v_fma_f32 v110, v110, v34, v66
	v_fma_f32 v111, v111, v35, v67
	global_store_dwordx4 v77, v[108:111], s[6:7] offset:1024
	v_mul_f32_e32 v112, v112, v237
	v_mul_f32_e32 v113, v113, v237
	v_mul_f32_e32 v114, v114, v237
	v_mul_f32_e32 v115, v115, v237
	v_fma_f32 v112, v112, v36, v68
	v_fma_f32 v113, v113, v37, v69
	v_fma_f32 v114, v114, v38, v70
	v_fma_f32 v115, v115, v39, v71
	global_store_dwordx4 v77, v[112:115], s[6:7] offset:2048
	v_mul_f32_e32 v116, v116, v237
	v_mul_f32_e32 v117, v117, v237
	v_mul_f32_e32 v118, v118, v237
	v_mul_f32_e32 v119, v119, v237
	v_fma_f32 v116, v116, v40, v72
	v_fma_f32 v117, v117, v41, v73
	v_fma_f32 v118, v118, v42, v74
	v_fma_f32 v119, v119, v43, v75
	global_store_dwordx4 v77, v[116:119], s[6:7] offset:3072
